# sel v2 (fused both-selected path) + nt on final output stores + nt on read-once f32 weight loads (P0 transposes, adaLN GEMV, P2 deferred copies)
# speedup vs baseline: 1.0321x; 1.0138x over previous
; __global__ void __launch_bounds__(NTHREADS, 2) mega_fwd(Args a_unused) {
;     ...
;             if (kc < 14) {
;                 float a0 = 0.f, a1 = 0.f;
;                 const float* wcol = ap->in[2] + j;
; #pragma nounroll
;                 for (int i0 = 0; i0 < 80; i0 += 8) {
;                     float w[8];
; #pragma unroll
;                     for (int u_ = 0; u_ < 8; ++u_) { const int k = kc + 14 * (i0 + u_); w[u_] = (k < D) ? wcol[(size_t)k * NMOD] : 0.f; }
; #pragma unroll
;                     for (int u_ = 0; u_ < 8; ++u_) { const int k = kc + 14 * (i0 + u_); const int kk = k < D ? k : 0; a0 += sc[kk] * w[u_]; a1 += sc[D + kk] * w[u_]; }
;                 }
.LBB0_15:
	s_cmpk_lt_u32 s48, 0x4a
	s_cselect_b64 s[8:9], -1, 0
	s_cmpk_gt_u32 s48, 0x49
	v_mov_b32_e32 v10, 0
	s_cbranch_scc1 .LBB0_17
	v_add_co_u32_e32 v18, vcc, 0xffc8e000, v6
	s_nop 1
	v_addc_co_u32_e32 v19, vcc, -1, v7, vcc
	global_load_dword v10, v[18:19], off nt
.LBB0_17:
	v_add_u32_e32 v5, 0xffffffac, v17
	v_cmp_gt_u32_e64 s[10:11], s45, v5
	v_mov_b32_e32 v12, 0
	v_mov_b32_e32 v14, 0
	s_and_saveexec_b64 s[12:13], s[10:11]
	s_cbranch_execz .LBB0_19
	v_add_co_u32_e32 v18, vcc, 0xffd0c000, v6
	s_nop 1
	v_addc_co_u32_e32 v19, vcc, -1, v7, vcc
	global_load_dword v14, v[18:19], off nt
.LBB0_19:
	s_or_b64 exec, exec, s[12:13]
	v_add_u32_e32 v19, 0xffffffba, v17
	v_cmp_gt_u32_e64 s[12:13], s45, v19
	s_and_saveexec_b64 s[14:15], s[12:13]
	s_cbranch_execz .LBB0_21
	v_add_co_u32_e32 v20, vcc, 0xffd8a000, v6
	s_nop 1
	v_addc_co_u32_e32 v21, vcc, -1, v7, vcc
	global_load_dword v12, v[20:21], off nt
.LBB0_21:
	s_or_b64 exec, exec, s[14:15]
	v_subrev_u32_e32 v21, 56, v17
	v_cmp_gt_u32_e64 s[14:15], s45, v21
	v_mov_b32_e32 v16, 0
	v_mov_b32_e32 v18, 0
	s_and_saveexec_b64 s[16:17], s[14:15]
	s_cbranch_execz .LBB0_23
	v_add_co_u32_e32 v22, vcc, 0xffe08000, v6
	s_nop 1
	v_addc_co_u32_e32 v23, vcc, -1, v7, vcc
	global_load_dword v18, v[22:23], off nt
.LBB0_23:
	s_or_b64 exec, exec, s[16:17]
	v_subrev_u32_e32 v23, 42, v17
	v_cmp_gt_u32_e64 s[16:17], s45, v23
	s_and_saveexec_b64 s[18:19], s[16:17]
	s_cbranch_execz .LBB0_25
	v_add_co_u32_e32 v24, vcc, 0xffe86000, v6
	s_nop 1
	v_addc_co_u32_e32 v25, vcc, -1, v7, vcc
	global_load_dword v16, v[24:25], off nt
.LBB0_25:
	s_or_b64 exec, exec, s[18:19]
	v_subrev_u32_e32 v25, 28, v17
	v_cmp_gt_u32_e64 s[18:19], s45, v25
	v_mov_b32_e32 v20, 0
	v_mov_b32_e32 v22, 0
	s_and_saveexec_b64 s[20:21], s[18:19]
	s_cbranch_execz .LBB0_27
	v_add_co_u32_e32 v26, vcc, 0xfff04000, v6
	s_nop 1
	v_addc_co_u32_e32 v27, vcc, -1, v7, vcc
	global_load_dword v22, v[26:27], off nt
.LBB0_27:
	s_or_b64 exec, exec, s[20:21]
	v_add_u32_e32 v26, -14, v17
	v_cmp_gt_u32_e64 s[20:21], s45, v26
	s_and_saveexec_b64 s[42:43], s[20:21]
	s_cbranch_execz .LBB0_29
	v_add_co_u32_e32 v28, vcc, 0xfff82000, v6
	s_nop 1
	v_addc_co_u32_e32 v29, vcc, -1, v7, vcc
	global_load_dword v20, v[28:29], off nt
.LBB0_29:
	s_or_b64 exec, exec, s[42:43]
	v_cmp_gt_u32_e32 vcc, s45, v17
	v_mov_b32_e32 v24, 0
	v_mov_b32_e32 v27, 0
	s_and_saveexec_b64 s[42:43], vcc
	s_cbranch_execz .LBB0_14
	global_load_dword v24, v[6:7], off nt
	v_mov_b32_e32 v27, v17
	s_branch .LBB0_14

; __global__ void __launch_bounds__(NTHREADS, 2) mega_fwd(Args a_unused) {
;     ...
;                 red[(kc * 36 + col) * 2] = a0; red[(kc * 36 + col) * 2 + 1] = a1;
;             }
;             __syncthreads();
;             if (tid < 72) { const int c2 = tid >> 1, bb = tid & 1; float s = ap->in[3][36 * cb + c2];
;                 for (int q = 0; q < 14; ++q) s += red[(q * 36 + c2) * 2 + bb];
;                 mod[(size_t)bb * NMOD + 36 * cb + c2] = s; }
;             __syncthreads();
.LBB0_32:
	s_or_b64 exec, exec, s[40:41]
	s_waitcnt lgkmcnt(0)
	s_barrier
	s_and_saveexec_b64 s[8:9], s[6:7]
	s_cbranch_execz .LBB0_11
	v_mov_b64_e32 v[6:7], s[38:39]
	global_load_dwordx2 v[6:7], v[6:7], off offset:24
	s_mul_i32 s10, s47, 36
	v_add_u32_e32 v8, s10, v140
	v_ashrrev_i32_e32 v9, 31, v8
	v_add_u32_e32 v10, 0x400, v15
	v_add_u32_e32 v24, 0xc00, v15
	v_add_u32_e32 v12, 0x800, v15
	v_add_u32_e32 v14, 0xa00, v15
	s_ashr_i32 s11, s10, 31
	s_waitcnt vmcnt(0) lgkmcnt(0)
	v_lshl_add_u64 v[6:7], v[8:9], 2, v[6:7]
	global_load_dword v5, v[6:7], off nt
	ds_read2_b32 v[6:7], v15 offset1:72
	ds_read2_b32 v[8:9], v15 offset0:144 offset1:216
	ds_read2_b32 v[16:17], v10 offset0:32 offset1:104
	ds_read2_b32 v[18:19], v10 offset0:176 offset1:248
	ds_read2_b32 v[20:21], v12 offset0:64 offset1:136
	ds_read2_b32 v[22:23], v14 offset0:80 offset1:152
	ds_read2_b32 v[24:25], v24 offset0:96 offset1:168
	s_waitcnt vmcnt(0) lgkmcnt(0)
	v_add_f32_e32 v5, v5, v6
	v_add_f32_e32 v5, v5, v7
	v_add_f32_e32 v5, v5, v8
	v_add_f32_e32 v5, v5, v9
	v_add_f32_e32 v5, v5, v16
	v_add_f32_e32 v5, v5, v17
	v_add_f32_e32 v5, v5, v18
	v_add_f32_e32 v5, v5, v19
	v_add_f32_e32 v5, v5, v20
	v_add_f32_e32 v5, v5, v21
	v_add_f32_e32 v5, v5, v22
	v_add_f32_e32 v5, v5, v23
	v_add_f32_e32 v5, v5, v24
	v_add_f32_e32 v5, v5, v25
	v_lshl_add_u64 v[6:7], s[10:11], 2, v[0:1]
	global_store_dword v[6:7], v5, off
	s_branch .LBB0_11

; #define LAS __attribute__((address_space(3)))
; #define TR_TRY(CNT, NBLK, ...) if (r < (CNT)) { const int k0 = 64 * (r / (NBLK)), n0 = 32 * (r % (NBLK)); (void)k0; (void)n0; __VA_ARGS__; continue; } r -= (CNT);
; #define TR_TRY(CNT, NBLK, ...) if (r < (CNT)) { const int k0 = 64 * (r / (NBLK)), n0 = 32 * (r % (NBLK)); (void)k0; (void)n0; __VA_ARGS__; continue; } r -= (CNT);
; __device__ __forceinline__ void tr_item(const float* W, int N, int k0, int n0, bf16* WT, int Kd, int drow0, int dk0, LAS float* scr, int lane) {
;     {
;         float wv[32]; const int n = n0 + (lane & 31); const float* wp = W + (size_t)(k0 + (lane >> 5)) * N + n;
; #pragma unroll
;         for (int i = 0; i < 32; ++i) wv[i] = (n < N) ? wp[(size_t)(2 * i) * N] : 0.f;
; #pragma unroll
;         for (int i = 0; i < 32; ++i) scr[(2 * i + (lane >> 5)) * 33 + (lane & 31)] = wv[i];
; __global__ void __launch_bounds__(NTHREADS, 2) mega_fwd(Args a_unused) {
;     ...
;             TR_TRY(I_UKV, 1024 / 32, { const int hk = n0 / 128, ek = n0 % 128; tr_item(ap->in[19], 1024, k0, n0, Wukv, 256, ek < 64 ? hk * 64 + ek : 512 + hk * 64 + (ek - 64), k0, scr, lane); })
.LBB0_101:
	s_cmpk_gt_i32 s97, 0x57f
	s_mov_b64 s[4:5], -1
	s_cbranch_scc0 .LBB0_191
	s_cmpk_gt_u32 s97, 0xaff
	s_cbranch_scc0 .LBB0_188
	s_cmpk_gt_u32 s97, 0x107f
	s_cbranch_scc0 .LBB0_185
	s_cmpk_gt_u32 s97, 0x147f
	s_cbranch_scc0 .LBB0_118
	s_cmpk_gt_u32 s97, 0x157f
	s_cbranch_scc0 .LBB0_115
	s_cmpk_gt_u32 s97, 0x167f
	s_cbranch_scc0 .LBB0_112
	s_cmpk_gt_u32 s97, 0x170f
	s_cbranch_scc0 .LBB0_109
	v_mov_b64_e32 v[16:17], s[38:39]
	global_load_dwordx2 v[16:17], v[16:17], off offset:152
	s_and_b32 s5, s17, 0x7fffffc0
	s_add_i32 s4, s7, 0xfffd1e00
	s_and_b32 s13, s4, 0x3e0
	v_or_b32_e32 v0, s5, v159
	v_or_b32_e32 v27, s13, v158
	v_lshlrev_b64 v[28:29], 12, v[0:1]
	v_lshlrev_b32_e32 v0, 2, v27
	s_mov_b32 s10, 0x14000
	s_mov_b32 s12, 0x1a000
	s_and_b32 s4, s4, 0x60
	s_waitcnt vmcnt(0) lgkmcnt(0)
	v_lshl_add_u64 v[16:17], v[16:17], 0, v[28:29]
	v_lshl_add_u64 v[16:17], v[16:17], 0, v[0:1]
	v_add_co_u32_e32 v28, vcc, s21, v16
	s_nop 1
	v_addc_co_u32_e32 v29, vcc, 0, v17, vcc
	v_add_co_u32_e32 v30, vcc, s35, v16
	s_nop 1
	v_addc_co_u32_e32 v31, vcc, 0, v17, vcc
	v_add_co_u32_e32 v32, vcc, s40, v16
	s_nop 1
	v_addc_co_u32_e32 v33, vcc, 0, v17, vcc
	v_add_co_u32_e32 v34, vcc, s41, v16
	s_nop 1
	v_addc_co_u32_e32 v35, vcc, 0, v17, vcc
	v_add_co_u32_e32 v36, vcc, s42, v16
	s_nop 1
	v_addc_co_u32_e32 v37, vcc, 0, v17, vcc
	v_add_co_u32_e32 v38, vcc, s43, v16
	s_nop 1
	v_addc_co_u32_e32 v39, vcc, 0, v17, vcc
	v_add_co_u32_e32 v40, vcc, s44, v16
	s_nop 1
	v_addc_co_u32_e32 v41, vcc, 0, v17, vcc
	v_add_co_u32_e32 v42, vcc, s45, v16
	s_nop 1
	v_addc_co_u32_e32 v43, vcc, 0, v17, vcc
	v_add_co_u32_e32 v44, vcc, s46, v16
	s_nop 1
	v_addc_co_u32_e32 v45, vcc, 0, v17, vcc
	v_add_co_u32_e32 v46, vcc, s10, v16
	s_mov_b32 s10, 0x20000
	s_nop 0
	v_addc_co_u32_e32 v47, vcc, 0, v17, vcc
	v_add_co_u32_e32 v48, vcc, s47, v16
	s_nop 1
	v_addc_co_u32_e32 v49, vcc, 0, v17, vcc
	v_add_co_u32_e32 v50, vcc, s48, v16
	s_nop 1
	v_addc_co_u32_e32 v51, vcc, 0, v17, vcc
	v_add_co_u32_e32 v52, vcc, s12, v16
	s_nop 1
	v_addc_co_u32_e32 v53, vcc, 0, v17, vcc
	v_add_co_u32_e32 v54, vcc, s49, v16
	s_nop 1
	v_addc_co_u32_e32 v55, vcc, 0, v17, vcc
	v_add_co_u32_e32 v56, vcc, s50, v16
	s_nop 1
	v_addc_co_u32_e32 v57, vcc, 0, v17, vcc
	global_load_dword v0, v[16:17], off nt
	global_load_dword v27, v[28:29], off nt
	global_load_dword v58, v[30:31], off nt
	global_load_dword v59, v[32:33], off nt
	global_load_dword v60, v[34:35], off nt
	global_load_dword v61, v[36:37], off nt
	global_load_dword v62, v[38:39], off nt
	global_load_dword v63, v[40:41], off nt
	global_load_dword v64, v[42:43], off nt
	s_nop 0
	global_load_dword v44, v[44:45], off nt
	s_nop 0
	global_load_dword v45, v[46:47], off nt
	s_nop 0
	global_load_dword v46, v[48:49], off nt
	global_load_dword v47, v[50:51], off nt
	s_nop 0
	global_load_dword v48, v[52:53], off nt
	global_load_dword v49, v[54:55], off nt
	global_load_dword v50, v[56:57], off nt
	v_add_co_u32_e32 v28, vcc, s10, v16
	s_mov_b32 s10, 0x30000
	s_nop 0
	v_addc_co_u32_e32 v29, vcc, 0, v17, vcc
	v_add_co_u32_e32 v30, vcc, s51, v16
	s_nop 1
	v_addc_co_u32_e32 v31, vcc, 0, v17, vcc
	v_add_co_u32_e32 v32, vcc, s52, v16
	s_nop 1
	v_addc_co_u32_e32 v33, vcc, 0, v17, vcc
	v_add_co_u32_e32 v34, vcc, s53, v16
	s_nop 1
	v_addc_co_u32_e32 v35, vcc, 0, v17, vcc
	v_add_co_u32_e32 v36, vcc, s54, v16
	s_nop 1
	v_addc_co_u32_e32 v37, vcc, 0, v17, vcc
	v_add_co_u32_e32 v38, vcc, s55, v16
	s_nop 1
	v_addc_co_u32_e32 v39, vcc, 0, v17, vcc
	v_add_co_u32_e32 v40, vcc, s56, v16
	s_nop 1
	v_addc_co_u32_e32 v41, vcc, 0, v17, vcc
	v_add_co_u32_e32 v42, vcc, s57, v16
	s_nop 1
	v_addc_co_u32_e32 v43, vcc, 0, v17, vcc
	global_load_dword v51, v[28:29], off nt
	global_load_dword v52, v[30:31], off nt
	global_load_dword v53, v[32:33], off nt
	global_load_dword v54, v[34:35], off nt
	global_load_dword v55, v[36:37], off nt
	global_load_dword v56, v[38:39], off nt
	global_load_dword v57, v[40:41], off nt
	s_nop 0
	global_load_dword v42, v[42:43], off nt
	v_add_co_u32_e32 v28, vcc, s10, v16
	s_mov_b32 s10, 0x32000
	s_nop 0
	v_addc_co_u32_e32 v29, vcc, 0, v17, vcc
	v_add_co_u32_e32 v30, vcc, s10, v16
	s_mov_b32 s10, 0x34000
	s_nop 0
	v_addc_co_u32_e32 v31, vcc, 0, v17, vcc
	v_add_co_u32_e32 v32, vcc, s10, v16
	s_mov_b32 s10, 0x36000
	s_nop 0
	v_addc_co_u32_e32 v33, vcc, 0, v17, vcc
	v_add_co_u32_e32 v34, vcc, s10, v16
	s_mov_b32 s10, 0x38000
	s_nop 0
	v_addc_co_u32_e32 v35, vcc, 0, v17, vcc
	v_add_co_u32_e32 v36, vcc, s10, v16
	s_mov_b32 s10, 0x3a000
	s_nop 0
	v_addc_co_u32_e32 v37, vcc, 0, v17, vcc
	v_add_co_u32_e32 v38, vcc, s10, v16
	s_mov_b32 s10, 0x3e000
	s_nop 0
	v_addc_co_u32_e32 v39, vcc, 0, v17, vcc
	v_add_co_u32_e32 v40, vcc, s58, v16
	s_nop 1
	v_addc_co_u32_e32 v41, vcc, 0, v17, vcc
	v_add_co_u32_e32 v16, vcc, s10, v16
	s_and_b32 s10, s15, 0x1c0
	s_nop 0
	v_addc_co_u32_e32 v17, vcc, 0, v17, vcc
	global_load_dword v28, v[28:29], off nt
	s_nop 0
	global_load_dword v29, v[30:31], off nt
	s_nop 0
	global_load_dword v30, v[32:33], off nt
	global_load_dword v31, v[34:35], off nt
	s_nop 0
	global_load_dword v32, v[36:37], off nt
	global_load_dword v33, v[38:39], off nt
	global_load_dword v34, v[40:41], off nt
	s_nop 0
	global_load_dword v16, v[16:17], off nt
	s_waitcnt vmcnt(0) lgkmcnt(0)
; #define LAS __attribute__((address_space(3)))
; #define LDS_WAIT() asm volatile("s_waitcnt lgkmcnt(0)" ::: "memory")
; __device__ __forceinline__ unsigned pk2(float lo, float hi) { return f2bf(lo) | (f2bf(hi) << 16); }
; #define TR_TRY(CNT, NBLK, ...) if (r < (CNT)) { const int k0 = 64 * (r / (NBLK)), n0 = 32 * (r % (NBLK)); (void)k0; (void)n0; __VA_ARGS__; continue; } r -= (CNT);
; #define TR_TRY(CNT, NBLK, ...) if (r < (CNT)) { const int k0 = 64 * (r / (NBLK)), n0 = 32 * (r % (NBLK)); (void)k0; (void)n0; __VA_ARGS__; continue; } r -= (CNT);
; __device__ __forceinline__ void tr_item(const float* W, int N, int k0, int n0, bf16* WT, int Kd, int drow0, int dk0, LAS float* scr, int lane) {
;     ...
;         for (int i = 0; i < 32; ++i) scr[(2 * i + (lane >> 5)) * 33 + (lane & 31)] = wv[i];
;     }
;     LDS_WAIT();
;     const int c = lane & 7;
; #pragma unroll
;     for (int j = 0; j < 4; ++j) { const int n = (lane >> 3) + 8 * j; const LAS float* s = scr + (8 * c) * 33 + n;
;         v4u o; o.x = pk2(s[0 * 33], s[1 * 33]); o.y = pk2(s[2 * 33], s[3 * 33]); o.z = pk2(s[4 * 33], s[5 * 33]); o.w = pk2(s[6 * 33], s[7 * 33]);
;         *(v4u*)(WT + (size_t)(drow0 + n) * Kd + dk0 + 8 * c) = o; }
;     LDS_WAIT();
; __global__ void __launch_bounds__(NTHREADS, 2) mega_fwd(Args a_unused) {
;     ...
;             TR_TRY(I_UKV, 1024 / 32, { const int hk = n0 / 128, ek = n0 % 128; tr_item(ap->in[19], 1024, k0, n0, Wukv, 256, ek < 64 ? hk * 64 + ek : 512 + hk * 64 + (ek - 64), k0, scr, lane); })
	ds_write2_b32 v18, v0, v27 offset1:66
	ds_write2_b32 v18, v58, v59 offset0:132 offset1:198
	ds_write2_b32 v20, v60, v61 offset0:8 offset1:74
	ds_write2_b32 v20, v62, v63 offset0:140 offset1:206
	ds_write2_b32 v21, v64, v44 offset0:16 offset1:82
	ds_write2_b32 v21, v45, v46 offset0:148 offset1:214
	ds_write2_b32 v22, v47, v48 offset0:24 offset1:90
	ds_write2_b32 v22, v49, v50 offset0:156 offset1:222
	ds_write2_b32 v23, v51, v52 offset0:32 offset1:98
	ds_write2_b32 v23, v53, v54 offset0:164 offset1:230
	ds_write2_b32 v24, v55, v56 offset0:40 offset1:106
	ds_write2_b32 v24, v57, v42 offset0:172 offset1:238
	ds_write2_b32 v25, v28, v29 offset0:48 offset1:114
	ds_write2_b32 v25, v30, v31 offset0:180 offset1:246
	ds_write2_b32 v26, v32, v33 offset0:56 offset1:122
	ds_write2_b32 v26, v34, v16 offset0:188 offset1:254
	s_waitcnt lgkmcnt(0)
	ds_read_b32 v0, v19
	ds_read_b32 v27, v19 offset:132
	ds_read_b32 v29, v19 offset:264
	ds_read_b32 v30, v19 offset:396
	ds_read_b32 v31, v19 offset:528
	ds_read_b32 v32, v19 offset:660
	ds_read_b32 v33, v19 offset:792
	ds_read_b32 v34, v19 offset:924
	s_waitcnt lgkmcnt(7)
	v_bfe_u32 v28, v0, 16, 1
	v_add3_u32 v0, v0, v28, s59
	s_waitcnt lgkmcnt(6)
	v_bfe_u32 v28, v27, 16, 1
	v_lshrrev_b32_e32 v0, 16, v0
	v_add3_u32 v27, v27, v28, s59
	v_and_or_b32 v28, v27, s60, v0
	s_waitcnt lgkmcnt(5)
	v_bfe_u32 v0, v29, 16, 1
	v_add3_u32 v0, v29, v0, s59
	s_waitcnt lgkmcnt(4)
	v_bfe_u32 v27, v30, 16, 1
	v_lshrrev_b32_e32 v0, 16, v0
	v_add3_u32 v27, v30, v27, s59
	v_and_or_b32 v29, v27, s60, v0
	s_waitcnt lgkmcnt(3)
	v_bfe_u32 v0, v31, 16, 1
	v_add3_u32 v0, v31, v0, s59
	s_waitcnt lgkmcnt(2)
	v_bfe_u32 v27, v32, 16, 1
	s_or_b32 s12, s10, s4
	s_add_i32 s10, s4, s10
	v_lshrrev_b32_e32 v0, 16, v0
	v_add3_u32 v27, v32, v27, s59
	s_addk_i32 s10, 0x1c0
	v_and_or_b32 v30, v27, s60, v0
	s_waitcnt lgkmcnt(1)
	v_bfe_u32 v0, v33, 16, 1
	s_cmp_lt_u32 s4, 64
	v_add3_u32 v0, v33, v0, s59
	s_waitcnt lgkmcnt(0)
	v_bfe_u32 v27, v34, 16, 1
	s_cselect_b32 s4, s12, s10
	v_lshrrev_b32_e32 v0, 16, v0
	v_add3_u32 v27, v34, v27, s59
	s_lshl_b32 s10, s5, 1
	v_and_or_b32 v31, v27, s60, v0
	v_or_b32_e32 v0, s4, v160
	v_lshl_add_u64 v[16:17], v[2:3], 0, s[10:11]
	v_lshlrev_b32_e32 v0, 9, v0
	v_lshl_add_u64 v[32:33], v[16:17], 0, v[0:1]
	global_store_dwordx4 v[32:33], v[28:31], off sc0 sc1
	ds_read_b32 v0, v19 offset:32
	ds_read_b32 v27, v19 offset:164
	ds_read_b32 v29, v19 offset:296
	ds_read_b32 v30, v19 offset:428
	ds_read_b32 v31, v19 offset:560
	ds_read_b32 v32, v19 offset:692
	ds_read_b32 v33, v19 offset:824
	ds_read_b32 v34, v19 offset:956
	s_waitcnt lgkmcnt(0)
	v_bfe_u32 v28, v0, 16, 1
	v_add3_u32 v0, v0, v28, s59
	v_bfe_u32 v28, v27, 16, 1
	v_lshrrev_b32_e32 v0, 16, v0
	v_add3_u32 v27, v27, v28, s59
	v_and_or_b32 v28, v27, s60, v0
	v_bfe_u32 v0, v29, 16, 1
	v_add3_u32 v0, v29, v0, s59
	v_bfe_u32 v27, v30, 16, 1
	v_lshrrev_b32_e32 v0, 16, v0
	v_add3_u32 v27, v30, v27, s59
	v_and_or_b32 v29, v27, s60, v0
	v_bfe_u32 v0, v31, 16, 1
	v_add3_u32 v0, v31, v0, s59
	v_bfe_u32 v27, v32, 16, 1
	v_lshrrev_b32_e32 v0, 16, v0
	v_add3_u32 v27, v32, v27, s59
	v_and_or_b32 v30, v27, s60, v0
	v_bfe_u32 v0, v33, 16, 1
	v_add3_u32 v0, v33, v0, s59
	v_bfe_u32 v27, v34, 16, 1
	v_lshrrev_b32_e32 v0, 16, v0
	v_add3_u32 v27, v34, v27, s59
	v_and_or_b32 v31, v27, s60, v0
	v_or_b32_e32 v0, s4, v161
	v_lshlrev_b32_e32 v0, 9, v0
	v_lshl_add_u64 v[32:33], v[16:17], 0, v[0:1]
	global_store_dwordx4 v[32:33], v[28:31], off sc0 sc1
	ds_read_b32 v0, v19 offset:64
	ds_read_b32 v27, v19 offset:196
	ds_read_b32 v29, v19 offset:328
	ds_read_b32 v30, v19 offset:460
	ds_read_b32 v31, v19 offset:592
	ds_read_b32 v32, v19 offset:724
	ds_read_b32 v33, v19 offset:856
	ds_read_b32 v34, v19 offset:988
	s_waitcnt lgkmcnt(0)
	v_bfe_u32 v28, v0, 16, 1
	v_add3_u32 v0, v0, v28, s59
	v_bfe_u32 v28, v27, 16, 1
	v_lshrrev_b32_e32 v0, 16, v0
	v_add3_u32 v27, v27, v28, s59
	v_and_or_b32 v28, v27, s60, v0
	v_bfe_u32 v0, v29, 16, 1
	v_add3_u32 v0, v29, v0, s59
	v_bfe_u32 v27, v30, 16, 1
	v_lshrrev_b32_e32 v0, 16, v0
	v_add3_u32 v27, v30, v27, s59
	v_and_or_b32 v29, v27, s60, v0
	v_bfe_u32 v0, v31, 16, 1
	v_add3_u32 v0, v31, v0, s59
	v_bfe_u32 v27, v32, 16, 1
	v_lshrrev_b32_e32 v0, 16, v0
	v_add3_u32 v27, v32, v27, s59
	v_and_or_b32 v30, v27, s60, v0
	v_bfe_u32 v0, v33, 16, 1
	v_add3_u32 v0, v33, v0, s59
	v_bfe_u32 v27, v34, 16, 1
	v_lshrrev_b32_e32 v0, 16, v0
	v_add3_u32 v27, v34, v27, s59
	v_and_or_b32 v31, v27, s60, v0
	v_or_b32_e32 v0, s4, v162
	v_lshlrev_b32_e32 v0, 9, v0
	v_lshl_add_u64 v[32:33], v[16:17], 0, v[0:1]
	global_store_dwordx4 v[32:33], v[28:31], off sc0 sc1
	ds_read_b32 v0, v19 offset:96
	ds_read_b32 v27, v19 offset:228
	ds_read_b32 v29, v19 offset:360
	ds_read_b32 v30, v19 offset:492
	ds_read_b32 v31, v19 offset:624
	ds_read_b32 v32, v19 offset:756
	ds_read_b32 v33, v19 offset:888
	ds_read_b32 v34, v19 offset:1020
	s_waitcnt lgkmcnt(0)
	v_bfe_u32 v28, v0, 16, 1
	v_add3_u32 v0, v0, v28, s59
	v_bfe_u32 v28, v27, 16, 1
	v_lshrrev_b32_e32 v0, 16, v0
	v_add3_u32 v27, v27, v28, s59
	v_and_or_b32 v28, v27, s60, v0
	v_bfe_u32 v0, v29, 16, 1
	v_add3_u32 v0, v29, v0, s59
	v_bfe_u32 v27, v30, 16, 1
	v_lshrrev_b32_e32 v0, 16, v0
	v_add3_u32 v27, v30, v27, s59
	v_and_or_b32 v29, v27, s60, v0
	v_bfe_u32 v0, v31, 16, 1
	v_add3_u32 v0, v31, v0, s59
	v_bfe_u32 v27, v32, 16, 1
	v_lshrrev_b32_e32 v0, 16, v0
	v_add3_u32 v27, v32, v27, s59
	v_and_or_b32 v30, v27, s60, v0
	v_bfe_u32 v0, v33, 16, 1
	v_add3_u32 v0, v33, v0, s59
	v_bfe_u32 v27, v34, 16, 1
	v_lshrrev_b32_e32 v0, 16, v0
	v_add3_u32 v27, v34, v27, s59
	v_and_or_b32 v31, v27, s60, v0
	v_or_b32_e32 v0, s4, v163
	v_lshlrev_b32_e32 v0, 9, v0
	v_lshl_add_u64 v[16:17], v[16:17], 0, v[0:1]
	global_store_dwordx4 v[16:17], v[28:31], off sc0 sc1
	s_waitcnt lgkmcnt(0)
	s_mov_b64 s[4:5], 0
; #define LAS __attribute__((address_space(3)))
; #define TR_TRY(CNT, NBLK, ...) if (r < (CNT)) { const int k0 = 64 * (r / (NBLK)), n0 = 32 * (r % (NBLK)); (void)k0; (void)n0; __VA_ARGS__; continue; } r -= (CNT);
; #define TR_TRY(CNT, NBLK, ...) if (r < (CNT)) { const int k0 = 64 * (r / (NBLK)), n0 = 32 * (r % (NBLK)); (void)k0; (void)n0; __VA_ARGS__; continue; } r -= (CNT);
; __device__ __forceinline__ void tr_item(const float* W, int N, int k0, int n0, bf16* WT, int Kd, int drow0, int dk0, LAS float* scr, int lane) {
;     {
;         float wv[32]; const int n = n0 + (lane & 31); const float* wp = W + (size_t)(k0 + (lane >> 5)) * N + n;
; #pragma unroll
;         for (int i = 0; i < 32; ++i) wv[i] = (n < N) ? wp[(size_t)(2 * i) * N] : 0.f;
; #pragma unroll
;         for (int i = 0; i < 32; ++i) scr[(2 * i + (lane >> 5)) * 33 + (lane & 31)] = wv[i];
; __global__ void __launch_bounds__(NTHREADS, 2) mega_fwd(Args a_unused) {
;     ...
;             TR_TRY(I_UQ, 768 / 32, { const int hq = n0 / 96, jq = (n0 % 96) / 32; tr_item(ap->in[18], 768, k0, n0, Wuq, 384, jq < 2 ? hq * 64 + 32 * jq : 512 + hq * 32, k0, scr, lane); })
.LBB0_109:
	s_andn2_b64 vcc, exec, s[4:5]
	s_cbranch_vccnz .LBB0_111
	v_mov_b64_e32 v[16:17], s[38:39]
	global_load_dwordx2 v[16:17], v[16:17], off offset:144
	s_xor_b32 s4, s97, 0xff80
	s_and_b32 s5, s4, 0xff
	s_mulk_i32 s5, 0xab
	s_bfe_u32 s5, s5, 0x4000c
	s_mul_i32 s10, s5, 24
	s_sub_i32 s4, s4, s10
	v_lshl_or_b32 v0, s5, 6, v159
	s_and_b32 s10, s4, 0xff
	v_mul_u32_u24_e32 v0, 0x300, v0
	s_lshl_b32 s4, s10, 5
	v_lshlrev_b32_e32 v0, 2, v0
	v_or_b32_e32 v27, s4, v158
	s_mov_b32 s12, 0x13000
	s_mov_b32 s13, 0x15000
	s_waitcnt vmcnt(0) lgkmcnt(0)
	v_lshl_add_u64 v[16:17], v[16:17], 0, v[0:1]
	v_lshlrev_b32_e32 v0, 2, v27
	v_lshl_add_u64 v[16:17], v[16:17], 0, v[0:1]
	v_add_co_u32_e32 v28, vcc, s61, v16
	s_nop 1
	v_addc_co_u32_e32 v29, vcc, 0, v17, vcc
	v_add_co_u32_e32 v30, vcc, s62, v16
	s_nop 1
	v_addc_co_u32_e32 v31, vcc, 0, v17, vcc
	v_add_co_u32_e32 v32, vcc, s35, v16
	s_nop 1
	v_addc_co_u32_e32 v33, vcc, 0, v17, vcc
	v_add_co_u32_e32 v34, vcc, s40, v16
	s_nop 1
	v_addc_co_u32_e32 v35, vcc, 0, v17, vcc
	v_add_co_u32_e32 v36, vcc, s63, v16
	s_nop 1
	v_addc_co_u32_e32 v37, vcc, 0, v17, vcc
	v_add_co_u32_e32 v38, vcc, s64, v16
	s_nop 1
	v_addc_co_u32_e32 v39, vcc, 0, v17, vcc
	v_add_co_u32_e32 v40, vcc, s42, v16
	s_nop 1
	v_addc_co_u32_e32 v41, vcc, 0, v17, vcc
	v_add_co_u32_e32 v42, vcc, s43, v16
	global_load_dword v0, v[16:17], off nt
	global_load_dword v27, v[28:29], off offset:2048 nt
	global_load_dword v56, v[30:31], off nt
	global_load_dword v57, v[32:33], off offset:2048 nt
	global_load_dword v58, v[34:35], off nt
	global_load_dword v59, v[36:37], off offset:2048 nt
	global_load_dword v60, v[38:39], off nt
	global_load_dword v61, v[40:41], off offset:2048 nt
	v_addc_co_u32_e32 v43, vcc, 0, v17, vcc
	v_add_co_u32_e32 v44, vcc, s65, v16
	s_nop 1
	v_addc_co_u32_e32 v45, vcc, 0, v17, vcc
	v_add_co_u32_e32 v46, vcc, s66, v16
	s_nop 1
	v_addc_co_u32_e32 v47, vcc, 0, v17, vcc
	v_add_co_u32_e32 v48, vcc, s45, v16
	s_nop 1
	v_addc_co_u32_e32 v49, vcc, 0, v17, vcc
	v_add_co_u32_e32 v50, vcc, s46, v16
	s_nop 1
	v_addc_co_u32_e32 v51, vcc, 0, v17, vcc
	v_add_co_u32_e32 v52, vcc, s12, v16
	s_mov_b32 s12, 0x19000
	s_nop 0
	v_addc_co_u32_e32 v53, vcc, 0, v17, vcc
	v_add_co_u32_e32 v54, vcc, s13, v16
	s_nop 1
	v_addc_co_u32_e32 v55, vcc, 0, v17, vcc
	v_add_co_u32_e32 v28, vcc, s47, v16
	s_nop 1
	v_addc_co_u32_e32 v29, vcc, 0, v17, vcc
	global_load_dword v62, v[42:43], off nt
	s_nop 0
	global_load_dword v44, v[44:45], off offset:2048 nt
	s_nop 0
	global_load_dword v45, v[46:47], off nt
	s_nop 0
	global_load_dword v46, v[48:49], off offset:2048 nt
	global_load_dword v47, v[50:51], off nt
	s_nop 0
	global_load_dword v48, v[52:53], off offset:2048 nt
	global_load_dword v49, v[54:55], off nt
	global_load_dword v50, v[28:29], off offset:2048 nt
	v_add_co_u32_e32 v28, vcc, s48, v16
	s_nop 1
	v_addc_co_u32_e32 v29, vcc, 0, v17, vcc
	v_add_co_u32_e32 v30, vcc, s12, v16
	s_mov_b32 s12, 0x1f000
	s_nop 0
	v_addc_co_u32_e32 v31, vcc, 0, v17, vcc
	v_add_co_u32_e32 v32, vcc, s67, v16
	s_nop 1
	v_addc_co_u32_e32 v33, vcc, 0, v17, vcc
	v_add_co_u32_e32 v34, vcc, s49, v16
	s_nop 1
	v_addc_co_u32_e32 v35, vcc, 0, v17, vcc
	v_add_co_u32_e32 v36, vcc, s50, v16
	s_nop 1
	v_addc_co_u32_e32 v37, vcc, 0, v17, vcc
	v_add_co_u32_e32 v38, vcc, s12, v16
	s_mov_b32 s12, 0x25000
	s_nop 0
	v_addc_co_u32_e32 v39, vcc, 0, v17, vcc
	v_add_co_u32_e32 v40, vcc, s68, v16
	s_nop 1
	v_addc_co_u32_e32 v41, vcc, 0, v17, vcc
	v_add_co_u32_e32 v42, vcc, s51, v16
	s_nop 1
	v_addc_co_u32_e32 v43, vcc, 0, v17, vcc
	global_load_dword v51, v[28:29], off nt
	global_load_dword v52, v[30:31], off offset:2048 nt
	global_load_dword v53, v[32:33], off nt
	global_load_dword v54, v[34:35], off offset:2048 nt
	global_load_dword v55, v[36:37], off nt
	global_load_dword v63, v[38:39], off offset:2048 nt
	global_load_dword v64, v[40:41], off nt
	s_nop 0
	global_load_dword v42, v[42:43], off offset:2048 nt
	v_add_co_u32_e32 v28, vcc, s52, v16
	s_nop 1
	v_addc_co_u32_e32 v29, vcc, 0, v17, vcc
	v_add_co_u32_e32 v30, vcc, s12, v16
	s_mov_b32 s12, 0x27000
	s_nop 0
	v_addc_co_u32_e32 v31, vcc, 0, v17, vcc
	v_add_co_u32_e32 v32, vcc, s12, v16
	s_mov_b32 s12, 0x2b000
	s_nop 0
	v_addc_co_u32_e32 v33, vcc, 0, v17, vcc
	v_add_co_u32_e32 v34, vcc, s54, v16
	s_nop 1
	v_addc_co_u32_e32 v35, vcc, 0, v17, vcc
	v_add_co_u32_e32 v36, vcc, s55, v16
	s_nop 1
	v_addc_co_u32_e32 v37, vcc, 0, v17, vcc
	v_add_co_u32_e32 v38, vcc, s12, v16
	s_mov_b32 s12, 0x2d000
	s_nop 0
	v_addc_co_u32_e32 v39, vcc, 0, v17, vcc
	v_add_co_u32_e32 v40, vcc, s12, v16
	s_mul_i32 s12, s10, 0xab
	s_nop 0
	v_addc_co_u32_e32 v41, vcc, 0, v17, vcc
	v_add_co_u32_e32 v16, vcc, s57, v16
	s_mul_i32 s10, s10, 0x15560
	s_nop 0
	v_addc_co_u32_e32 v17, vcc, 0, v17, vcc
	global_load_dword v28, v[28:29], off nt
	s_nop 0
	global_load_dword v29, v[30:31], off offset:2048 nt
	s_nop 0
	global_load_dword v30, v[32:33], off nt
	global_load_dword v31, v[34:35], off offset:2048 nt
	s_nop 0
	global_load_dword v32, v[36:37], off nt
	global_load_dword v33, v[38:39], off offset:2048 nt
	global_load_dword v34, v[40:41], off nt
	s_nop 0
	global_load_dword v16, v[16:17], off offset:2048 nt
	s_waitcnt vmcnt(0) lgkmcnt(0)
; #define LAS __attribute__((address_space(3)))
; #define LDS_WAIT() asm volatile("s_waitcnt lgkmcnt(0)" ::: "memory")
; __device__ __forceinline__ unsigned pk2(float lo, float hi) { return f2bf(lo) | (f2bf(hi) << 16); }
; #define TR_TRY(CNT, NBLK, ...) if (r < (CNT)) { const int k0 = 64 * (r / (NBLK)), n0 = 32 * (r % (NBLK)); (void)k0; (void)n0; __VA_ARGS__; continue; } r -= (CNT);
; #define TR_TRY(CNT, NBLK, ...) if (r < (CNT)) { const int k0 = 64 * (r / (NBLK)), n0 = 32 * (r % (NBLK)); (void)k0; (void)n0; __VA_ARGS__; continue; } r -= (CNT);
; __device__ __forceinline__ void tr_item(const float* W, int N, int k0, int n0, bf16* WT, int Kd, int drow0, int dk0, LAS float* scr, int lane) {
;     ...
;         for (int i = 0; i < 32; ++i) scr[(2 * i + (lane >> 5)) * 33 + (lane & 31)] = wv[i];
;     }
;     LDS_WAIT();
;     const int c = lane & 7;
; #pragma unroll
;     for (int j = 0; j < 4; ++j) { const int n = (lane >> 3) + 8 * j; const LAS float* s = scr + (8 * c) * 33 + n;
;         v4u o; o.x = pk2(s[0 * 33], s[1 * 33]); o.y = pk2(s[2 * 33], s[3 * 33]); o.z = pk2(s[4 * 33], s[5 * 33]); o.w = pk2(s[6 * 33], s[7 * 33]);
;         *(v4u*)(WT + (size_t)(drow0 + n) * Kd + dk0 + 8 * c) = o; }
;     LDS_WAIT();
; __global__ void __launch_bounds__(NTHREADS, 2) mega_fwd(Args a_unused) {
;     ...
;             TR_TRY(I_UQ, 768 / 32, { const int hq = n0 / 96, jq = (n0 % 96) / 32; tr_item(ap->in[18], 768, k0, n0, Wuq, 384, jq < 2 ? hq * 64 + 32 * jq : 512 + hq * 32, k0, scr, lane); })
	ds_write2_b32 v18, v0, v27 offset1:66
	ds_write2_b32 v18, v56, v57 offset0:132 offset1:198
	ds_write2_b32 v20, v58, v59 offset0:8 offset1:74
	ds_write2_b32 v20, v60, v61 offset0:140 offset1:206
	ds_write2_b32 v21, v62, v44 offset0:16 offset1:82
	ds_write2_b32 v21, v45, v46 offset0:148 offset1:214
	ds_write2_b32 v22, v47, v48 offset0:24 offset1:90
	ds_write2_b32 v22, v49, v50 offset0:156 offset1:222
	ds_write2_b32 v23, v51, v52 offset0:32 offset1:98
	ds_write2_b32 v23, v53, v54 offset0:164 offset1:230
	ds_write2_b32 v24, v55, v63 offset0:40 offset1:106
	ds_write2_b32 v24, v64, v42 offset0:172 offset1:238
	ds_write2_b32 v25, v28, v29 offset0:48 offset1:114
	ds_write2_b32 v25, v30, v31 offset0:180 offset1:246
	ds_write2_b32 v26, v32, v33 offset0:56 offset1:122
	ds_write2_b32 v26, v34, v16 offset0:188 offset1:254
	s_waitcnt lgkmcnt(0)
	ds_read_b32 v0, v19
	ds_read_b32 v27, v19 offset:132
	ds_read_b32 v29, v19 offset:264
	ds_read_b32 v30, v19 offset:396
	ds_read_b32 v31, v19 offset:528
	ds_read_b32 v32, v19 offset:660
	ds_read_b32 v33, v19 offset:792
	ds_read_b32 v34, v19 offset:924
	s_waitcnt lgkmcnt(7)
	v_bfe_u32 v28, v0, 16, 1
	v_add3_u32 v0, v0, v28, s59
	s_waitcnt lgkmcnt(6)
	v_bfe_u32 v28, v27, 16, 1
	v_lshrrev_b32_e32 v0, 16, v0
	v_add3_u32 v27, v27, v28, s59
	v_and_or_b32 v28, v27, s60, v0
	s_waitcnt lgkmcnt(5)
	v_bfe_u32 v0, v29, 16, 1
	v_add3_u32 v0, v29, v0, s59
	s_waitcnt lgkmcnt(4)
	v_bfe_u32 v27, v30, 16, 1
	s_lshr_b32 s10, s10, 18
	v_lshrrev_b32_e32 v0, 16, v0
	v_add3_u32 v27, v30, v27, s59
	s_mulk_i32 s10, 0x60
	v_and_or_b32 v29, v27, s60, v0
	s_waitcnt lgkmcnt(3)
	v_bfe_u32 v0, v31, 16, 1
	s_bfe_u32 s12, s12, 0x70009
	s_sub_i32 s4, s4, s10
	v_add3_u32 v0, v31, v0, s59
	s_waitcnt lgkmcnt(2)
	v_bfe_u32 v27, v32, 16, 1
	s_and_b32 s4, s4, 0xffe0
	s_lshl_b32 s10, s12, 6
	s_lshl_b32 s12, s12, 5
	v_lshrrev_b32_e32 v0, 16, v0
	v_add3_u32 v27, v32, v27, s59
	s_add_i32 s10, s10, s4
	s_bitset1_b32 s12, 9
	v_and_or_b32 v30, v27, s60, v0
	s_waitcnt lgkmcnt(1)
	v_bfe_u32 v0, v33, 16, 1
	s_cmp_lt_u32 s4, 64
	v_add3_u32 v0, v33, v0, s59
	s_waitcnt lgkmcnt(0)
	v_bfe_u32 v27, v34, 16, 1
	s_cselect_b32 s4, s10, s12
	v_lshrrev_b32_e32 v0, 16, v0
	v_add3_u32 v27, v34, v27, s59
	s_lshl_b32 s10, s5, 7
	v_and_or_b32 v31, v27, s60, v0
	v_or_b32_e32 v0, s4, v160
	v_lshl_add_u64 v[16:17], v[4:5], 0, s[10:11]
	v_mul_u32_u24_e32 v0, 0x180, v0
	v_lshl_add_u64 v[32:33], v[0:1], 1, v[16:17]
	global_store_dwordx4 v[32:33], v[28:31], off sc0 sc1
	ds_read_b32 v0, v19 offset:32
	ds_read_b32 v27, v19 offset:164
	ds_read_b32 v29, v19 offset:296
	ds_read_b32 v30, v19 offset:428
	ds_read_b32 v31, v19 offset:560
	ds_read_b32 v32, v19 offset:692
	ds_read_b32 v33, v19 offset:824
	ds_read_b32 v34, v19 offset:956
	s_waitcnt lgkmcnt(0)
	v_bfe_u32 v28, v0, 16, 1
	v_add3_u32 v0, v0, v28, s59
	v_bfe_u32 v28, v27, 16, 1
	v_lshrrev_b32_e32 v0, 16, v0
	v_add3_u32 v27, v27, v28, s59
	v_and_or_b32 v28, v27, s60, v0
	v_bfe_u32 v0, v29, 16, 1
	v_add3_u32 v0, v29, v0, s59
	v_bfe_u32 v27, v30, 16, 1
	v_lshrrev_b32_e32 v0, 16, v0
	v_add3_u32 v27, v30, v27, s59
	v_and_or_b32 v29, v27, s60, v0
	v_bfe_u32 v0, v31, 16, 1
	v_add3_u32 v0, v31, v0, s59
	v_bfe_u32 v27, v32, 16, 1
	v_lshrrev_b32_e32 v0, 16, v0
	v_add3_u32 v27, v32, v27, s59
	v_and_or_b32 v30, v27, s60, v0
	v_bfe_u32 v0, v33, 16, 1
	v_add3_u32 v0, v33, v0, s59
	v_bfe_u32 v27, v34, 16, 1
	v_lshrrev_b32_e32 v0, 16, v0
	v_add3_u32 v27, v34, v27, s59
	v_and_or_b32 v31, v27, s60, v0
	v_or_b32_e32 v0, s4, v161
	v_mul_u32_u24_e32 v0, 0x180, v0
	v_lshl_add_u64 v[32:33], v[0:1], 1, v[16:17]
	global_store_dwordx4 v[32:33], v[28:31], off sc0 sc1
	ds_read_b32 v0, v19 offset:64
	ds_read_b32 v27, v19 offset:196
	ds_read_b32 v29, v19 offset:328
	ds_read_b32 v30, v19 offset:460
	ds_read_b32 v31, v19 offset:592
	ds_read_b32 v32, v19 offset:724
	ds_read_b32 v33, v19 offset:856
	ds_read_b32 v34, v19 offset:988
	s_waitcnt lgkmcnt(0)
	v_bfe_u32 v28, v0, 16, 1
	v_add3_u32 v0, v0, v28, s59
	v_bfe_u32 v28, v27, 16, 1
	v_lshrrev_b32_e32 v0, 16, v0
	v_add3_u32 v27, v27, v28, s59
	v_and_or_b32 v28, v27, s60, v0
	v_bfe_u32 v0, v29, 16, 1
	v_add3_u32 v0, v29, v0, s59
	v_bfe_u32 v27, v30, 16, 1
	v_lshrrev_b32_e32 v0, 16, v0
	v_add3_u32 v27, v30, v27, s59
	v_and_or_b32 v29, v27, s60, v0
	v_bfe_u32 v0, v31, 16, 1
	v_add3_u32 v0, v31, v0, s59
	v_bfe_u32 v27, v32, 16, 1
	v_lshrrev_b32_e32 v0, 16, v0
	v_add3_u32 v27, v32, v27, s59
	v_and_or_b32 v30, v27, s60, v0
	v_bfe_u32 v0, v33, 16, 1
	v_add3_u32 v0, v33, v0, s59
	v_bfe_u32 v27, v34, 16, 1
	v_lshrrev_b32_e32 v0, 16, v0
	v_add3_u32 v27, v34, v27, s59
	v_and_or_b32 v31, v27, s60, v0
	v_or_b32_e32 v0, s4, v162
	v_mul_u32_u24_e32 v0, 0x180, v0
	v_lshl_add_u64 v[32:33], v[0:1], 1, v[16:17]
	global_store_dwordx4 v[32:33], v[28:31], off sc0 sc1
	ds_read_b32 v0, v19 offset:96
	ds_read_b32 v27, v19 offset:228
	ds_read_b32 v29, v19 offset:360
	ds_read_b32 v30, v19 offset:492
	ds_read_b32 v31, v19 offset:624
	ds_read_b32 v32, v19 offset:756
	ds_read_b32 v33, v19 offset:888
	ds_read_b32 v34, v19 offset:1020
	s_waitcnt lgkmcnt(0)
	v_bfe_u32 v28, v0, 16, 1
	v_add3_u32 v0, v0, v28, s59
	v_bfe_u32 v28, v27, 16, 1
	v_lshrrev_b32_e32 v0, 16, v0
	v_add3_u32 v27, v27, v28, s59
	v_and_or_b32 v28, v27, s60, v0
	v_bfe_u32 v0, v29, 16, 1
	v_add3_u32 v0, v29, v0, s59
	v_bfe_u32 v27, v30, 16, 1
	v_lshrrev_b32_e32 v0, 16, v0
	v_add3_u32 v27, v30, v27, s59
	v_and_or_b32 v29, v27, s60, v0
	v_bfe_u32 v0, v31, 16, 1
	v_add3_u32 v0, v31, v0, s59
	v_bfe_u32 v27, v32, 16, 1
	v_lshrrev_b32_e32 v0, 16, v0
	v_add3_u32 v27, v32, v27, s59
	v_and_or_b32 v30, v27, s60, v0
	v_bfe_u32 v0, v33, 16, 1
	v_add3_u32 v0, v33, v0, s59
	v_bfe_u32 v27, v34, 16, 1
	v_lshrrev_b32_e32 v0, 16, v0
	v_add3_u32 v27, v34, v27, s59
	v_and_or_b32 v31, v27, s60, v0
	v_or_b32_e32 v0, s4, v163
	v_mul_u32_u24_e32 v0, 0x180, v0
	v_lshl_add_u64 v[16:17], v[0:1], 1, v[16:17]
	global_store_dwordx4 v[16:17], v[28:31], off sc0 sc1
	s_waitcnt lgkmcnt(0)

; #define LAS __attribute__((address_space(3)))
; #define TR_TRY(CNT, NBLK, ...) if (r < (CNT)) { const int k0 = 64 * (r / (NBLK)), n0 = 32 * (r % (NBLK)); (void)k0; (void)n0; __VA_ARGS__; continue; } r -= (CNT);
; #define TR_TRY(CNT, NBLK, ...) if (r < (CNT)) { const int k0 = 64 * (r / (NBLK)), n0 = 32 * (r % (NBLK)); (void)k0; (void)n0; __VA_ARGS__; continue; } r -= (CNT);
; __device__ __forceinline__ void tr_item(const float* W, int N, int k0, int n0, bf16* WT, int Kd, int drow0, int dk0, LAS float* scr, int lane) {
;     {
;         float wv[32]; const int n = n0 + (lane & 31); const float* wp = W + (size_t)(k0 + (lane >> 5)) * N + n;
; #pragma unroll
;         for (int i = 0; i < 32; ++i) wv[i] = (n < N) ? wp[(size_t)(2 * i) * N] : 0.f;
; #pragma unroll
;         for (int i = 0; i < 32; ++i) scr[(2 * i + (lane >> 5)) * 33 + (lane & 31)] = wv[i];
; __global__ void __launch_bounds__(NTHREADS, 2) mega_fwd(Args a_unused) {
;     ...
;             TR_TRY(I_W1, 256 / 32, tr_item(ap->in[14], 256, k0, n0, W1v, 1024, (k0 >= 1024 ? 256 : 0) + n0, k0 & 1023, scr, lane))
.LBB0_112:
	s_andn2_b64 vcc, exec, s[4:5]
	s_cbranch_vccnz .LBB0_114
	v_mov_b64_e32 v[16:17], s[38:39]
	global_load_dwordx2 v[16:17], v[16:17], off offset:112
	s_add_i32 s5, s19, 0x7fff5400
	s_and_b32 s5, s5, 0x7fffffc0
	s_and_b32 s4, s7, 0xe0
	v_or_b32_e32 v0, s5, v159
	v_or_b32_e32 v27, s4, v158
	v_lshlrev_b64 v[28:29], 10, v[0:1]
	v_lshlrev_b32_e32 v0, 2, v27
	s_cmpk_gt_u32 s5, 0x3ff
	s_cselect_b32 s5, 0x100, 0
	s_and_b32 s10, s19, 0x3c0
	s_or_b32 s4, s5, s4
	s_lshl_b32 s10, s10, 1
	s_waitcnt vmcnt(0) lgkmcnt(0)
	v_lshl_add_u64 v[16:17], v[16:17], 0, v[28:29]
	v_lshl_add_u64 v[16:17], v[16:17], 0, v[0:1]
	v_add_co_u32_e32 v28, vcc, s61, v16
	v_or_b32_e32 v0, s4, v160
	s_nop 0
	v_addc_co_u32_e32 v29, vcc, 0, v17, vcc
	v_add_co_u32_e32 v30, vcc, s21, v16
	v_lshlrev_b32_e32 v0, 11, v0
	s_nop 0
	v_addc_co_u32_e32 v31, vcc, 0, v17, vcc
	v_add_co_u32_e32 v32, vcc, s62, v16
	s_nop 1
	v_addc_co_u32_e32 v33, vcc, 0, v17, vcc
	v_add_co_u32_e32 v34, vcc, s35, v16
	s_nop 1
	v_addc_co_u32_e32 v35, vcc, 0, v17, vcc
	v_add_co_u32_e32 v36, vcc, s70, v16
	s_nop 1
	v_addc_co_u32_e32 v37, vcc, 0, v17, vcc
	v_add_co_u32_e32 v38, vcc, s40, v16
	s_nop 1
	v_addc_co_u32_e32 v39, vcc, 0, v17, vcc
	v_add_co_u32_e32 v40, vcc, s63, v16
	s_nop 1
	v_addc_co_u32_e32 v41, vcc, 0, v17, vcc
	v_add_co_u32_e32 v42, vcc, s41, v16
	s_nop 1
	v_addc_co_u32_e32 v43, vcc, 0, v17, vcc
	v_add_co_u32_e32 v44, vcc, s64, v16
	s_nop 1
	v_addc_co_u32_e32 v45, vcc, 0, v17, vcc
	v_add_co_u32_e32 v46, vcc, s42, v16
	s_nop 1
	v_addc_co_u32_e32 v47, vcc, 0, v17, vcc
	v_add_co_u32_e32 v48, vcc, s71, v16
	s_nop 1
	v_addc_co_u32_e32 v49, vcc, 0, v17, vcc
	v_add_co_u32_e32 v50, vcc, s43, v16
	global_load_dword v27, v[16:17], off nt
	global_load_dword v52, v[16:17], off offset:2048 nt
	global_load_dword v53, v[28:29], off nt
	global_load_dword v54, v[28:29], off offset:2048 nt
	global_load_dword v55, v[30:31], off nt
	global_load_dword v56, v[30:31], off offset:2048 nt
	global_load_dword v57, v[32:33], off nt
	global_load_dword v58, v[32:33], off offset:2048 nt
	global_load_dword v59, v[34:35], off nt
	s_nop 0
	global_load_dword v34, v[34:35], off offset:2048 nt
	s_nop 0
	global_load_dword v35, v[36:37], off nt
	s_nop 0
	global_load_dword v36, v[36:37], off offset:2048 nt
	s_nop 0
	global_load_dword v37, v[38:39], off nt
	s_nop 0
	global_load_dword v38, v[38:39], off offset:2048 nt
	s_nop 0
	global_load_dword v39, v[40:41], off nt
	s_nop 0
	global_load_dword v40, v[40:41], off offset:2048 nt
	s_nop 0
	global_load_dword v41, v[42:43], off nt
	s_nop 0
	global_load_dword v42, v[42:43], off offset:2048 nt
	s_nop 0
	global_load_dword v43, v[44:45], off nt
	s_nop 0
	global_load_dword v44, v[44:45], off offset:2048 nt
	s_nop 0
	global_load_dword v45, v[46:47], off nt
	s_nop 0
	global_load_dword v46, v[46:47], off offset:2048 nt
	s_nop 0
	global_load_dword v47, v[48:49], off nt
	s_nop 0
	global_load_dword v48, v[48:49], off offset:2048 nt
	v_addc_co_u32_e32 v51, vcc, 0, v17, vcc
	v_add_co_u32_e32 v28, vcc, s65, v16
	s_nop 1
	v_addc_co_u32_e32 v29, vcc, 0, v17, vcc
	v_add_co_u32_e32 v30, vcc, s44, v16
	s_nop 1
	v_addc_co_u32_e32 v31, vcc, 0, v17, vcc
	v_add_co_u32_e32 v16, vcc, s66, v16
	s_nop 1
	v_addc_co_u32_e32 v17, vcc, 0, v17, vcc
	global_load_dword v49, v[50:51], off nt
	s_nop 0
	global_load_dword v50, v[50:51], off offset:2048 nt
	s_nop 0
	global_load_dword v51, v[28:29], off nt
	s_nop 0
	global_load_dword v28, v[28:29], off offset:2048 nt
	s_nop 0
	global_load_dword v29, v[30:31], off nt
	s_nop 0
	global_load_dword v30, v[30:31], off offset:2048 nt
	s_nop 0
	global_load_dword v31, v[16:17], off nt
	global_load_dword v60, v[16:17], off offset:2048 nt
	v_lshl_add_u64 v[16:17], v[6:7], 0, s[10:11]
	v_lshl_add_u64 v[32:33], v[16:17], 0, v[0:1]
	s_waitcnt vmcnt(0) lgkmcnt(0)
	ds_write2_b32 v18, v27, v52 offset1:66
	ds_write2_b32 v18, v53, v54 offset0:132 offset1:198
	ds_write2_b32 v20, v55, v56 offset0:8 offset1:74
	ds_write2_b32 v20, v57, v58 offset0:140 offset1:206
	ds_write2_b32 v21, v59, v34 offset0:16 offset1:82
	ds_write2_b32 v21, v35, v36 offset0:148 offset1:214
	ds_write2_b32 v22, v37, v38 offset0:24 offset1:90
	ds_write2_b32 v22, v39, v40 offset0:156 offset1:222
	ds_write2_b32 v23, v41, v42 offset0:32 offset1:98
	ds_write2_b32 v23, v43, v44 offset0:164 offset1:230
	ds_write2_b32 v24, v45, v46 offset0:40 offset1:106
	ds_write2_b32 v24, v47, v48 offset0:172 offset1:238
	ds_write2_b32 v25, v49, v50 offset0:48 offset1:114
	ds_write2_b32 v25, v51, v28 offset0:180 offset1:246
	ds_write2_b32 v26, v29, v30 offset0:56 offset1:122
	ds_write2_b32 v26, v31, v60 offset0:188 offset1:254
	s_waitcnt lgkmcnt(0)
; #define LAS __attribute__((address_space(3)))
; #define LDS_WAIT() asm volatile("s_waitcnt lgkmcnt(0)" ::: "memory")
; __device__ __forceinline__ unsigned pk2(float lo, float hi) { return f2bf(lo) | (f2bf(hi) << 16); }
; #define TR_TRY(CNT, NBLK, ...) if (r < (CNT)) { const int k0 = 64 * (r / (NBLK)), n0 = 32 * (r % (NBLK)); (void)k0; (void)n0; __VA_ARGS__; continue; } r -= (CNT);
; #define TR_TRY(CNT, NBLK, ...) if (r < (CNT)) { const int k0 = 64 * (r / (NBLK)), n0 = 32 * (r % (NBLK)); (void)k0; (void)n0; __VA_ARGS__; continue; } r -= (CNT);
; __device__ __forceinline__ void tr_item(const float* W, int N, int k0, int n0, bf16* WT, int Kd, int drow0, int dk0, LAS float* scr, int lane) {
;     ...
;         for (int i = 0; i < 32; ++i) scr[(2 * i + (lane >> 5)) * 33 + (lane & 31)] = wv[i];
;     }
;     LDS_WAIT();
;     const int c = lane & 7;
; #pragma unroll
;     for (int j = 0; j < 4; ++j) { const int n = (lane >> 3) + 8 * j; const LAS float* s = scr + (8 * c) * 33 + n;
;         v4u o; o.x = pk2(s[0 * 33], s[1 * 33]); o.y = pk2(s[2 * 33], s[3 * 33]); o.z = pk2(s[4 * 33], s[5 * 33]); o.w = pk2(s[6 * 33], s[7 * 33]);
;         *(v4u*)(WT + (size_t)(drow0 + n) * Kd + dk0 + 8 * c) = o; }
;     LDS_WAIT();
; __global__ void __launch_bounds__(NTHREADS, 2) mega_fwd(Args a_unused) {
;     ...
;             TR_TRY(I_W1, 256 / 32, tr_item(ap->in[14], 256, k0, n0, W1v, 1024, (k0 >= 1024 ? 256 : 0) + n0, k0 & 1023, scr, lane))
	ds_read_b32 v0, v19
	ds_read_b32 v27, v19 offset:132
	ds_read_b32 v28, v19 offset:264
	ds_read_b32 v29, v19 offset:396
	ds_read_b32 v30, v19 offset:528
	ds_read_b32 v31, v19 offset:660
	ds_read_b32 v34, v19 offset:792
	ds_read_b32 v35, v19 offset:924
	s_waitcnt lgkmcnt(7)
	v_bfe_u32 v36, v0, 16, 1
	s_waitcnt lgkmcnt(5)
	v_bfe_u32 v38, v28, 16, 1
	s_waitcnt lgkmcnt(3)
	v_bfe_u32 v40, v30, 16, 1
	s_waitcnt lgkmcnt(1)
	v_bfe_u32 v42, v34, 16, 1
	v_bfe_u32 v37, v27, 16, 1
	v_bfe_u32 v39, v29, 16, 1
	v_bfe_u32 v41, v31, 16, 1
	s_waitcnt lgkmcnt(0)
	v_bfe_u32 v43, v35, 16, 1
	v_add3_u32 v0, v0, v36, s59
	v_add3_u32 v28, v28, v38, s59
	v_add3_u32 v30, v30, v40, s59
	v_add3_u32 v34, v34, v42, s59
	v_add3_u32 v27, v27, v37, s59
	v_add3_u32 v29, v29, v39, s59
	v_add3_u32 v31, v31, v41, s59
	v_add3_u32 v35, v35, v43, s59
	v_lshrrev_b32_e32 v0, 16, v0
	v_lshrrev_b32_e32 v36, 16, v28
	v_lshrrev_b32_e32 v30, 16, v30
	v_lshrrev_b32_e32 v34, 16, v34
	v_and_or_b32 v28, v27, s60, v0
	v_and_or_b32 v29, v29, s60, v36
	v_and_or_b32 v30, v31, s60, v30
	v_and_or_b32 v31, v35, s60, v34
	global_store_dwordx4 v[32:33], v[28:31], off sc0 sc1
	ds_read_b32 v0, v19 offset:32
	ds_read_b32 v27, v19 offset:164
	ds_read_b32 v28, v19 offset:296
	ds_read_b32 v29, v19 offset:428
	ds_read_b32 v30, v19 offset:560
	ds_read_b32 v31, v19 offset:692
	ds_read_b32 v32, v19 offset:824
	ds_read_b32 v33, v19 offset:956
	s_waitcnt lgkmcnt(0)
	v_bfe_u32 v34, v0, 16, 1
	v_bfe_u32 v35, v27, 16, 1
	v_bfe_u32 v36, v28, 16, 1
	v_add3_u32 v0, v0, v34, s59
	v_bfe_u32 v38, v30, 16, 1
	v_add3_u32 v27, v27, v35, s59
	v_add3_u32 v28, v28, v36, s59
	v_lshrrev_b32_e32 v0, 16, v0
	v_add3_u32 v30, v30, v38, s59
	v_lshrrev_b32_e32 v34, 16, v28
	v_and_or_b32 v28, v27, s60, v0
	v_bfe_u32 v0, v31, 16, 1
	v_lshrrev_b32_e32 v30, 16, v30
	v_add3_u32 v0, v31, v0, s59
	v_and_or_b32 v30, v0, s60, v30
	v_bfe_u32 v0, v32, 16, 1
	v_add3_u32 v0, v32, v0, s59
	v_bfe_u32 v27, v33, 16, 1
	v_lshrrev_b32_e32 v0, 16, v0
	v_add3_u32 v27, v33, v27, s59
	v_bfe_u32 v37, v29, 16, 1
	v_and_or_b32 v31, v27, s60, v0
	v_or_b32_e32 v0, s4, v161
	v_add3_u32 v29, v29, v37, s59
	v_lshlrev_b32_e32 v0, 11, v0
	v_and_or_b32 v29, v29, s60, v34
	v_lshl_add_u64 v[32:33], v[16:17], 0, v[0:1]
	global_store_dwordx4 v[32:33], v[28:31], off sc0 sc1
	ds_read_b32 v0, v19 offset:64
	ds_read_b32 v27, v19 offset:196
	ds_read_b32 v29, v19 offset:328
	ds_read_b32 v30, v19 offset:460
	ds_read_b32 v31, v19 offset:592
	ds_read_b32 v32, v19 offset:724
	ds_read_b32 v33, v19 offset:856
	ds_read_b32 v34, v19 offset:988
	s_waitcnt lgkmcnt(0)
	v_bfe_u32 v28, v0, 16, 1
	v_add3_u32 v0, v0, v28, s59
	v_bfe_u32 v28, v27, 16, 1
	v_lshrrev_b32_e32 v0, 16, v0
	v_add3_u32 v27, v27, v28, s59
	v_and_or_b32 v28, v27, s60, v0
	v_bfe_u32 v0, v29, 16, 1
	v_add3_u32 v0, v29, v0, s59
	v_bfe_u32 v27, v30, 16, 1
	v_lshrrev_b32_e32 v0, 16, v0
	v_add3_u32 v27, v30, v27, s59
	v_and_or_b32 v29, v27, s60, v0
	v_bfe_u32 v0, v31, 16, 1
	v_add3_u32 v0, v31, v0, s59
	v_bfe_u32 v27, v32, 16, 1
	v_lshrrev_b32_e32 v0, 16, v0
	v_add3_u32 v27, v32, v27, s59
	v_and_or_b32 v30, v27, s60, v0
	v_bfe_u32 v0, v33, 16, 1
	v_add3_u32 v0, v33, v0, s59
	v_bfe_u32 v27, v34, 16, 1
	v_lshrrev_b32_e32 v0, 16, v0
	v_add3_u32 v27, v34, v27, s59
	v_and_or_b32 v31, v27, s60, v0
	v_or_b32_e32 v0, s4, v162
	v_lshlrev_b32_e32 v0, 11, v0
	v_lshl_add_u64 v[32:33], v[16:17], 0, v[0:1]
	global_store_dwordx4 v[32:33], v[28:31], off sc0 sc1
	ds_read_b32 v0, v19 offset:96
	ds_read_b32 v27, v19 offset:228
	ds_read_b32 v29, v19 offset:360
	ds_read_b32 v30, v19 offset:492
	ds_read_b32 v31, v19 offset:624
	ds_read_b32 v32, v19 offset:756
	ds_read_b32 v33, v19 offset:888
	ds_read_b32 v34, v19 offset:1020
	s_waitcnt lgkmcnt(0)
	v_bfe_u32 v28, v0, 16, 1
	v_add3_u32 v0, v0, v28, s59
	v_bfe_u32 v28, v27, 16, 1
	v_lshrrev_b32_e32 v0, 16, v0
	v_add3_u32 v27, v27, v28, s59
	v_and_or_b32 v28, v27, s60, v0
	v_bfe_u32 v0, v29, 16, 1
	v_add3_u32 v0, v29, v0, s59
	v_bfe_u32 v27, v30, 16, 1
	v_lshrrev_b32_e32 v0, 16, v0
	v_add3_u32 v27, v30, v27, s59
	v_and_or_b32 v29, v27, s60, v0
	v_bfe_u32 v0, v31, 16, 1
	v_add3_u32 v0, v31, v0, s59
	v_bfe_u32 v27, v32, 16, 1
	v_lshrrev_b32_e32 v0, 16, v0
	v_add3_u32 v27, v32, v27, s59
	v_and_or_b32 v30, v27, s60, v0
	v_bfe_u32 v0, v33, 16, 1
	v_add3_u32 v0, v33, v0, s59
	v_bfe_u32 v27, v34, 16, 1
	v_lshrrev_b32_e32 v0, 16, v0
	v_add3_u32 v27, v34, v27, s59
	v_and_or_b32 v31, v27, s60, v0
	v_or_b32_e32 v0, s4, v163
	v_lshlrev_b32_e32 v0, 11, v0
	v_lshl_add_u64 v[16:17], v[16:17], 0, v[0:1]
	global_store_dwordx4 v[16:17], v[28:31], off sc0 sc1
	s_waitcnt lgkmcnt(0)

; #define LAS __attribute__((address_space(3)))
; #define TR_TRY(CNT, NBLK, ...) if (r < (CNT)) { const int k0 = 64 * (r / (NBLK)), n0 = 32 * (r % (NBLK)); (void)k0; (void)n0; __VA_ARGS__; continue; } r -= (CNT);
; #define TR_TRY(CNT, NBLK, ...) if (r < (CNT)) { const int k0 = 64 * (r / (NBLK)), n0 = 32 * (r % (NBLK)); (void)k0; (void)n0; __VA_ARGS__; continue; } r -= (CNT);
; __device__ __forceinline__ void tr_item(const float* W, int N, int k0, int n0, bf16* WT, int Kd, int drow0, int dk0, LAS float* scr, int lane) {
;     {
;         float wv[32]; const int n = n0 + (lane & 31); const float* wp = W + (size_t)(k0 + (lane >> 5)) * N + n;
; #pragma unroll
;         for (int i = 0; i < 32; ++i) wv[i] = (n < N) ? wp[(size_t)(2 * i) * N] : 0.f;
; #pragma unroll
;         for (int i = 0; i < 32; ++i) scr[(2 * i + (lane >> 5)) * 33 + (lane & 31)] = wv[i];
; __global__ void __launch_bounds__(NTHREADS, 2) mega_fwd(Args a_unused) {
;     ...
;             TR_TRY(I_W1, 256 / 32, tr_item(ap->in[11], 256, k0, n0, W1k, 1024, (k0 >= 1024 ? 256 : 0) + n0, k0 & 1023, scr, lane))
.LBB0_115:
	s_andn2_b64 vcc, exec, s[4:5]
	s_cbranch_vccnz .LBB0_117
	v_mov_b64_e32 v[16:17], s[38:39]
	global_load_dwordx2 v[16:17], v[16:17], off offset:88
	s_add_i32 s5, s19, 0x7fff5c00
	s_and_b32 s5, s5, 0x7fffffc0
	s_and_b32 s4, s7, 0xe0
	v_or_b32_e32 v0, s5, v159
	v_or_b32_e32 v27, s4, v158
	v_lshlrev_b64 v[28:29], 10, v[0:1]
	v_lshlrev_b32_e32 v0, 2, v27
	s_cmpk_gt_u32 s5, 0x3ff
	s_cselect_b32 s5, 0x100, 0
	s_and_b32 s10, s19, 0x3c0
	s_or_b32 s4, s5, s4
	s_lshl_b32 s10, s10, 1
	s_waitcnt vmcnt(0) lgkmcnt(0)
	v_lshl_add_u64 v[16:17], v[16:17], 0, v[28:29]
	v_lshl_add_u64 v[16:17], v[16:17], 0, v[0:1]
	v_add_co_u32_e32 v28, vcc, s61, v16
	v_or_b32_e32 v0, s4, v160
	s_nop 0
	v_addc_co_u32_e32 v29, vcc, 0, v17, vcc
	v_add_co_u32_e32 v30, vcc, s21, v16
	v_lshlrev_b32_e32 v0, 11, v0
	s_nop 0
	v_addc_co_u32_e32 v31, vcc, 0, v17, vcc
	v_add_co_u32_e32 v32, vcc, s62, v16
	s_nop 1
	v_addc_co_u32_e32 v33, vcc, 0, v17, vcc
	v_add_co_u32_e32 v34, vcc, s35, v16
	s_nop 1
	v_addc_co_u32_e32 v35, vcc, 0, v17, vcc
	v_add_co_u32_e32 v36, vcc, s70, v16
	s_nop 1
	v_addc_co_u32_e32 v37, vcc, 0, v17, vcc
	v_add_co_u32_e32 v38, vcc, s40, v16
	s_nop 1
	v_addc_co_u32_e32 v39, vcc, 0, v17, vcc
	v_add_co_u32_e32 v40, vcc, s63, v16
	s_nop 1
	v_addc_co_u32_e32 v41, vcc, 0, v17, vcc
	v_add_co_u32_e32 v42, vcc, s41, v16
	s_nop 1
	v_addc_co_u32_e32 v43, vcc, 0, v17, vcc
	v_add_co_u32_e32 v44, vcc, s64, v16
	s_nop 1
	v_addc_co_u32_e32 v45, vcc, 0, v17, vcc
	v_add_co_u32_e32 v46, vcc, s42, v16
	s_nop 1
	v_addc_co_u32_e32 v47, vcc, 0, v17, vcc
	v_add_co_u32_e32 v48, vcc, s71, v16
	s_nop 1
	v_addc_co_u32_e32 v49, vcc, 0, v17, vcc
	v_add_co_u32_e32 v50, vcc, s43, v16
	global_load_dword v27, v[16:17], off nt
	global_load_dword v52, v[16:17], off offset:2048 nt
	global_load_dword v53, v[28:29], off nt
	global_load_dword v54, v[28:29], off offset:2048 nt
	global_load_dword v55, v[30:31], off nt
	global_load_dword v56, v[30:31], off offset:2048 nt
	global_load_dword v57, v[32:33], off nt
	global_load_dword v58, v[32:33], off offset:2048 nt
	global_load_dword v59, v[34:35], off nt
	s_nop 0
	global_load_dword v34, v[34:35], off offset:2048 nt
	s_nop 0
	global_load_dword v35, v[36:37], off nt
	s_nop 0
	global_load_dword v36, v[36:37], off offset:2048 nt
	s_nop 0
	global_load_dword v37, v[38:39], off nt
	s_nop 0
	global_load_dword v38, v[38:39], off offset:2048 nt
	s_nop 0
	global_load_dword v39, v[40:41], off nt
	s_nop 0
	global_load_dword v40, v[40:41], off offset:2048 nt
	s_nop 0
	global_load_dword v41, v[42:43], off nt
	s_nop 0
	global_load_dword v42, v[42:43], off offset:2048 nt
	s_nop 0
	global_load_dword v43, v[44:45], off nt
	s_nop 0
	global_load_dword v44, v[44:45], off offset:2048 nt
	s_nop 0
	global_load_dword v45, v[46:47], off nt
	s_nop 0
	global_load_dword v46, v[46:47], off offset:2048 nt
	s_nop 0
	global_load_dword v47, v[48:49], off nt
	s_nop 0
	global_load_dword v48, v[48:49], off offset:2048 nt
	v_addc_co_u32_e32 v51, vcc, 0, v17, vcc
	v_add_co_u32_e32 v28, vcc, s65, v16
	s_nop 1
	v_addc_co_u32_e32 v29, vcc, 0, v17, vcc
	v_add_co_u32_e32 v30, vcc, s44, v16
	s_nop 1
	v_addc_co_u32_e32 v31, vcc, 0, v17, vcc
	v_add_co_u32_e32 v16, vcc, s66, v16
	s_nop 1
	v_addc_co_u32_e32 v17, vcc, 0, v17, vcc
	global_load_dword v49, v[50:51], off nt
	s_nop 0
	global_load_dword v50, v[50:51], off offset:2048 nt
	s_nop 0
	global_load_dword v51, v[28:29], off nt
	s_nop 0
	global_load_dword v28, v[28:29], off offset:2048 nt
	s_nop 0
	global_load_dword v29, v[30:31], off nt
	s_nop 0
	global_load_dword v30, v[30:31], off offset:2048 nt
	s_nop 0
	global_load_dword v31, v[16:17], off nt
	global_load_dword v60, v[16:17], off offset:2048 nt
	v_lshl_add_u64 v[16:17], v[8:9], 0, s[10:11]
	v_lshl_add_u64 v[32:33], v[16:17], 0, v[0:1]
	s_waitcnt vmcnt(0) lgkmcnt(0)
	ds_write2_b32 v18, v27, v52 offset1:66
	ds_write2_b32 v18, v53, v54 offset0:132 offset1:198
	ds_write2_b32 v20, v55, v56 offset0:8 offset1:74
	ds_write2_b32 v20, v57, v58 offset0:140 offset1:206
	ds_write2_b32 v21, v59, v34 offset0:16 offset1:82
	ds_write2_b32 v21, v35, v36 offset0:148 offset1:214
	ds_write2_b32 v22, v37, v38 offset0:24 offset1:90
	ds_write2_b32 v22, v39, v40 offset0:156 offset1:222
	ds_write2_b32 v23, v41, v42 offset0:32 offset1:98
	ds_write2_b32 v23, v43, v44 offset0:164 offset1:230
	ds_write2_b32 v24, v45, v46 offset0:40 offset1:106
	ds_write2_b32 v24, v47, v48 offset0:172 offset1:238
	ds_write2_b32 v25, v49, v50 offset0:48 offset1:114
	ds_write2_b32 v25, v51, v28 offset0:180 offset1:246
	ds_write2_b32 v26, v29, v30 offset0:56 offset1:122
	ds_write2_b32 v26, v31, v60 offset0:188 offset1:254
	s_waitcnt lgkmcnt(0)
; #define LAS __attribute__((address_space(3)))
; #define LDS_WAIT() asm volatile("s_waitcnt lgkmcnt(0)" ::: "memory")
; __device__ __forceinline__ unsigned pk2(float lo, float hi) { return f2bf(lo) | (f2bf(hi) << 16); }
; #define TR_TRY(CNT, NBLK, ...) if (r < (CNT)) { const int k0 = 64 * (r / (NBLK)), n0 = 32 * (r % (NBLK)); (void)k0; (void)n0; __VA_ARGS__; continue; } r -= (CNT);
; #define TR_TRY(CNT, NBLK, ...) if (r < (CNT)) { const int k0 = 64 * (r / (NBLK)), n0 = 32 * (r % (NBLK)); (void)k0; (void)n0; __VA_ARGS__; continue; } r -= (CNT);
; __device__ __forceinline__ void tr_item(const float* W, int N, int k0, int n0, bf16* WT, int Kd, int drow0, int dk0, LAS float* scr, int lane) {
;     ...
;         for (int i = 0; i < 32; ++i) scr[(2 * i + (lane >> 5)) * 33 + (lane & 31)] = wv[i];
;     }
;     LDS_WAIT();
;     const int c = lane & 7;
; #pragma unroll
;     for (int j = 0; j < 4; ++j) { const int n = (lane >> 3) + 8 * j; const LAS float* s = scr + (8 * c) * 33 + n;
;         v4u o; o.x = pk2(s[0 * 33], s[1 * 33]); o.y = pk2(s[2 * 33], s[3 * 33]); o.z = pk2(s[4 * 33], s[5 * 33]); o.w = pk2(s[6 * 33], s[7 * 33]);
;         *(v4u*)(WT + (size_t)(drow0 + n) * Kd + dk0 + 8 * c) = o; }
;     LDS_WAIT();
; __global__ void __launch_bounds__(NTHREADS, 2) mega_fwd(Args a_unused) {
;     ...
;             TR_TRY(I_W1, 256 / 32, tr_item(ap->in[11], 256, k0, n0, W1k, 1024, (k0 >= 1024 ? 256 : 0) + n0, k0 & 1023, scr, lane))
	ds_read_b32 v0, v19
	ds_read_b32 v27, v19 offset:132
	ds_read_b32 v28, v19 offset:264
	ds_read_b32 v29, v19 offset:396
	ds_read_b32 v30, v19 offset:528
	ds_read_b32 v31, v19 offset:660
	ds_read_b32 v34, v19 offset:792
	ds_read_b32 v35, v19 offset:924
	s_waitcnt lgkmcnt(7)
	v_bfe_u32 v36, v0, 16, 1
	s_waitcnt lgkmcnt(5)
	v_bfe_u32 v38, v28, 16, 1
	s_waitcnt lgkmcnt(3)
	v_bfe_u32 v40, v30, 16, 1
	s_waitcnt lgkmcnt(1)
	v_bfe_u32 v42, v34, 16, 1
	v_bfe_u32 v37, v27, 16, 1
	v_bfe_u32 v39, v29, 16, 1
	v_bfe_u32 v41, v31, 16, 1
	s_waitcnt lgkmcnt(0)
	v_bfe_u32 v43, v35, 16, 1
	v_add3_u32 v0, v0, v36, s59
	v_add3_u32 v28, v28, v38, s59
	v_add3_u32 v30, v30, v40, s59
	v_add3_u32 v34, v34, v42, s59
	v_add3_u32 v27, v27, v37, s59
	v_add3_u32 v29, v29, v39, s59
	v_add3_u32 v31, v31, v41, s59
	v_add3_u32 v35, v35, v43, s59
	v_lshrrev_b32_e32 v0, 16, v0
	v_lshrrev_b32_e32 v36, 16, v28
	v_lshrrev_b32_e32 v30, 16, v30
	v_lshrrev_b32_e32 v34, 16, v34
	v_and_or_b32 v28, v27, s60, v0
	v_and_or_b32 v29, v29, s60, v36
	v_and_or_b32 v30, v31, s60, v30
	v_and_or_b32 v31, v35, s60, v34
	global_store_dwordx4 v[32:33], v[28:31], off sc0 sc1
	ds_read_b32 v0, v19 offset:32
	ds_read_b32 v27, v19 offset:164
	ds_read_b32 v28, v19 offset:296
	ds_read_b32 v29, v19 offset:428
	ds_read_b32 v30, v19 offset:560
	ds_read_b32 v31, v19 offset:692
	ds_read_b32 v32, v19 offset:824
	ds_read_b32 v33, v19 offset:956
	s_waitcnt lgkmcnt(0)
	v_bfe_u32 v34, v0, 16, 1
	v_bfe_u32 v35, v27, 16, 1
	v_bfe_u32 v36, v28, 16, 1
	v_add3_u32 v0, v0, v34, s59
	v_bfe_u32 v38, v30, 16, 1
	v_add3_u32 v27, v27, v35, s59
	v_add3_u32 v28, v28, v36, s59
	v_lshrrev_b32_e32 v0, 16, v0
	v_add3_u32 v30, v30, v38, s59
	v_lshrrev_b32_e32 v34, 16, v28
	v_and_or_b32 v28, v27, s60, v0
	v_bfe_u32 v0, v31, 16, 1
	v_lshrrev_b32_e32 v30, 16, v30
	v_add3_u32 v0, v31, v0, s59
	v_and_or_b32 v30, v0, s60, v30
	v_bfe_u32 v0, v32, 16, 1
	v_add3_u32 v0, v32, v0, s59
	v_bfe_u32 v27, v33, 16, 1
	v_lshrrev_b32_e32 v0, 16, v0
	v_add3_u32 v27, v33, v27, s59
	v_bfe_u32 v37, v29, 16, 1
	v_and_or_b32 v31, v27, s60, v0
	v_or_b32_e32 v0, s4, v161
	v_add3_u32 v29, v29, v37, s59
	v_lshlrev_b32_e32 v0, 11, v0
	v_and_or_b32 v29, v29, s60, v34
	v_lshl_add_u64 v[32:33], v[16:17], 0, v[0:1]
	global_store_dwordx4 v[32:33], v[28:31], off sc0 sc1
	ds_read_b32 v0, v19 offset:64
	ds_read_b32 v27, v19 offset:196
	ds_read_b32 v29, v19 offset:328
	ds_read_b32 v30, v19 offset:460
	ds_read_b32 v31, v19 offset:592
	ds_read_b32 v32, v19 offset:724
	ds_read_b32 v33, v19 offset:856
	ds_read_b32 v34, v19 offset:988
	s_waitcnt lgkmcnt(0)
	v_bfe_u32 v28, v0, 16, 1
	v_add3_u32 v0, v0, v28, s59
	v_bfe_u32 v28, v27, 16, 1
	v_lshrrev_b32_e32 v0, 16, v0
	v_add3_u32 v27, v27, v28, s59
	v_and_or_b32 v28, v27, s60, v0
	v_bfe_u32 v0, v29, 16, 1
	v_add3_u32 v0, v29, v0, s59
	v_bfe_u32 v27, v30, 16, 1
	v_lshrrev_b32_e32 v0, 16, v0
	v_add3_u32 v27, v30, v27, s59
	v_and_or_b32 v29, v27, s60, v0
	v_bfe_u32 v0, v31, 16, 1
	v_add3_u32 v0, v31, v0, s59
	v_bfe_u32 v27, v32, 16, 1
	v_lshrrev_b32_e32 v0, 16, v0
	v_add3_u32 v27, v32, v27, s59
	v_and_or_b32 v30, v27, s60, v0
	v_bfe_u32 v0, v33, 16, 1
	v_add3_u32 v0, v33, v0, s59
	v_bfe_u32 v27, v34, 16, 1
	v_lshrrev_b32_e32 v0, 16, v0
	v_add3_u32 v27, v34, v27, s59
	v_and_or_b32 v31, v27, s60, v0
	v_or_b32_e32 v0, s4, v162
	v_lshlrev_b32_e32 v0, 11, v0
	v_lshl_add_u64 v[32:33], v[16:17], 0, v[0:1]
	global_store_dwordx4 v[32:33], v[28:31], off sc0 sc1
	ds_read_b32 v0, v19 offset:96
	ds_read_b32 v27, v19 offset:228
	ds_read_b32 v29, v19 offset:360
	ds_read_b32 v30, v19 offset:492
	ds_read_b32 v31, v19 offset:624
	ds_read_b32 v32, v19 offset:756
	ds_read_b32 v33, v19 offset:888
	ds_read_b32 v34, v19 offset:1020
	s_waitcnt lgkmcnt(0)
	v_bfe_u32 v28, v0, 16, 1
	v_add3_u32 v0, v0, v28, s59
	v_bfe_u32 v28, v27, 16, 1
	v_lshrrev_b32_e32 v0, 16, v0
	v_add3_u32 v27, v27, v28, s59
	v_and_or_b32 v28, v27, s60, v0
	v_bfe_u32 v0, v29, 16, 1
	v_add3_u32 v0, v29, v0, s59
	v_bfe_u32 v27, v30, 16, 1
	v_lshrrev_b32_e32 v0, 16, v0
	v_add3_u32 v27, v30, v27, s59
	v_and_or_b32 v29, v27, s60, v0
	v_bfe_u32 v0, v31, 16, 1
	v_add3_u32 v0, v31, v0, s59
	v_bfe_u32 v27, v32, 16, 1
	v_lshrrev_b32_e32 v0, 16, v0
	v_add3_u32 v27, v32, v27, s59
	v_and_or_b32 v30, v27, s60, v0
	v_bfe_u32 v0, v33, 16, 1
	v_add3_u32 v0, v33, v0, s59
	v_bfe_u32 v27, v34, 16, 1
	v_lshrrev_b32_e32 v0, 16, v0
	v_add3_u32 v27, v34, v27, s59
	v_and_or_b32 v31, v27, s60, v0
	v_or_b32_e32 v0, s4, v163
	v_lshlrev_b32_e32 v0, 11, v0
	v_lshl_add_u64 v[16:17], v[16:17], 0, v[0:1]
	global_store_dwordx4 v[16:17], v[28:31], off sc0 sc1
	s_waitcnt lgkmcnt(0)

; #define LAS __attribute__((address_space(3)))
; #define TR_TRY(CNT, NBLK, ...) if (r < (CNT)) { const int k0 = 64 * (r / (NBLK)), n0 = 32 * (r % (NBLK)); (void)k0; (void)n0; __VA_ARGS__; continue; } r -= (CNT);
; #define TR_TRY(CNT, NBLK, ...) if (r < (CNT)) { const int k0 = 64 * (r / (NBLK)), n0 = 32 * (r % (NBLK)); (void)k0; (void)n0; __VA_ARGS__; continue; } r -= (CNT);
; __device__ __forceinline__ void tr_item(const float* W, int N, int k0, int n0, bf16* WT, int Kd, int drow0, int dk0, LAS float* scr, int lane) {
;     {
;         float wv[32]; const int n = n0 + (lane & 31); const float* wp = W + (size_t)(k0 + (lane >> 5)) * N + n;
; #pragma unroll
;         for (int i = 0; i < 32; ++i) wv[i] = (n < N) ? wp[(size_t)(2 * i) * N] : 0.f;
; __global__ void __launch_bounds__(NTHREADS, 2) mega_fwd(Args a_unused) {
;     ...
;             TR_TRY(I_IN, DINP / 32, tr_item(ap->in[9], DIN, k0, n0, Win, D, n0, k0, scr, lane))
.LBB0_118:
	s_andn2_b64 vcc, exec, s[4:5]
	s_cbranch_vccnz .LBB0_184
	v_mov_b64_e32 v[16:17], s[38:39]
	global_load_dwordx2 v[16:17], v[16:17], off offset:72
	s_and_b32 s4, s97, 0x1fc0
	s_and_b32 s69, s7, 0x7e0
	s_add_i32 s10, s4, 0xffffef80
	v_or_b32_e32 v28, s69, v158
	v_or_b32_e32 v29, s10, v159
	v_lshlrev_b32_e32 v0, 2, v28
	v_mov_b32_e32 v27, 0
	v_cmp_gt_u32_e64 s[4:5], s73, v28
	s_waitcnt vmcnt(0) lgkmcnt(0)
	v_mad_u64_u32 v[16:17], s[12:13], v29, s72, v[16:17]
	v_lshl_add_u64 v[16:17], v[16:17], 0, v[0:1]
	v_mov_b32_e32 v0, 0
	s_and_saveexec_b64 s[12:13], s[4:5]
	s_cbranch_execz .LBB0_121
	global_load_dword v0, v[16:17], off nt
.LBB0_121:
	s_or_b64 exec, exec, s[12:13]
	s_and_saveexec_b64 s[12:13], s[4:5]
	s_cbranch_execz .LBB0_123
	v_add_co_u32_e32 v28, vcc, 0x3000, v16
	s_nop 1
	v_addc_co_u32_e32 v29, vcc, 0, v17, vcc
	global_load_dword v27, v[28:29], off offset:3520 nt
.LBB0_123:
	s_or_b64 exec, exec, s[12:13]
	v_mov_b32_e32 v28, 0
	v_mov_b32_e32 v29, 0
	s_and_saveexec_b64 s[12:13], s[4:5]
	s_cbranch_execz .LBB0_125
	v_add_co_u32_e32 v30, vcc, 0x7000, v16
	s_nop 1
	v_addc_co_u32_e32 v31, vcc, 0, v17, vcc
	global_load_dword v29, v[30:31], off offset:2944 nt
.LBB0_125:
	s_or_b64 exec, exec, s[12:13]
	s_and_saveexec_b64 s[12:13], s[4:5]
	s_cbranch_execz .LBB0_127
	v_add_co_u32_e32 v30, vcc, 0xb000, v16
	s_nop 1
	v_addc_co_u32_e32 v31, vcc, 0, v17, vcc
	global_load_dword v28, v[30:31], off offset:2368 nt
.LBB0_127:
	s_or_b64 exec, exec, s[12:13]
	v_mov_b32_e32 v30, 0
	v_mov_b32_e32 v31, 0
	s_and_saveexec_b64 s[12:13], s[4:5]
	s_cbranch_execz .LBB0_129
	v_add_co_u32_e32 v32, vcc, 0xf000, v16
	s_nop 1
	v_addc_co_u32_e32 v33, vcc, 0, v17, vcc
	global_load_dword v31, v[32:33], off offset:1792 nt
.LBB0_129:
	s_or_b64 exec, exec, s[12:13]
	s_and_saveexec_b64 s[12:13], s[4:5]
	s_cbranch_execz .LBB0_131
	v_add_co_u32_e32 v32, vcc, 0x13000, v16
	s_nop 1
	v_addc_co_u32_e32 v33, vcc, 0, v17, vcc
	global_load_dword v30, v[32:33], off offset:1216 nt
.LBB0_131:
	s_or_b64 exec, exec, s[12:13]
	v_mov_b32_e32 v32, 0
	v_mov_b32_e32 v33, 0
	s_and_saveexec_b64 s[12:13], s[4:5]
	s_cbranch_execz .LBB0_133
	v_add_co_u32_e32 v34, vcc, 0x17000, v16
	s_nop 1
	v_addc_co_u32_e32 v35, vcc, 0, v17, vcc
	global_load_dword v33, v[34:35], off offset:640 nt
.LBB0_133:
	s_or_b64 exec, exec, s[12:13]
	s_and_saveexec_b64 s[12:13], s[4:5]
	s_cbranch_execz .LBB0_135
	v_add_co_u32_e32 v34, vcc, 0x1b000, v16
	s_nop 1
	v_addc_co_u32_e32 v35, vcc, 0, v17, vcc
	global_load_dword v32, v[34:35], off offset:64 nt
.LBB0_135:
	s_or_b64 exec, exec, s[12:13]
	v_mov_b32_e32 v34, 0
	v_mov_b32_e32 v35, 0
	s_and_saveexec_b64 s[12:13], s[4:5]
	s_cbranch_execz .LBB0_137
	v_add_co_u32_e32 v36, vcc, 0x1e000, v16
	s_nop 1
	v_addc_co_u32_e32 v37, vcc, 0, v17, vcc
	global_load_dword v35, v[36:37], off offset:3584 nt
.LBB0_137:
	s_or_b64 exec, exec, s[12:13]
	s_and_saveexec_b64 s[12:13], s[4:5]
	s_cbranch_execz .LBB0_139
	v_add_co_u32_e32 v36, vcc, 0x22000, v16
	s_nop 1
	v_addc_co_u32_e32 v37, vcc, 0, v17, vcc
	global_load_dword v34, v[36:37], off offset:3008 nt
.LBB0_139:
	s_or_b64 exec, exec, s[12:13]
	v_mov_b32_e32 v36, 0
	v_mov_b32_e32 v37, 0
	s_and_saveexec_b64 s[12:13], s[4:5]
	s_cbranch_execz .LBB0_141
	v_add_co_u32_e32 v38, vcc, 0x26000, v16
	s_nop 1
	v_addc_co_u32_e32 v39, vcc, 0, v17, vcc
	global_load_dword v37, v[38:39], off offset:2432 nt
.LBB0_141:
	s_or_b64 exec, exec, s[12:13]
	s_and_saveexec_b64 s[12:13], s[4:5]
	s_cbranch_execz .LBB0_143
	v_add_co_u32_e32 v38, vcc, 0x2a000, v16
	s_nop 1
	v_addc_co_u32_e32 v39, vcc, 0, v17, vcc
	global_load_dword v36, v[38:39], off offset:1856 nt
.LBB0_143:
	s_or_b64 exec, exec, s[12:13]
	v_mov_b32_e32 v38, 0
	v_mov_b32_e32 v39, 0
	s_and_saveexec_b64 s[12:13], s[4:5]
	s_cbranch_execz .LBB0_145
	v_add_co_u32_e32 v40, vcc, 0x2e000, v16
	s_nop 1
	v_addc_co_u32_e32 v41, vcc, 0, v17, vcc
	global_load_dword v39, v[40:41], off offset:1280 nt
.LBB0_145:
	s_or_b64 exec, exec, s[12:13]
	s_and_saveexec_b64 s[12:13], s[4:5]
	s_cbranch_execz .LBB0_147
	v_add_co_u32_e32 v40, vcc, 0x32000, v16
	s_nop 1
	v_addc_co_u32_e32 v41, vcc, 0, v17, vcc
	global_load_dword v38, v[40:41], off offset:704 nt
.LBB0_147:
	s_or_b64 exec, exec, s[12:13]
	v_mov_b32_e32 v40, 0
	v_mov_b32_e32 v41, 0
	s_and_saveexec_b64 s[12:13], s[4:5]
	s_cbranch_execz .LBB0_149
	v_add_co_u32_e32 v42, vcc, 0x36000, v16
	s_nop 1
	v_addc_co_u32_e32 v43, vcc, 0, v17, vcc
	global_load_dword v41, v[42:43], off offset:128 nt
; __device__ __forceinline__ void tr_item(const float* W, int N, int k0, int n0, bf16* WT, int Kd, int drow0, int dk0, LAS float* scr, int lane) {
;     ...
;         float wv[32]; const int n = n0 + (lane & 31); const float* wp = W + (size_t)(k0 + (lane >> 5)) * N + n;
; #pragma unroll
;         for (int i = 0; i < 32; ++i) wv[i] = (n < N) ? wp[(size_t)(2 * i) * N] : 0.f;
.LBB0_149:
	s_or_b64 exec, exec, s[12:13]
	s_and_saveexec_b64 s[12:13], s[4:5]
	s_cbranch_execz .LBB0_151
	v_add_co_u32_e32 v42, vcc, 0x39000, v16
	s_nop 1
	v_addc_co_u32_e32 v43, vcc, 0, v17, vcc
	global_load_dword v40, v[42:43], off offset:3648 nt
.LBB0_151:
	s_or_b64 exec, exec, s[12:13]
	v_mov_b32_e32 v42, 0
	v_mov_b32_e32 v43, 0
	s_and_saveexec_b64 s[12:13], s[4:5]
	s_cbranch_execz .LBB0_153
	v_add_co_u32_e32 v44, vcc, 0x3d000, v16
	s_nop 1
	v_addc_co_u32_e32 v45, vcc, 0, v17, vcc
	global_load_dword v43, v[44:45], off offset:3072 nt
.LBB0_153:
	s_or_b64 exec, exec, s[12:13]
	s_and_saveexec_b64 s[12:13], s[4:5]
	s_cbranch_execz .LBB0_155
	v_add_co_u32_e32 v44, vcc, 0x41000, v16
	s_nop 1
	v_addc_co_u32_e32 v45, vcc, 0, v17, vcc
	global_load_dword v42, v[44:45], off offset:2496 nt
.LBB0_155:
	s_or_b64 exec, exec, s[12:13]
	v_mov_b32_e32 v44, 0
	v_mov_b32_e32 v45, 0
	s_and_saveexec_b64 s[12:13], s[4:5]
	s_cbranch_execz .LBB0_157
	v_add_co_u32_e32 v46, vcc, 0x45000, v16
	s_nop 1
	v_addc_co_u32_e32 v47, vcc, 0, v17, vcc
	global_load_dword v45, v[46:47], off offset:1920 nt
.LBB0_157:
	s_or_b64 exec, exec, s[12:13]
	s_and_saveexec_b64 s[12:13], s[4:5]
	s_cbranch_execz .LBB0_159
	v_add_co_u32_e32 v46, vcc, 0x49000, v16
	s_nop 1
	v_addc_co_u32_e32 v47, vcc, 0, v17, vcc
	global_load_dword v44, v[46:47], off offset:1344 nt
.LBB0_159:
	s_or_b64 exec, exec, s[12:13]
	v_mov_b32_e32 v46, 0
	v_mov_b32_e32 v47, 0
	s_and_saveexec_b64 s[12:13], s[4:5]
	s_cbranch_execz .LBB0_161
	v_add_co_u32_e32 v48, vcc, 0x4d000, v16
	s_nop 1
	v_addc_co_u32_e32 v49, vcc, 0, v17, vcc
	global_load_dword v47, v[48:49], off offset:768 nt
.LBB0_161:
	s_or_b64 exec, exec, s[12:13]
	s_and_saveexec_b64 s[12:13], s[4:5]
	s_cbranch_execz .LBB0_163
	v_add_co_u32_e32 v48, vcc, 0x51000, v16
	s_nop 1
	v_addc_co_u32_e32 v49, vcc, 0, v17, vcc
	global_load_dword v46, v[48:49], off offset:192 nt
.LBB0_163:
	s_or_b64 exec, exec, s[12:13]
	v_mov_b32_e32 v48, 0
	v_mov_b32_e32 v49, 0
	s_and_saveexec_b64 s[12:13], s[4:5]
	s_cbranch_execz .LBB0_165
	v_add_co_u32_e32 v50, vcc, 0x54000, v16
	s_nop 1
	v_addc_co_u32_e32 v51, vcc, 0, v17, vcc
	global_load_dword v49, v[50:51], off offset:3712 nt
.LBB0_165:
	s_or_b64 exec, exec, s[12:13]
	s_and_saveexec_b64 s[12:13], s[4:5]
	s_cbranch_execz .LBB0_167
	v_add_co_u32_e32 v50, vcc, 0x58000, v16
	s_nop 1
	v_addc_co_u32_e32 v51, vcc, 0, v17, vcc
	global_load_dword v48, v[50:51], off offset:3136 nt
.LBB0_167:
	s_or_b64 exec, exec, s[12:13]
	v_mov_b32_e32 v50, 0
	v_mov_b32_e32 v51, 0
	s_and_saveexec_b64 s[12:13], s[4:5]
	s_cbranch_execz .LBB0_169
	v_add_co_u32_e32 v52, vcc, 0x5c000, v16
	s_nop 1
	v_addc_co_u32_e32 v53, vcc, 0, v17, vcc
	global_load_dword v51, v[52:53], off offset:2560 nt
.LBB0_169:
	s_or_b64 exec, exec, s[12:13]
	s_and_saveexec_b64 s[12:13], s[4:5]
	s_cbranch_execz .LBB0_171
	v_add_co_u32_e32 v52, vcc, 0x60000, v16
	s_nop 1
	v_addc_co_u32_e32 v53, vcc, 0, v17, vcc
	global_load_dword v50, v[52:53], off offset:1984 nt
.LBB0_171:
	s_or_b64 exec, exec, s[12:13]
	v_mov_b32_e32 v52, 0
	v_mov_b32_e32 v53, 0
	s_and_saveexec_b64 s[12:13], s[4:5]
	s_cbranch_execz .LBB0_173
	v_add_co_u32_e32 v54, vcc, 0x64000, v16
	s_nop 1
	v_addc_co_u32_e32 v55, vcc, 0, v17, vcc
	global_load_dword v53, v[54:55], off offset:1408 nt
.LBB0_173:
	s_or_b64 exec, exec, s[12:13]
	s_and_saveexec_b64 s[12:13], s[4:5]
	s_cbranch_execz .LBB0_175
	v_add_co_u32_e32 v54, vcc, 0x68000, v16
	s_nop 1
	v_addc_co_u32_e32 v55, vcc, 0, v17, vcc
	global_load_dword v52, v[54:55], off offset:832 nt
.LBB0_175:
	s_or_b64 exec, exec, s[12:13]
	v_mov_b32_e32 v54, 0
	v_mov_b32_e32 v55, 0
	s_and_saveexec_b64 s[12:13], s[4:5]
	s_cbranch_execz .LBB0_177
	v_add_co_u32_e32 v56, vcc, 0x6c000, v16
	s_nop 1
	v_addc_co_u32_e32 v57, vcc, 0, v17, vcc
	global_load_dword v55, v[56:57], off offset:256 nt
.LBB0_177:
	s_or_b64 exec, exec, s[12:13]
	s_and_saveexec_b64 s[12:13], s[4:5]
	s_cbranch_execz .LBB0_179
	v_add_co_u32_e32 v56, vcc, 0x6f000, v16
	s_nop 1
	v_addc_co_u32_e32 v57, vcc, 0, v17, vcc
	global_load_dword v54, v[56:57], off offset:3776 nt
.LBB0_179:
	s_or_b64 exec, exec, s[12:13]
	v_mov_b32_e32 v56, 0
	v_mov_b32_e32 v57, 0
	s_and_saveexec_b64 s[12:13], s[4:5]
	s_cbranch_execz .LBB0_181
	v_add_co_u32_e32 v58, vcc, 0x73000, v16
	s_nop 1
	v_addc_co_u32_e32 v59, vcc, 0, v17, vcc
	global_load_dword v57, v[58:59], off offset:3200 nt
.LBB0_181:
	s_or_b64 exec, exec, s[12:13]
	s_and_saveexec_b64 s[12:13], s[4:5]
	s_cbranch_execz .LBB0_183
	v_add_co_u32_e32 v16, vcc, 0x77000, v16
	s_nop 1
	v_addc_co_u32_e32 v17, vcc, 0, v17, vcc
	global_load_dword v56, v[16:17], off offset:2624 nt

; #define TR_TRY(CNT, NBLK, ...) if (r < (CNT)) { const int k0 = 64 * (r / (NBLK)), n0 = 32 * (r % (NBLK)); (void)k0; (void)n0; __VA_ARGS__; continue; } r -= (CNT);
; #define TR_TRY(CNT, NBLK, ...) if (r < (CNT)) { const int k0 = 64 * (r / (NBLK)), n0 = 32 * (r % (NBLK)); (void)k0; (void)n0; __VA_ARGS__; continue; } r -= (CNT);
; __device__ __forceinline__ void tr_item(const float* W, int N, int k0, int n0, bf16* WT, int Kd, int drow0, int dk0, LAS float* scr, int lane) {
;     ...
;         float wv[32]; const int n = n0 + (lane & 31); const float* wp = W + (size_t)(k0 + (lane >> 5)) * N + n;
; #pragma unroll
;         for (int i = 0; i < 32; ++i) wv[i] = (n < N) ? wp[(size_t)(2 * i) * N] : 0.f;
; #pragma unroll
;         for (int i = 0; i < 32; ++i) scr[(2 * i + (lane >> 5)) * 33 + (lane & 31)] = wv[i];
; __global__ void __launch_bounds__(NTHREADS, 2) mega_fwd(Args a_unused) {
;     ...
;             TR_TRY(I_WD, D / 32, tr_item(ap->in[8], D, k0, n0, Wd1, FF, n0, k0, scr, lane))
.LBB0_185:
	s_andn2_b64 vcc, exec, s[4:5]
	s_cbranch_vccnz .LBB0_187
	v_mov_b64_e32 v[16:17], s[38:39]
	global_load_dwordx2 v[16:17], v[16:17], off offset:64
	s_add_i32 s5, s17, 0x80001820
	s_and_b32 s5, s5, 0x7fffffc0
	s_and_b32 s4, s7, 0x3e0
	v_or_b32_e32 v0, s5, v159
	v_or_b32_e32 v27, s4, v158
	v_lshlrev_b64 v[28:29], 12, v[0:1]
	v_lshlrev_b32_e32 v0, 2, v27
	s_lshl_b32 s10, s5, 1
	s_waitcnt vmcnt(0) lgkmcnt(0)
	v_lshl_add_u64 v[16:17], v[16:17], 0, v[28:29]
	v_lshl_add_u64 v[16:17], v[16:17], 0, v[0:1]
	v_add_co_u32_e32 v28, vcc, 0x2000, v16
	s_nop 1
	v_addc_co_u32_e32 v29, vcc, 0, v17, vcc
	v_add_co_u32_e32 v30, vcc, 0x4000, v16
	s_nop 1
	v_addc_co_u32_e32 v31, vcc, 0, v17, vcc
	v_add_co_u32_e32 v32, vcc, 0x6000, v16
	s_nop 1
	v_addc_co_u32_e32 v33, vcc, 0, v17, vcc
	v_add_co_u32_e32 v34, vcc, 0x8000, v16
	s_nop 1
	v_addc_co_u32_e32 v35, vcc, 0, v17, vcc
	v_add_co_u32_e32 v36, vcc, 0xa000, v16
	s_nop 1
	v_addc_co_u32_e32 v37, vcc, 0, v17, vcc
	v_add_co_u32_e32 v38, vcc, 0xc000, v16
	s_nop 1
	v_addc_co_u32_e32 v39, vcc, 0, v17, vcc
	v_add_co_u32_e32 v40, vcc, 0xe000, v16
	s_nop 1
	v_addc_co_u32_e32 v41, vcc, 0, v17, vcc
	v_add_co_u32_e32 v42, vcc, 0x10000, v16
	global_load_dword v0, v[16:17], off nt
	global_load_dword v27, v[28:29], off nt
	global_load_dword v44, v[30:31], off nt
	global_load_dword v45, v[32:33], off nt
	global_load_dword v46, v[34:35], off nt
	global_load_dword v47, v[36:37], off nt
	global_load_dword v48, v[38:39], off nt
	global_load_dword v49, v[40:41], off nt
	v_addc_co_u32_e32 v43, vcc, 0, v17, vcc
	v_add_co_u32_e32 v28, vcc, 0x12000, v16
	s_nop 1
	v_addc_co_u32_e32 v29, vcc, 0, v17, vcc
	v_add_co_u32_e32 v30, vcc, 0x14000, v16
	s_nop 1
	v_addc_co_u32_e32 v31, vcc, 0, v17, vcc
	v_add_co_u32_e32 v32, vcc, 0x16000, v16
	s_nop 1
	v_addc_co_u32_e32 v33, vcc, 0, v17, vcc
	v_add_co_u32_e32 v34, vcc, 0x18000, v16
	s_nop 1
	v_addc_co_u32_e32 v35, vcc, 0, v17, vcc
	v_add_co_u32_e32 v36, vcc, 0x1a000, v16
	s_nop 1
	v_addc_co_u32_e32 v37, vcc, 0, v17, vcc
	v_add_co_u32_e32 v38, vcc, 0x1c000, v16
	s_nop 1
	v_addc_co_u32_e32 v39, vcc, 0, v17, vcc
	v_add_co_u32_e32 v40, vcc, 0x1e000, v16
	s_nop 1
	v_addc_co_u32_e32 v41, vcc, 0, v17, vcc
	global_load_dword v50, v[42:43], off nt
	global_load_dword v51, v[28:29], off nt
	global_load_dword v52, v[30:31], off nt
	global_load_dword v53, v[32:33], off nt
	global_load_dword v54, v[34:35], off nt
	global_load_dword v55, v[36:37], off nt
	global_load_dword v56, v[38:39], off nt
	global_load_dword v57, v[40:41], off nt
	v_add_co_u32_e32 v28, vcc, 0x20000, v16
	s_nop 1
	v_addc_co_u32_e32 v29, vcc, 0, v17, vcc
	v_add_co_u32_e32 v30, vcc, 0x22000, v16
	s_nop 1
	v_addc_co_u32_e32 v31, vcc, 0, v17, vcc
	v_add_co_u32_e32 v32, vcc, 0x24000, v16
	s_nop 1
	v_addc_co_u32_e32 v33, vcc, 0, v17, vcc
	v_add_co_u32_e32 v34, vcc, 0x26000, v16
	s_nop 1
	v_addc_co_u32_e32 v35, vcc, 0, v17, vcc
	v_add_co_u32_e32 v36, vcc, 0x28000, v16
	s_nop 1
	v_addc_co_u32_e32 v37, vcc, 0, v17, vcc
	v_add_co_u32_e32 v38, vcc, 0x2a000, v16
	s_nop 1
	v_addc_co_u32_e32 v39, vcc, 0, v17, vcc
	v_add_co_u32_e32 v40, vcc, 0x2c000, v16
	s_nop 1
	v_addc_co_u32_e32 v41, vcc, 0, v17, vcc
	v_add_co_u32_e32 v42, vcc, 0x2e000, v16
	s_nop 1
	v_addc_co_u32_e32 v43, vcc, 0, v17, vcc
	global_load_dword v58, v[28:29], off nt
	global_load_dword v59, v[30:31], off nt
	global_load_dword v60, v[32:33], off nt
	global_load_dword v61, v[34:35], off nt
	global_load_dword v62, v[36:37], off nt
	global_load_dword v63, v[38:39], off nt
	global_load_dword v64, v[40:41], off nt
	s_nop 0
	global_load_dword v42, v[42:43], off nt
	v_add_co_u32_e32 v28, vcc, 0x30000, v16
	s_nop 1
	v_addc_co_u32_e32 v29, vcc, 0, v17, vcc
	v_add_co_u32_e32 v30, vcc, 0x32000, v16
	s_nop 1
	v_addc_co_u32_e32 v31, vcc, 0, v17, vcc
	v_add_co_u32_e32 v32, vcc, 0x34000, v16
	s_nop 1
	v_addc_co_u32_e32 v33, vcc, 0, v17, vcc
	v_add_co_u32_e32 v34, vcc, 0x36000, v16
	s_nop 1
	v_addc_co_u32_e32 v35, vcc, 0, v17, vcc
	v_add_co_u32_e32 v36, vcc, 0x38000, v16
	s_nop 1
	v_addc_co_u32_e32 v37, vcc, 0, v17, vcc
	v_add_co_u32_e32 v38, vcc, 0x3a000, v16
	s_nop 1
	v_addc_co_u32_e32 v39, vcc, 0, v17, vcc
	v_add_co_u32_e32 v40, vcc, 0x3c000, v16
	s_nop 1
	v_addc_co_u32_e32 v41, vcc, 0, v17, vcc
	v_add_co_u32_e32 v16, vcc, 0x3e000, v16
	s_nop 1
	v_addc_co_u32_e32 v17, vcc, 0, v17, vcc
	global_load_dword v28, v[28:29], off nt
	s_nop 0
	global_load_dword v29, v[30:31], off nt
	s_nop 0
	global_load_dword v30, v[32:33], off nt
	global_load_dword v31, v[34:35], off nt
	s_nop 0
	global_load_dword v32, v[36:37], off nt
	global_load_dword v33, v[38:39], off nt
	global_load_dword v34, v[40:41], off nt
	s_nop 0
	global_load_dword v16, v[16:17], off nt
	s_waitcnt vmcnt(0) lgkmcnt(0)
	ds_write2_b32 v18, v0, v27 offset1:66
	ds_write2_b32 v18, v44, v45 offset0:132 offset1:198
	ds_write2_b32 v20, v46, v47 offset0:8 offset1:74
	ds_write2_b32 v20, v48, v49 offset0:140 offset1:206
	ds_write2_b32 v21, v50, v51 offset0:16 offset1:82
	ds_write2_b32 v21, v52, v53 offset0:148 offset1:214
	ds_write2_b32 v22, v54, v55 offset0:24 offset1:90
	ds_write2_b32 v22, v56, v57 offset0:156 offset1:222
	ds_write2_b32 v23, v58, v59 offset0:32 offset1:98
	ds_write2_b32 v23, v60, v61 offset0:164 offset1:230
	ds_write2_b32 v24, v62, v63 offset0:40 offset1:106
	ds_write2_b32 v24, v64, v42 offset0:172 offset1:238
	ds_write2_b32 v25, v28, v29 offset0:48 offset1:114
	ds_write2_b32 v25, v30, v31 offset0:180 offset1:246
	ds_write2_b32 v26, v32, v33 offset0:56 offset1:122
	ds_write2_b32 v26, v34, v16 offset0:188 offset1:254
	s_waitcnt lgkmcnt(0)
; #define LAS __attribute__((address_space(3)))
; #define LDS_WAIT() asm volatile("s_waitcnt lgkmcnt(0)" ::: "memory")
; __device__ __forceinline__ unsigned pk2(float lo, float hi) { return f2bf(lo) | (f2bf(hi) << 16); }
; __device__ __forceinline__ void tr_item(const float* W, int N, int k0, int n0, bf16* WT, int Kd, int drow0, int dk0, LAS float* scr, int lane) {
;     ...
;     LDS_WAIT();
;     const int c = lane & 7;
; #pragma unroll
;     for (int j = 0; j < 4; ++j) { const int n = (lane >> 3) + 8 * j; const LAS float* s = scr + (8 * c) * 33 + n;
;         v4u o; o.x = pk2(s[0 * 33], s[1 * 33]); o.y = pk2(s[2 * 33], s[3 * 33]); o.z = pk2(s[4 * 33], s[5 * 33]); o.w = pk2(s[6 * 33], s[7 * 33]);
;         *(v4u*)(WT + (size_t)(drow0 + n) * Kd + dk0 + 8 * c) = o; }
;     LDS_WAIT();
	ds_read_b32 v0, v19
	ds_read_b32 v27, v19 offset:132
	ds_read_b32 v29, v19 offset:264
	ds_read_b32 v30, v19 offset:396
	ds_read_b32 v31, v19 offset:528
	ds_read_b32 v32, v19 offset:660
	ds_read_b32 v33, v19 offset:792
	ds_read_b32 v34, v19 offset:924
	s_waitcnt lgkmcnt(7)
	v_bfe_u32 v28, v0, 16, 1
	v_add3_u32 v0, v0, v28, s59
	s_waitcnt lgkmcnt(6)
	v_bfe_u32 v28, v27, 16, 1
	v_lshrrev_b32_e32 v0, 16, v0
	v_add3_u32 v27, v27, v28, s59
	v_and_or_b32 v28, v27, s60, v0
	s_waitcnt lgkmcnt(5)
	v_bfe_u32 v0, v29, 16, 1
	v_add3_u32 v0, v29, v0, s59
	s_waitcnt lgkmcnt(4)
	v_bfe_u32 v27, v30, 16, 1
	v_lshrrev_b32_e32 v0, 16, v0
	v_add3_u32 v27, v30, v27, s59
	v_and_or_b32 v29, v27, s60, v0
	s_waitcnt lgkmcnt(3)
	v_bfe_u32 v0, v31, 16, 1
	v_add3_u32 v0, v31, v0, s59
	s_waitcnt lgkmcnt(2)
	v_bfe_u32 v27, v32, 16, 1
	v_lshrrev_b32_e32 v0, 16, v0
	v_add3_u32 v27, v32, v27, s59
	v_and_or_b32 v30, v27, s60, v0
	s_waitcnt lgkmcnt(1)
	v_bfe_u32 v0, v33, 16, 1
	v_add3_u32 v0, v33, v0, s59
	s_waitcnt lgkmcnt(0)
	v_bfe_u32 v27, v34, 16, 1
	v_lshrrev_b32_e32 v0, 16, v0
	v_add3_u32 v27, v34, v27, s59
	v_and_or_b32 v31, v27, s60, v0
	v_or_b32_e32 v0, s4, v160
	v_mul_u32_u24_e32 v0, 0xb00, v0
	v_lshl_add_u64 v[16:17], v[12:13], 0, s[10:11]
	v_lshlrev_b32_e32 v0, 1, v0
	v_lshl_add_u64 v[32:33], v[16:17], 0, v[0:1]
	global_store_dwordx4 v[32:33], v[28:31], off sc0 sc1
	ds_read_b32 v0, v19 offset:32
	ds_read_b32 v27, v19 offset:164
	ds_read_b32 v29, v19 offset:296
	ds_read_b32 v30, v19 offset:428
	ds_read_b32 v31, v19 offset:560
	ds_read_b32 v32, v19 offset:692
	ds_read_b32 v33, v19 offset:824
	ds_read_b32 v34, v19 offset:956
	s_waitcnt lgkmcnt(0)
	v_bfe_u32 v28, v0, 16, 1
	v_add3_u32 v0, v0, v28, s59
	v_bfe_u32 v28, v27, 16, 1
	v_lshrrev_b32_e32 v0, 16, v0
	v_add3_u32 v27, v27, v28, s59
	v_and_or_b32 v28, v27, s60, v0
	v_bfe_u32 v0, v29, 16, 1
	v_add3_u32 v0, v29, v0, s59
	v_bfe_u32 v27, v30, 16, 1
	v_lshrrev_b32_e32 v0, 16, v0
	v_add3_u32 v27, v30, v27, s59
	v_and_or_b32 v29, v27, s60, v0
	v_bfe_u32 v0, v31, 16, 1
	v_add3_u32 v0, v31, v0, s59
	v_bfe_u32 v27, v32, 16, 1
	v_lshrrev_b32_e32 v0, 16, v0
	v_add3_u32 v27, v32, v27, s59
	v_and_or_b32 v30, v27, s60, v0
	v_bfe_u32 v0, v33, 16, 1
	v_add3_u32 v0, v33, v0, s59
	v_bfe_u32 v27, v34, 16, 1
	v_lshrrev_b32_e32 v0, 16, v0
	v_add3_u32 v27, v34, v27, s59
	v_and_or_b32 v31, v27, s60, v0
	v_or_b32_e32 v0, s4, v161
	v_mul_u32_u24_e32 v0, 0xb00, v0
	v_lshlrev_b32_e32 v0, 1, v0
	v_lshl_add_u64 v[32:33], v[16:17], 0, v[0:1]
	global_store_dwordx4 v[32:33], v[28:31], off sc0 sc1
	ds_read_b32 v0, v19 offset:64
	ds_read_b32 v27, v19 offset:196
	ds_read_b32 v29, v19 offset:328
	ds_read_b32 v30, v19 offset:460
	ds_read_b32 v31, v19 offset:592
	ds_read_b32 v32, v19 offset:724
	ds_read_b32 v33, v19 offset:856
	ds_read_b32 v34, v19 offset:988
	s_waitcnt lgkmcnt(0)
	v_bfe_u32 v28, v0, 16, 1
	v_add3_u32 v0, v0, v28, s59
	v_bfe_u32 v28, v27, 16, 1
	v_lshrrev_b32_e32 v0, 16, v0
	v_add3_u32 v27, v27, v28, s59
	v_and_or_b32 v28, v27, s60, v0
	v_bfe_u32 v0, v29, 16, 1
	v_add3_u32 v0, v29, v0, s59
	v_bfe_u32 v27, v30, 16, 1
	v_lshrrev_b32_e32 v0, 16, v0
	v_add3_u32 v27, v30, v27, s59
	v_and_or_b32 v29, v27, s60, v0
	v_bfe_u32 v0, v31, 16, 1
	v_add3_u32 v0, v31, v0, s59
	v_bfe_u32 v27, v32, 16, 1
	v_lshrrev_b32_e32 v0, 16, v0
	v_add3_u32 v27, v32, v27, s59
	v_and_or_b32 v30, v27, s60, v0
	v_bfe_u32 v0, v33, 16, 1
	v_add3_u32 v0, v33, v0, s59
	v_bfe_u32 v27, v34, 16, 1
	v_lshrrev_b32_e32 v0, 16, v0
	v_add3_u32 v27, v34, v27, s59
	v_and_or_b32 v31, v27, s60, v0
	v_or_b32_e32 v0, s4, v162
	v_mul_u32_u24_e32 v0, 0xb00, v0
	v_lshlrev_b32_e32 v0, 1, v0
	v_lshl_add_u64 v[32:33], v[16:17], 0, v[0:1]
	global_store_dwordx4 v[32:33], v[28:31], off sc0 sc1
	ds_read_b32 v0, v19 offset:96
	ds_read_b32 v27, v19 offset:228
	ds_read_b32 v29, v19 offset:360
	ds_read_b32 v30, v19 offset:492
	ds_read_b32 v31, v19 offset:624
	ds_read_b32 v32, v19 offset:756
	ds_read_b32 v33, v19 offset:888
	ds_read_b32 v34, v19 offset:1020
	s_waitcnt lgkmcnt(0)
	v_bfe_u32 v28, v0, 16, 1
	v_add3_u32 v0, v0, v28, s59
	v_bfe_u32 v28, v27, 16, 1
	v_lshrrev_b32_e32 v0, 16, v0
	v_add3_u32 v27, v27, v28, s59
	v_and_or_b32 v28, v27, s60, v0
	v_bfe_u32 v0, v29, 16, 1
	v_add3_u32 v0, v29, v0, s59
	v_bfe_u32 v27, v30, 16, 1
	v_lshrrev_b32_e32 v0, 16, v0
	v_add3_u32 v27, v30, v27, s59
	v_and_or_b32 v29, v27, s60, v0
	v_bfe_u32 v0, v31, 16, 1
	v_add3_u32 v0, v31, v0, s59
	v_bfe_u32 v27, v32, 16, 1
	v_lshrrev_b32_e32 v0, 16, v0
	v_add3_u32 v27, v32, v27, s59
	v_and_or_b32 v30, v27, s60, v0
	v_bfe_u32 v0, v33, 16, 1
	v_add3_u32 v0, v33, v0, s59
	v_bfe_u32 v27, v34, 16, 1
	v_lshrrev_b32_e32 v0, 16, v0
	v_add3_u32 v27, v34, v27, s59
	v_and_or_b32 v31, v27, s60, v0
	v_or_b32_e32 v0, s4, v163
	v_mul_u32_u24_e32 v0, 0xb00, v0
	v_lshlrev_b32_e32 v0, 1, v0
	v_lshl_add_u64 v[16:17], v[16:17], 0, v[0:1]
	global_store_dwordx4 v[16:17], v[28:31], off sc0 sc1
	s_waitcnt lgkmcnt(0)

; #define TR_TRY(CNT, NBLK, ...) if (r < (CNT)) { const int k0 = 64 * (r / (NBLK)), n0 = 32 * (r % (NBLK)); (void)k0; (void)n0; __VA_ARGS__; continue; } r -= (CNT);
; #define TR_TRY(CNT, NBLK, ...) if (r < (CNT)) { const int k0 = 64 * (r / (NBLK)), n0 = 32 * (r % (NBLK)); (void)k0; (void)n0; __VA_ARGS__; continue; } r -= (CNT);
; __device__ __forceinline__ void tr_item(const float* W, int N, int k0, int n0, bf16* WT, int Kd, int drow0, int dk0, LAS float* scr, int lane) {
;     ...
;         float wv[32]; const int n = n0 + (lane & 31); const float* wp = W + (size_t)(k0 + (lane >> 5)) * N + n;
; #pragma unroll
;         for (int i = 0; i < 32; ++i) wv[i] = (n < N) ? wp[(size_t)(2 * i) * N] : 0.f;
; #pragma unroll
;         for (int i = 0; i < 32; ++i) scr[(2 * i + (lane >> 5)) * 33 + (lane & 31)] = wv[i];
; __global__ void __launch_bounds__(NTHREADS, 2) mega_fwd(Args a_unused) {
;     ...
;             TR_TRY(I_GU, FF / 32, tr_item(ap->in[7], FF, k0, n0, Wgu1, D, (n0 / 128) * 256 + 128 + (n0 % 128), k0, scr, lane))
.LBB0_188:
	s_andn2_b64 vcc, exec, s[4:5]
	s_cbranch_vccnz .LBB0_190
	v_mov_b64_e32 v[16:17], s[38:39]
	global_load_dwordx2 v[16:17], v[16:17], off offset:56
	s_add_i32 s4, s97, 0xfa80
	s_and_b32 s5, s4, 0xffff
	s_mul_i32 s5, s5, 0xba2f
	s_lshr_b32 s10, s5, 22
	s_lshr_b32 s5, s5, 16
	s_mulk_i32 s10, 0x58
	s_and_b32 s5, s5, 0xffc0
	s_sub_i32 s4, s4, s10
	v_or_b32_e32 v0, s5, v159
	s_and_b32 s4, s4, 0xffff
	v_mul_u32_u24_e32 v0, 0xb00, v0
	s_lshl_b32 s10, s4, 5
	v_lshlrev_b32_e32 v0, 2, v0
	v_or_b32_e32 v27, s10, v158
	s_lshl_b32 s4, s4, 6
	s_and_b32 s4, s4, 0x1f00
	s_and_b32 s10, s10, 0x60
	s_or_b32 s4, s10, s4
	s_bitset1_b32 s4, 7
	s_lshl_b32 s10, s5, 1
	s_waitcnt vmcnt(0) lgkmcnt(0)
	v_lshl_add_u64 v[16:17], v[16:17], 0, v[0:1]
	v_lshlrev_b32_e32 v0, 2, v27
	v_lshl_add_u64 v[16:17], v[16:17], 0, v[0:1]
	v_add_co_u32_e32 v28, vcc, s70, v16
	s_nop 1
	v_addc_co_u32_e32 v29, vcc, 0, v17, vcc
	v_add_co_u32_e32 v30, vcc, s71, v16
	s_nop 1
	v_addc_co_u32_e32 v31, vcc, 0, v17, vcc
	v_add_co_u32_e32 v32, vcc, s45, v16
	s_nop 1
	v_addc_co_u32_e32 v33, vcc, 0, v17, vcc
	v_add_co_u32_e32 v34, vcc, s47, v16
	s_nop 1
	v_addc_co_u32_e32 v35, vcc, 0, v17, vcc
	v_add_co_u32_e32 v36, vcc, s67, v16
	s_nop 1
	v_addc_co_u32_e32 v37, vcc, 0, v17, vcc
	v_add_co_u32_e32 v38, vcc, s68, v16
	s_nop 1
	v_addc_co_u32_e32 v39, vcc, 0, v17, vcc
	v_add_co_u32_e32 v40, vcc, s53, v16
	s_nop 1
	v_addc_co_u32_e32 v41, vcc, 0, v17, vcc
	v_add_co_u32_e32 v42, vcc, s56, v16
	global_load_dword v0, v[16:17], off nt
	global_load_dword v27, v[28:29], off offset:2048 nt
	global_load_dword v56, v[30:31], off nt
	global_load_dword v57, v[32:33], off offset:2048 nt
	global_load_dword v58, v[34:35], off nt
	global_load_dword v59, v[36:37], off offset:2048 nt
	global_load_dword v60, v[38:39], off nt
	global_load_dword v61, v[40:41], off offset:2048 nt
	v_addc_co_u32_e32 v43, vcc, 0, v17, vcc
	v_add_co_u32_e32 v44, vcc, s78, v16
	s_nop 1
	v_addc_co_u32_e32 v45, vcc, 0, v17, vcc
	v_add_co_u32_e32 v46, vcc, s79, v16
	s_nop 1
	v_addc_co_u32_e32 v47, vcc, 0, v17, vcc
	v_add_co_u32_e32 v48, vcc, s58, v16
	s_nop 1
	v_addc_co_u32_e32 v49, vcc, 0, v17, vcc
	v_add_co_u32_e32 v50, vcc, s80, v16
	s_nop 1
	v_addc_co_u32_e32 v51, vcc, 0, v17, vcc
	v_add_co_u32_e32 v52, vcc, s81, v16
	s_nop 1
	v_addc_co_u32_e32 v53, vcc, 0, v17, vcc
	v_add_co_u32_e32 v54, vcc, s74, v16
	s_nop 1
	v_addc_co_u32_e32 v55, vcc, 0, v17, vcc
	v_add_co_u32_e32 v28, vcc, s82, v16
	s_nop 1
	v_addc_co_u32_e32 v29, vcc, 0, v17, vcc
	global_load_dword v62, v[42:43], off nt
	s_nop 0
	global_load_dword v44, v[44:45], off offset:2048 nt
	s_nop 0
	global_load_dword v45, v[46:47], off nt
	s_nop 0
	global_load_dword v46, v[48:49], off offset:2048 nt
	global_load_dword v47, v[50:51], off nt
	s_nop 0
	global_load_dword v48, v[52:53], off offset:2048 nt
	global_load_dword v49, v[54:55], off nt
	global_load_dword v50, v[28:29], off offset:2048 nt
	v_add_co_u32_e32 v28, vcc, s75, v16
	s_nop 1
	v_addc_co_u32_e32 v29, vcc, 0, v17, vcc
	v_add_co_u32_e32 v30, vcc, s83, v16
	s_nop 1
	v_addc_co_u32_e32 v31, vcc, 0, v17, vcc
	v_add_co_u32_e32 v32, vcc, s84, v16
	s_nop 1
	v_addc_co_u32_e32 v33, vcc, 0, v17, vcc
	v_add_co_u32_e32 v34, vcc, s76, v16
	s_nop 1
	v_addc_co_u32_e32 v35, vcc, 0, v17, vcc
	v_add_co_u32_e32 v36, vcc, s85, v16
	s_nop 1
	v_addc_co_u32_e32 v37, vcc, 0, v17, vcc
	v_add_co_u32_e32 v38, vcc, s77, v16
	s_nop 1
	v_addc_co_u32_e32 v39, vcc, 0, v17, vcc
	v_add_co_u32_e32 v40, vcc, s86, v16
	s_nop 1
	v_addc_co_u32_e32 v41, vcc, 0, v17, vcc
	v_add_co_u32_e32 v42, vcc, s87, v16
	s_nop 1
	v_addc_co_u32_e32 v43, vcc, 0, v17, vcc
	global_load_dword v51, v[28:29], off nt
	global_load_dword v52, v[30:31], off offset:2048 nt
	global_load_dword v53, v[32:33], off nt
	global_load_dword v54, v[34:35], off offset:2048 nt
	global_load_dword v55, v[36:37], off nt
	global_load_dword v63, v[38:39], off offset:2048 nt
	global_load_dword v64, v[40:41], off nt
	s_nop 0
	global_load_dword v42, v[42:43], off offset:2048 nt
	v_add_co_u32_e32 v28, vcc, s88, v16
	s_nop 1
	v_addc_co_u32_e32 v29, vcc, 0, v17, vcc
	v_add_co_u32_e32 v30, vcc, s89, v16
	s_nop 1
	v_addc_co_u32_e32 v31, vcc, 0, v17, vcc
	v_add_co_u32_e32 v32, vcc, s90, v16
	s_nop 1
	v_addc_co_u32_e32 v33, vcc, 0, v17, vcc
	v_add_co_u32_e32 v34, vcc, s91, v16
	s_nop 1
	v_addc_co_u32_e32 v35, vcc, 0, v17, vcc
	v_add_co_u32_e32 v36, vcc, s92, v16
	s_nop 1
	v_addc_co_u32_e32 v37, vcc, 0, v17, vcc
	v_add_co_u32_e32 v38, vcc, s93, v16
	s_nop 1
	v_addc_co_u32_e32 v39, vcc, 0, v17, vcc
	v_add_co_u32_e32 v40, vcc, s94, v16
	s_nop 1
	v_addc_co_u32_e32 v41, vcc, 0, v17, vcc
	v_add_co_u32_e32 v16, vcc, s95, v16
	s_nop 1
	v_addc_co_u32_e32 v17, vcc, 0, v17, vcc
	global_load_dword v28, v[28:29], off nt
	s_nop 0
	global_load_dword v29, v[30:31], off offset:2048 nt
	s_nop 0
	global_load_dword v30, v[32:33], off nt
	global_load_dword v31, v[34:35], off offset:2048 nt
	s_nop 0
	global_load_dword v32, v[36:37], off nt
	global_load_dword v33, v[38:39], off offset:2048 nt
	global_load_dword v34, v[40:41], off nt
	s_nop 0
	global_load_dword v16, v[16:17], off offset:2048 nt
	s_waitcnt vmcnt(0) lgkmcnt(0)
; #define LAS __attribute__((address_space(3)))
; #define LDS_WAIT() asm volatile("s_waitcnt lgkmcnt(0)" ::: "memory")
; __device__ __forceinline__ unsigned pk2(float lo, float hi) { return f2bf(lo) | (f2bf(hi) << 16); }
; __device__ __forceinline__ void tr_item(const float* W, int N, int k0, int n0, bf16* WT, int Kd, int drow0, int dk0, LAS float* scr, int lane) {
;     ...
;         for (int i = 0; i < 32; ++i) scr[(2 * i + (lane >> 5)) * 33 + (lane & 31)] = wv[i];
;     }
;     LDS_WAIT();
;     const int c = lane & 7;
; #pragma unroll
;     for (int j = 0; j < 4; ++j) { const int n = (lane >> 3) + 8 * j; const LAS float* s = scr + (8 * c) * 33 + n;
;         v4u o; o.x = pk2(s[0 * 33], s[1 * 33]); o.y = pk2(s[2 * 33], s[3 * 33]); o.z = pk2(s[4 * 33], s[5 * 33]); o.w = pk2(s[6 * 33], s[7 * 33]);
;         *(v4u*)(WT + (size_t)(drow0 + n) * Kd + dk0 + 8 * c) = o; }
;     LDS_WAIT();
	ds_write2_b32 v18, v0, v27 offset1:66
	ds_write2_b32 v18, v56, v57 offset0:132 offset1:198
	ds_write2_b32 v20, v58, v59 offset0:8 offset1:74
	ds_write2_b32 v20, v60, v61 offset0:140 offset1:206
	ds_write2_b32 v21, v62, v44 offset0:16 offset1:82
	ds_write2_b32 v21, v45, v46 offset0:148 offset1:214
	ds_write2_b32 v22, v47, v48 offset0:24 offset1:90
	ds_write2_b32 v22, v49, v50 offset0:156 offset1:222
	ds_write2_b32 v23, v51, v52 offset0:32 offset1:98
	ds_write2_b32 v23, v53, v54 offset0:164 offset1:230
	ds_write2_b32 v24, v55, v63 offset0:40 offset1:106
	ds_write2_b32 v24, v64, v42 offset0:172 offset1:238
	ds_write2_b32 v25, v28, v29 offset0:48 offset1:114
	ds_write2_b32 v25, v30, v31 offset0:180 offset1:246
	ds_write2_b32 v26, v32, v33 offset0:56 offset1:122
	ds_write2_b32 v26, v34, v16 offset0:188 offset1:254
	s_waitcnt lgkmcnt(0)
	ds_read_b32 v0, v19
	ds_read_b32 v27, v19 offset:132
	ds_read_b32 v29, v19 offset:264
	ds_read_b32 v30, v19 offset:396
	ds_read_b32 v31, v19 offset:528
	ds_read_b32 v32, v19 offset:660
	ds_read_b32 v33, v19 offset:792
	ds_read_b32 v34, v19 offset:924
	s_waitcnt lgkmcnt(7)
	v_bfe_u32 v28, v0, 16, 1
	v_add3_u32 v0, v0, v28, s59
	s_waitcnt lgkmcnt(6)
	v_bfe_u32 v28, v27, 16, 1
	v_lshrrev_b32_e32 v0, 16, v0
	v_add3_u32 v27, v27, v28, s59
	v_and_or_b32 v28, v27, s60, v0
	s_waitcnt lgkmcnt(5)
	v_bfe_u32 v0, v29, 16, 1
	v_add3_u32 v0, v29, v0, s59
	s_waitcnt lgkmcnt(4)
	v_bfe_u32 v27, v30, 16, 1
	v_lshrrev_b32_e32 v0, 16, v0
	v_add3_u32 v27, v30, v27, s59
	v_and_or_b32 v29, v27, s60, v0
	s_waitcnt lgkmcnt(3)
	v_bfe_u32 v0, v31, 16, 1
	v_add3_u32 v0, v31, v0, s59
	s_waitcnt lgkmcnt(2)
	v_bfe_u32 v27, v32, 16, 1
	v_lshrrev_b32_e32 v0, 16, v0
	v_add3_u32 v27, v32, v27, s59
	v_and_or_b32 v30, v27, s60, v0
	s_waitcnt lgkmcnt(1)
	v_bfe_u32 v0, v33, 16, 1
	v_add3_u32 v0, v33, v0, s59
	s_waitcnt lgkmcnt(0)
	v_bfe_u32 v27, v34, 16, 1
	v_lshrrev_b32_e32 v0, 16, v0
	v_add3_u32 v27, v34, v27, s59
	v_and_or_b32 v31, v27, s60, v0
	v_or_b32_e32 v0, s4, v160
	v_lshl_add_u64 v[16:17], v[14:15], 0, s[10:11]
	v_lshlrev_b32_e32 v0, 11, v0
	v_lshl_add_u64 v[32:33], v[16:17], 0, v[0:1]
	global_store_dwordx4 v[32:33], v[28:31], off sc0 sc1
	ds_read_b32 v0, v19 offset:32
	ds_read_b32 v27, v19 offset:164
	ds_read_b32 v29, v19 offset:296
	ds_read_b32 v30, v19 offset:428
	ds_read_b32 v31, v19 offset:560
	ds_read_b32 v32, v19 offset:692
	ds_read_b32 v33, v19 offset:824
	ds_read_b32 v34, v19 offset:956
	s_waitcnt lgkmcnt(0)
	v_bfe_u32 v28, v0, 16, 1
	v_add3_u32 v0, v0, v28, s59
	v_bfe_u32 v28, v27, 16, 1
	v_lshrrev_b32_e32 v0, 16, v0
	v_add3_u32 v27, v27, v28, s59
	v_and_or_b32 v28, v27, s60, v0
	v_bfe_u32 v0, v29, 16, 1
	v_add3_u32 v0, v29, v0, s59
	v_bfe_u32 v27, v30, 16, 1
	v_lshrrev_b32_e32 v0, 16, v0
	v_add3_u32 v27, v30, v27, s59
	v_and_or_b32 v29, v27, s60, v0
	v_bfe_u32 v0, v31, 16, 1
	v_add3_u32 v0, v31, v0, s59
	v_bfe_u32 v27, v32, 16, 1
	v_lshrrev_b32_e32 v0, 16, v0
	v_add3_u32 v27, v32, v27, s59
	v_and_or_b32 v30, v27, s60, v0
	v_bfe_u32 v0, v33, 16, 1
	v_add3_u32 v0, v33, v0, s59
	v_bfe_u32 v27, v34, 16, 1
	v_lshrrev_b32_e32 v0, 16, v0
	v_add3_u32 v27, v34, v27, s59
	v_and_or_b32 v31, v27, s60, v0
	v_or_b32_e32 v0, s4, v161
	v_lshlrev_b32_e32 v0, 11, v0
	v_lshl_add_u64 v[32:33], v[16:17], 0, v[0:1]
	global_store_dwordx4 v[32:33], v[28:31], off sc0 sc1
	ds_read_b32 v0, v19 offset:64
	ds_read_b32 v27, v19 offset:196
	ds_read_b32 v29, v19 offset:328
	ds_read_b32 v30, v19 offset:460
	ds_read_b32 v31, v19 offset:592
	ds_read_b32 v32, v19 offset:724
	ds_read_b32 v33, v19 offset:856
	ds_read_b32 v34, v19 offset:988
	s_waitcnt lgkmcnt(0)
	v_bfe_u32 v28, v0, 16, 1
	v_add3_u32 v0, v0, v28, s59
	v_bfe_u32 v28, v27, 16, 1
	v_lshrrev_b32_e32 v0, 16, v0
	v_add3_u32 v27, v27, v28, s59
	v_and_or_b32 v28, v27, s60, v0
	v_bfe_u32 v0, v29, 16, 1
	v_add3_u32 v0, v29, v0, s59
	v_bfe_u32 v27, v30, 16, 1
	v_lshrrev_b32_e32 v0, 16, v0
	v_add3_u32 v27, v30, v27, s59
	v_and_or_b32 v29, v27, s60, v0
	v_bfe_u32 v0, v31, 16, 1
	v_add3_u32 v0, v31, v0, s59
	v_bfe_u32 v27, v32, 16, 1
	v_lshrrev_b32_e32 v0, 16, v0
	v_add3_u32 v27, v32, v27, s59
	v_and_or_b32 v30, v27, s60, v0
	v_bfe_u32 v0, v33, 16, 1
	v_add3_u32 v0, v33, v0, s59
	v_bfe_u32 v27, v34, 16, 1
	v_lshrrev_b32_e32 v0, 16, v0
	v_add3_u32 v27, v34, v27, s59
	v_and_or_b32 v31, v27, s60, v0
	v_or_b32_e32 v0, s4, v162
	v_lshlrev_b32_e32 v0, 11, v0
	v_lshl_add_u64 v[32:33], v[16:17], 0, v[0:1]
	global_store_dwordx4 v[32:33], v[28:31], off sc0 sc1
	ds_read_b32 v0, v19 offset:96
	ds_read_b32 v27, v19 offset:228
	ds_read_b32 v29, v19 offset:360
	ds_read_b32 v30, v19 offset:492
	ds_read_b32 v31, v19 offset:624
	ds_read_b32 v32, v19 offset:756
	ds_read_b32 v33, v19 offset:888
	ds_read_b32 v34, v19 offset:1020
	s_waitcnt lgkmcnt(0)
	v_bfe_u32 v28, v0, 16, 1
	v_add3_u32 v0, v0, v28, s59
	v_bfe_u32 v28, v27, 16, 1
	v_lshrrev_b32_e32 v0, 16, v0
	v_add3_u32 v27, v27, v28, s59
	v_and_or_b32 v28, v27, s60, v0
	v_bfe_u32 v0, v29, 16, 1
	v_add3_u32 v0, v29, v0, s59
	v_bfe_u32 v27, v30, 16, 1
	v_lshrrev_b32_e32 v0, 16, v0
	v_add3_u32 v27, v30, v27, s59
	v_and_or_b32 v29, v27, s60, v0
	v_bfe_u32 v0, v31, 16, 1
	v_add3_u32 v0, v31, v0, s59
	v_bfe_u32 v27, v32, 16, 1
	v_lshrrev_b32_e32 v0, 16, v0
	v_add3_u32 v27, v32, v27, s59
	v_and_or_b32 v30, v27, s60, v0
	v_bfe_u32 v0, v33, 16, 1
	v_add3_u32 v0, v33, v0, s59
	v_bfe_u32 v27, v34, 16, 1
	v_lshrrev_b32_e32 v0, 16, v0
	v_add3_u32 v27, v34, v27, s59
	v_and_or_b32 v31, v27, s60, v0
	v_or_b32_e32 v0, s4, v163
	v_lshlrev_b32_e32 v0, 11, v0
	v_lshl_add_u64 v[16:17], v[16:17], 0, v[0:1]
	global_store_dwordx4 v[16:17], v[28:31], off sc0 sc1
	s_waitcnt lgkmcnt(0)

; #define TR_TRY(CNT, NBLK, ...) if (r < (CNT)) { const int k0 = 64 * (r / (NBLK)), n0 = 32 * (r % (NBLK)); (void)k0; (void)n0; __VA_ARGS__; continue; } r -= (CNT);
; #define TR_TRY(CNT, NBLK, ...) if (r < (CNT)) { const int k0 = 64 * (r / (NBLK)), n0 = 32 * (r % (NBLK)); (void)k0; (void)n0; __VA_ARGS__; continue; } r -= (CNT);
; __device__ __forceinline__ void tr_item(const float* W, int N, int k0, int n0, bf16* WT, int Kd, int drow0, int dk0, LAS float* scr, int lane) {
;     ...
;         float wv[32]; const int n = n0 + (lane & 31); const float* wp = W + (size_t)(k0 + (lane >> 5)) * N + n;
; #pragma unroll
;         for (int i = 0; i < 32; ++i) wv[i] = (n < N) ? wp[(size_t)(2 * i) * N] : 0.f;
; #pragma unroll
;         for (int i = 0; i < 32; ++i) scr[(2 * i + (lane >> 5)) * 33 + (lane & 31)] = wv[i];
; __global__ void __launch_bounds__(NTHREADS, 2) mega_fwd(Args a_unused) {
;     ...
;             TR_TRY(I_GU, FF / 32, tr_item(ap->in[6], FF, k0, n0, Wgu1, D, (n0 / 128) * 256 + (n0 % 128), k0, scr, lane))
.LBB0_191:
	s_andn2_b64 vcc, exec, s[4:5]
	s_cbranch_vccnz .LBB0_100
	v_mov_b64_e32 v[16:17], s[38:39]
	global_load_dwordx2 v[16:17], v[16:17], off offset:48
	s_mul_hi_i32 s4, s97, 0x2e8ba2e9
	s_lshr_b32 s5, s4, 31
	s_ashr_i32 s10, s4, 4
	s_add_i32 s10, s10, s5
	s_mul_i32 s5, s10, 0xfffff500
	s_lshl_b32 s4, s10, 6
	s_add_i32 s5, s7, s5
	v_or_b32_e32 v0, s4, v159
	v_add_u32_e32 v28, s5, v158
	v_ashrrev_i32_e32 v29, 31, v28
	s_mulk_i32 s10, 0xffa8
	s_add_i32 s10, s97, s10
	s_waitcnt vmcnt(0) lgkmcnt(0)
	v_mad_i64_i32 v[16:17], s[12:13], v0, s96, v[16:17]
	v_lshl_add_u64 v[16:17], v[28:29], 2, v[16:17]
	v_add_co_u32_e32 v28, vcc, s70, v16
	s_bfe_i32 s12, s10, 0x80000
	s_nop 0
	v_addc_co_u32_e32 v29, vcc, 0, v17, vcc
	v_add_co_u32_e32 v30, vcc, s71, v16
	s_bfe_u32 s12, s12, 0x2000d
	s_nop 0
	v_addc_co_u32_e32 v31, vcc, 0, v17, vcc
	v_add_co_u32_e32 v32, vcc, s45, v16
	s_add_i32 s10, s10, s12
	s_nop 0
	v_addc_co_u32_e32 v33, vcc, 0, v17, vcc
	v_add_co_u32_e32 v34, vcc, s47, v16
	s_bfe_u32 s12, s5, 0x70018
	s_nop 0
	v_addc_co_u32_e32 v35, vcc, 0, v17, vcc
	v_add_co_u32_e32 v36, vcc, s67, v16
	s_bfe_i32 s10, s10, 0x80000
	s_nop 0
	v_addc_co_u32_e32 v37, vcc, 0, v17, vcc
	v_add_co_u32_e32 v38, vcc, s68, v16
	s_add_i32 s12, s5, s12
	s_nop 0
	v_addc_co_u32_e32 v39, vcc, 0, v17, vcc
	v_add_co_u32_e32 v40, vcc, s53, v16
	s_sext_i32_i16 s10, s10
	s_nop 0
	v_addc_co_u32_e32 v41, vcc, 0, v17, vcc
	v_add_co_u32_e32 v42, vcc, s56, v16
	s_and_b32 s12, s12, 0xff80
	s_nop 0
	v_addc_co_u32_e32 v43, vcc, 0, v17, vcc
	v_add_co_u32_e32 v44, vcc, s78, v16
	s_lshl_b32 s10, s10, 6
	s_nop 0
	v_addc_co_u32_e32 v45, vcc, 0, v17, vcc
	v_add_co_u32_e32 v46, vcc, s79, v16
	s_sub_i32 s5, s5, s12
	s_nop 0
	v_addc_co_u32_e32 v47, vcc, 0, v17, vcc
	v_add_co_u32_e32 v48, vcc, s58, v16
	s_and_b32 s10, s10, 0xffffff00
	s_nop 0
	v_addc_co_u32_e32 v49, vcc, 0, v17, vcc
	v_add_co_u32_e32 v50, vcc, s80, v16
	s_sext_i32_i16 s5, s5
	s_nop 0
	v_addc_co_u32_e32 v51, vcc, 0, v17, vcc
	v_add_co_u32_e32 v52, vcc, s81, v16
	s_add_i32 s10, s10, s5
	s_nop 0
	v_addc_co_u32_e32 v53, vcc, 0, v17, vcc
	v_add_co_u32_e32 v54, vcc, s74, v16
	s_ashr_i32 s5, s4, 31
	s_nop 0
	v_addc_co_u32_e32 v55, vcc, 0, v17, vcc
	v_add_co_u32_e32 v56, vcc, s82, v16
	s_nop 1
	v_addc_co_u32_e32 v57, vcc, 0, v17, vcc
	global_load_dword v0, v[16:17], off nt
	global_load_dword v27, v[28:29], off offset:2048 nt
	global_load_dword v58, v[30:31], off nt
	global_load_dword v59, v[32:33], off offset:2048 nt
	global_load_dword v60, v[34:35], off nt
	global_load_dword v61, v[36:37], off offset:2048 nt
	global_load_dword v62, v[38:39], off nt
	global_load_dword v63, v[40:41], off offset:2048 nt
	global_load_dword v64, v[42:43], off nt
	s_nop 0
	global_load_dword v44, v[44:45], off offset:2048 nt
	s_nop 0
	global_load_dword v45, v[46:47], off nt
	s_nop 0
	global_load_dword v46, v[48:49], off offset:2048 nt
	global_load_dword v47, v[50:51], off nt
	s_nop 0
	global_load_dword v48, v[52:53], off offset:2048 nt
	global_load_dword v49, v[54:55], off nt
	global_load_dword v50, v[56:57], off offset:2048 nt
	v_add_co_u32_e32 v28, vcc, s75, v16
	s_nop 1
	v_addc_co_u32_e32 v29, vcc, 0, v17, vcc
	v_add_co_u32_e32 v30, vcc, s83, v16
	s_nop 1
	v_addc_co_u32_e32 v31, vcc, 0, v17, vcc
	v_add_co_u32_e32 v32, vcc, s84, v16
	s_nop 1
	v_addc_co_u32_e32 v33, vcc, 0, v17, vcc
	v_add_co_u32_e32 v34, vcc, s76, v16
	s_nop 1
	v_addc_co_u32_e32 v35, vcc, 0, v17, vcc
	v_add_co_u32_e32 v36, vcc, s85, v16
	s_nop 1
	v_addc_co_u32_e32 v37, vcc, 0, v17, vcc
	v_add_co_u32_e32 v38, vcc, s77, v16
	s_nop 1
	v_addc_co_u32_e32 v39, vcc, 0, v17, vcc
	v_add_co_u32_e32 v40, vcc, s86, v16
	s_nop 1
	v_addc_co_u32_e32 v41, vcc, 0, v17, vcc
	v_add_co_u32_e32 v42, vcc, s87, v16
	s_nop 1
	v_addc_co_u32_e32 v43, vcc, 0, v17, vcc
	global_load_dword v51, v[28:29], off nt
	global_load_dword v52, v[30:31], off offset:2048 nt
	global_load_dword v53, v[32:33], off nt
	global_load_dword v54, v[34:35], off offset:2048 nt
	global_load_dword v55, v[36:37], off nt
	global_load_dword v56, v[38:39], off offset:2048 nt
	global_load_dword v57, v[40:41], off nt
	s_nop 0
	global_load_dword v42, v[42:43], off offset:2048 nt
	v_add_co_u32_e32 v28, vcc, s88, v16
	s_nop 1
	v_addc_co_u32_e32 v29, vcc, 0, v17, vcc
	v_add_co_u32_e32 v30, vcc, s89, v16
	s_nop 1
	v_addc_co_u32_e32 v31, vcc, 0, v17, vcc
	v_add_co_u32_e32 v32, vcc, s90, v16
	s_nop 1
	v_addc_co_u32_e32 v33, vcc, 0, v17, vcc
	v_add_co_u32_e32 v34, vcc, s91, v16
	s_nop 1
	v_addc_co_u32_e32 v35, vcc, 0, v17, vcc
	v_add_co_u32_e32 v36, vcc, s92, v16
	s_nop 1
	v_addc_co_u32_e32 v37, vcc, 0, v17, vcc
	v_add_co_u32_e32 v38, vcc, s93, v16
	s_nop 1
	v_addc_co_u32_e32 v39, vcc, 0, v17, vcc
	v_add_co_u32_e32 v40, vcc, s94, v16
	s_nop 1
	v_addc_co_u32_e32 v41, vcc, 0, v17, vcc
	v_add_co_u32_e32 v16, vcc, s95, v16
	s_nop 1
	v_addc_co_u32_e32 v17, vcc, 0, v17, vcc
	global_load_dword v28, v[28:29], off nt
	s_nop 0
	global_load_dword v29, v[30:31], off offset:2048 nt
	s_nop 0
	global_load_dword v30, v[32:33], off nt
	global_load_dword v31, v[34:35], off offset:2048 nt
	s_nop 0
	global_load_dword v32, v[36:37], off nt
	global_load_dword v33, v[38:39], off offset:2048 nt
	global_load_dword v34, v[40:41], off nt
	s_nop 0
	global_load_dword v16, v[16:17], off offset:2048 nt
	s_waitcnt vmcnt(0) lgkmcnt(0)
; #define LAS __attribute__((address_space(3)))
; #define LDS_WAIT() asm volatile("s_waitcnt lgkmcnt(0)" ::: "memory")
; __device__ __forceinline__ unsigned pk2(float lo, float hi) { return f2bf(lo) | (f2bf(hi) << 16); }
; #define TR_TRY(CNT, NBLK, ...) if (r < (CNT)) { const int k0 = 64 * (r / (NBLK)), n0 = 32 * (r % (NBLK)); (void)k0; (void)n0; __VA_ARGS__; continue; } r -= (CNT);
; #define TR_TRY(CNT, NBLK, ...) if (r < (CNT)) { const int k0 = 64 * (r / (NBLK)), n0 = 32 * (r % (NBLK)); (void)k0; (void)n0; __VA_ARGS__; continue; } r -= (CNT);
; __device__ __forceinline__ void tr_item(const float* W, int N, int k0, int n0, bf16* WT, int Kd, int drow0, int dk0, LAS float* scr, int lane) {
;     ...
;         for (int i = 0; i < 32; ++i) scr[(2 * i + (lane >> 5)) * 33 + (lane & 31)] = wv[i];
;     }
;     LDS_WAIT();
;     const int c = lane & 7;
; #pragma unroll
;     for (int j = 0; j < 4; ++j) { const int n = (lane >> 3) + 8 * j; const LAS float* s = scr + (8 * c) * 33 + n;
;         v4u o; o.x = pk2(s[0 * 33], s[1 * 33]); o.y = pk2(s[2 * 33], s[3 * 33]); o.z = pk2(s[4 * 33], s[5 * 33]); o.w = pk2(s[6 * 33], s[7 * 33]);
;         *(v4u*)(WT + (size_t)(drow0 + n) * Kd + dk0 + 8 * c) = o; }
;     LDS_WAIT();
; __global__ void __launch_bounds__(NTHREADS, 2) mega_fwd(Args a_unused) {
;     ...
;         for (int it = gw; it < NITEMS; it += NGW) {
;             int r = it;
;     ...
;             TR_TRY(I_GU, FF / 32, tr_item(ap->in[6], FF, k0, n0, Wgu1, D, (n0 / 128) * 256 + (n0 % 128), k0, scr, lane))
	ds_write2_b32 v18, v0, v27 offset1:66
	ds_write2_b32 v18, v58, v59 offset0:132 offset1:198
	ds_write2_b32 v20, v60, v61 offset0:8 offset1:74
	ds_write2_b32 v20, v62, v63 offset0:140 offset1:206
	ds_write2_b32 v21, v64, v44 offset0:16 offset1:82
	ds_write2_b32 v21, v45, v46 offset0:148 offset1:214
	ds_write2_b32 v22, v47, v48 offset0:24 offset1:90
	ds_write2_b32 v22, v49, v50 offset0:156 offset1:222
	ds_write2_b32 v23, v51, v52 offset0:32 offset1:98
	ds_write2_b32 v23, v53, v54 offset0:164 offset1:230
	ds_write2_b32 v24, v55, v56 offset0:40 offset1:106
	ds_write2_b32 v24, v57, v42 offset0:172 offset1:238
	ds_write2_b32 v25, v28, v29 offset0:48 offset1:114
	ds_write2_b32 v25, v30, v31 offset0:180 offset1:246
	ds_write2_b32 v26, v32, v33 offset0:56 offset1:122
	ds_write2_b32 v26, v34, v16 offset0:188 offset1:254
	s_waitcnt lgkmcnt(0)
	ds_read_b32 v0, v19
	ds_read_b32 v27, v19 offset:132
	ds_read_b32 v29, v19 offset:264
	ds_read_b32 v30, v19 offset:396
	ds_read_b32 v31, v19 offset:528
	ds_read_b32 v32, v19 offset:660
	ds_read_b32 v33, v19 offset:792
	ds_read_b32 v34, v19 offset:924
	s_waitcnt lgkmcnt(7)
	v_bfe_u32 v28, v0, 16, 1
	v_add3_u32 v0, v0, v28, s59
	s_waitcnt lgkmcnt(6)
	v_bfe_u32 v28, v27, 16, 1
	v_lshrrev_b32_e32 v0, 16, v0
	v_add3_u32 v27, v27, v28, s59
	v_and_or_b32 v28, v27, s60, v0
	s_waitcnt lgkmcnt(5)
	v_bfe_u32 v0, v29, 16, 1
	v_add3_u32 v0, v29, v0, s59
	s_waitcnt lgkmcnt(4)
	v_bfe_u32 v27, v30, 16, 1
	v_lshrrev_b32_e32 v0, 16, v0
	v_add3_u32 v27, v30, v27, s59
	v_and_or_b32 v29, v27, s60, v0
	s_waitcnt lgkmcnt(3)
	v_bfe_u32 v0, v31, 16, 1
	v_add3_u32 v0, v31, v0, s59
	s_waitcnt lgkmcnt(2)
	v_bfe_u32 v27, v32, 16, 1
	v_lshrrev_b32_e32 v0, 16, v0
	v_add3_u32 v27, v32, v27, s59
	v_and_or_b32 v30, v27, s60, v0
	s_waitcnt lgkmcnt(1)
	v_bfe_u32 v0, v33, 16, 1
	v_or_b32_e32 v32, s10, v160
	v_add3_u32 v0, v33, v0, s59
	s_waitcnt lgkmcnt(0)
	v_bfe_u32 v27, v34, 16, 1
	v_ashrrev_i32_e32 v33, 31, v32
	v_lshl_add_u64 v[16:17], s[4:5], 1, v[14:15]
	v_lshrrev_b32_e32 v0, 16, v0
	v_add3_u32 v27, v34, v27, s59
	v_lshlrev_b64 v[32:33], 11, v[32:33]
	v_and_or_b32 v31, v27, s60, v0
	v_lshl_add_u64 v[32:33], v[16:17], 0, v[32:33]
	global_store_dwordx4 v[32:33], v[28:31], off sc0 sc1
	ds_read_b32 v0, v19 offset:32
	ds_read_b32 v27, v19 offset:164
	ds_read_b32 v29, v19 offset:296
	ds_read_b32 v30, v19 offset:428
	ds_read_b32 v31, v19 offset:560
	ds_read_b32 v32, v19 offset:692
	ds_read_b32 v33, v19 offset:824
	ds_read_b32 v34, v19 offset:956
	s_waitcnt lgkmcnt(0)
	v_bfe_u32 v28, v0, 16, 1
	v_add3_u32 v0, v0, v28, s59
	v_bfe_u32 v28, v27, 16, 1
	v_lshrrev_b32_e32 v0, 16, v0
	v_add3_u32 v27, v27, v28, s59
	v_and_or_b32 v28, v27, s60, v0
	v_bfe_u32 v0, v29, 16, 1
	v_add3_u32 v0, v29, v0, s59
	v_bfe_u32 v27, v30, 16, 1
	v_lshrrev_b32_e32 v0, 16, v0
	v_add3_u32 v27, v30, v27, s59
	v_and_or_b32 v29, v27, s60, v0
	v_bfe_u32 v0, v31, 16, 1
	v_add3_u32 v0, v31, v0, s59
	v_bfe_u32 v27, v32, 16, 1
	v_lshrrev_b32_e32 v0, 16, v0
	v_add3_u32 v27, v32, v27, s59
	v_and_or_b32 v30, v27, s60, v0
	v_bfe_u32 v0, v33, 16, 1
	v_or_b32_e32 v32, s10, v161
	v_add3_u32 v0, v33, v0, s59
	v_bfe_u32 v27, v34, 16, 1
	v_ashrrev_i32_e32 v33, 31, v32
	v_lshrrev_b32_e32 v0, 16, v0
	v_add3_u32 v27, v34, v27, s59
	v_lshlrev_b64 v[32:33], 11, v[32:33]
	v_and_or_b32 v31, v27, s60, v0
	v_lshl_add_u64 v[32:33], v[16:17], 0, v[32:33]
	global_store_dwordx4 v[32:33], v[28:31], off sc0 sc1
	ds_read_b32 v0, v19 offset:64
	ds_read_b32 v27, v19 offset:196
	ds_read_b32 v29, v19 offset:328
	ds_read_b32 v30, v19 offset:460
	ds_read_b32 v31, v19 offset:592
	ds_read_b32 v32, v19 offset:724
	ds_read_b32 v33, v19 offset:856
	ds_read_b32 v34, v19 offset:988
	s_waitcnt lgkmcnt(0)
	v_bfe_u32 v28, v0, 16, 1
	v_add3_u32 v0, v0, v28, s59
	v_bfe_u32 v28, v27, 16, 1
	v_lshrrev_b32_e32 v0, 16, v0
	v_add3_u32 v27, v27, v28, s59
	v_and_or_b32 v28, v27, s60, v0
	v_bfe_u32 v0, v29, 16, 1
	v_add3_u32 v0, v29, v0, s59
	v_bfe_u32 v27, v30, 16, 1
	v_lshrrev_b32_e32 v0, 16, v0
	v_add3_u32 v27, v30, v27, s59
	v_and_or_b32 v29, v27, s60, v0
	v_bfe_u32 v0, v31, 16, 1
	v_add3_u32 v0, v31, v0, s59
	v_bfe_u32 v27, v32, 16, 1
	v_lshrrev_b32_e32 v0, 16, v0
	v_add3_u32 v27, v32, v27, s59
	v_and_or_b32 v30, v27, s60, v0
	v_bfe_u32 v0, v33, 16, 1
	v_or_b32_e32 v32, s10, v162
	v_add3_u32 v0, v33, v0, s59
	v_bfe_u32 v27, v34, 16, 1
	v_ashrrev_i32_e32 v33, 31, v32
	v_lshrrev_b32_e32 v0, 16, v0
	v_add3_u32 v27, v34, v27, s59
	v_lshlrev_b64 v[32:33], 11, v[32:33]
	v_and_or_b32 v31, v27, s60, v0
	v_lshl_add_u64 v[32:33], v[16:17], 0, v[32:33]
	global_store_dwordx4 v[32:33], v[28:31], off sc0 sc1
	ds_read_b32 v0, v19 offset:96
	ds_read_b32 v27, v19 offset:228
	ds_read_b32 v29, v19 offset:360
	ds_read_b32 v30, v19 offset:492
	ds_read_b32 v31, v19 offset:624
	ds_read_b32 v32, v19 offset:756
	ds_read_b32 v33, v19 offset:888
	ds_read_b32 v34, v19 offset:1020
	s_waitcnt lgkmcnt(0)
	v_bfe_u32 v28, v0, 16, 1
	v_add3_u32 v0, v0, v28, s59
	v_bfe_u32 v28, v27, 16, 1
	v_lshrrev_b32_e32 v0, 16, v0
	v_add3_u32 v27, v27, v28, s59
	v_and_or_b32 v28, v27, s60, v0
	v_bfe_u32 v0, v29, 16, 1
	v_add3_u32 v0, v29, v0, s59
	v_bfe_u32 v27, v30, 16, 1
	v_lshrrev_b32_e32 v0, 16, v0
	v_add3_u32 v27, v30, v27, s59
	v_and_or_b32 v29, v27, s60, v0
	v_bfe_u32 v0, v31, 16, 1
	v_add3_u32 v0, v31, v0, s59
	v_bfe_u32 v27, v32, 16, 1
	v_lshrrev_b32_e32 v0, 16, v0
	v_add3_u32 v27, v32, v27, s59
	v_and_or_b32 v30, v27, s60, v0
	v_bfe_u32 v0, v33, 16, 1
	v_or_b32_e32 v32, s10, v163
	v_add3_u32 v0, v33, v0, s59
	v_bfe_u32 v27, v34, 16, 1
	v_ashrrev_i32_e32 v33, 31, v32
	v_lshrrev_b32_e32 v0, 16, v0
	v_add3_u32 v27, v34, v27, s59
	v_lshlrev_b64 v[32:33], 11, v[32:33]
	v_and_or_b32 v31, v27, s60, v0
	v_lshl_add_u64 v[16:17], v[16:17], 0, v[32:33]
	global_store_dwordx4 v[16:17], v[28:31], off sc0 sc1
	s_waitcnt lgkmcnt(0)
	s_branch .LBB0_100

; #define TR_TRY(CNT, NBLK, ...) if (r < (CNT)) { const int k0 = 64 * (r / (NBLK)), n0 = 32 * (r % (NBLK)); (void)k0; (void)n0; __VA_ARGS__; continue; } r -= (CNT);
; #define TR_TRY(CNT, NBLK, ...) if (r < (CNT)) { const int k0 = 64 * (r / (NBLK)), n0 = 32 * (r % (NBLK)); (void)k0; (void)n0; __VA_ARGS__; continue; } r -= (CNT);
; __device__ __forceinline__ void tr_item(const float* W, int N, int k0, int n0, bf16* WT, int Kd, int drow0, int dk0, LAS float* scr, int lane) {
;     ...
;         float wv[32]; const int n = n0 + (lane & 31); const float* wp = W + (size_t)(k0 + (lane >> 5)) * N + n;
; #pragma unroll
;         for (int i = 0; i < 32; ++i) wv[i] = (n < N) ? wp[(size_t)(2 * i) * N] : 0.f;
; #pragma unroll
;         for (int i = 0; i < 32; ++i) scr[(2 * i + (lane >> 5)) * 33 + (lane & 31)] = wv[i];
; __global__ void __launch_bounds__(NTHREADS, 2) mega_fwd(Args a_unused) {
;     ...
;                 TR_TRY(I_OUT, D / 32, tr_item(ap->in[20], D, k0, n0, Wout, D, n0, k0, scr, lane))
.LBB0_302:
	s_cmpk_gt_i32 s12, 0x57f
	s_mov_b64 s[6:7], -1
	s_cbranch_scc0 .LBB0_312
	s_cmpk_gt_u32 s12, 0xaff
	s_cbranch_scc0 .LBB0_309
	s_and_b32 s4, s11, 0x3e0
	v_or_b32_e32 v0, s4, v158
	s_cmpk_gt_u32 s12, 0x107f
	v_or_b32_e32 v22, s4, v160
	v_or_b32_e32 v21, s4, v161
	v_or_b32_e32 v20, s4, v162
	v_or_b32_e32 v19, s4, v163
	v_lshlrev_b32_e32 v8, 2, v0
	s_cbranch_scc0 .LBB0_306
	v_mov_b64_e32 v[24:25], s[8:9]
	global_load_dwordx2 v[24:25], v[24:25], off offset:160
	s_and_b32 s4, s14, 0x7fffffc0
	v_or_b32_e32 v0, s4, v159
	v_lshlrev_b64 v[26:27], 12, v[0:1]
	v_mov_b32_e32 v9, v1
	s_lshl_b32 s4, s4, 1
	s_mov_b64 s[6:7], 0
	s_waitcnt vmcnt(0) lgkmcnt(0)
	v_lshl_add_u64 v[24:25], v[24:25], 0, v[26:27]
	v_lshl_add_u64 v[24:25], v[24:25], 0, v[8:9]
	v_add_co_u32_e32 v26, vcc, 0x2000, v24
	s_nop 1
	v_addc_co_u32_e32 v27, vcc, 0, v25, vcc
	v_add_co_u32_e32 v28, vcc, 0x4000, v24
	s_nop 1
	v_addc_co_u32_e32 v29, vcc, 0, v25, vcc
	v_add_co_u32_e32 v30, vcc, 0x6000, v24
	s_nop 1
	v_addc_co_u32_e32 v31, vcc, 0, v25, vcc
	v_add_co_u32_e32 v32, vcc, 0x8000, v24
	s_nop 1
	v_addc_co_u32_e32 v33, vcc, 0, v25, vcc
	v_add_co_u32_e32 v34, vcc, 0xa000, v24
	s_nop 1
	v_addc_co_u32_e32 v35, vcc, 0, v25, vcc
	v_add_co_u32_e32 v36, vcc, 0xc000, v24
	s_nop 1
	v_addc_co_u32_e32 v37, vcc, 0, v25, vcc
	v_add_co_u32_e32 v38, vcc, 0xe000, v24
	s_nop 1
	v_addc_co_u32_e32 v39, vcc, 0, v25, vcc
	v_add_co_u32_e32 v40, vcc, 0x10000, v24
	global_load_dword v0, v[24:25], off nt
	global_load_dword v9, v[26:27], off nt
	global_load_dword v23, v[28:29], off nt
	global_load_dword v42, v[30:31], off nt
	global_load_dword v43, v[32:33], off nt
	global_load_dword v44, v[34:35], off nt
	global_load_dword v45, v[36:37], off nt
	global_load_dword v46, v[38:39], off nt
	v_addc_co_u32_e32 v41, vcc, 0, v25, vcc
	v_add_co_u32_e32 v26, vcc, 0x12000, v24
	s_nop 1
	v_addc_co_u32_e32 v27, vcc, 0, v25, vcc
	v_add_co_u32_e32 v28, vcc, 0x14000, v24
	s_nop 1
	v_addc_co_u32_e32 v29, vcc, 0, v25, vcc
	v_add_co_u32_e32 v30, vcc, 0x16000, v24
	s_nop 1
	v_addc_co_u32_e32 v31, vcc, 0, v25, vcc
	v_add_co_u32_e32 v32, vcc, 0x18000, v24
	s_nop 1
	v_addc_co_u32_e32 v33, vcc, 0, v25, vcc
	v_add_co_u32_e32 v34, vcc, 0x1a000, v24
	s_nop 1
	v_addc_co_u32_e32 v35, vcc, 0, v25, vcc
	v_add_co_u32_e32 v36, vcc, 0x1c000, v24
	s_nop 1
	v_addc_co_u32_e32 v37, vcc, 0, v25, vcc
	v_add_co_u32_e32 v38, vcc, 0x1e000, v24
	s_nop 1
	v_addc_co_u32_e32 v39, vcc, 0, v25, vcc
	global_load_dword v47, v[40:41], off nt
	global_load_dword v48, v[26:27], off nt
	global_load_dword v49, v[28:29], off nt
	global_load_dword v50, v[30:31], off nt
	global_load_dword v51, v[32:33], off nt
	global_load_dword v52, v[34:35], off nt
	global_load_dword v53, v[36:37], off nt
	global_load_dword v54, v[38:39], off nt
	v_add_co_u32_e32 v26, vcc, 0x20000, v24
	s_nop 1
	v_addc_co_u32_e32 v27, vcc, 0, v25, vcc
	v_add_co_u32_e32 v28, vcc, 0x22000, v24
	s_nop 1
	v_addc_co_u32_e32 v29, vcc, 0, v25, vcc
	v_add_co_u32_e32 v30, vcc, 0x24000, v24
	s_nop 1
	v_addc_co_u32_e32 v31, vcc, 0, v25, vcc
	v_add_co_u32_e32 v32, vcc, 0x26000, v24
	s_nop 1
	v_addc_co_u32_e32 v33, vcc, 0, v25, vcc
	v_add_co_u32_e32 v34, vcc, 0x28000, v24
	s_nop 1
	v_addc_co_u32_e32 v35, vcc, 0, v25, vcc
	v_add_co_u32_e32 v36, vcc, 0x2a000, v24
	s_nop 1
	v_addc_co_u32_e32 v37, vcc, 0, v25, vcc
	v_add_co_u32_e32 v38, vcc, 0x2c000, v24
	s_nop 1
	v_addc_co_u32_e32 v39, vcc, 0, v25, vcc
	v_add_co_u32_e32 v40, vcc, 0x2e000, v24
	s_nop 1
	v_addc_co_u32_e32 v41, vcc, 0, v25, vcc
	global_load_dword v55, v[26:27], off nt
	global_load_dword v56, v[28:29], off nt
	global_load_dword v57, v[30:31], off nt
	global_load_dword v58, v[32:33], off nt
	global_load_dword v59, v[34:35], off nt
	global_load_dword v60, v[36:37], off nt
	global_load_dword v61, v[38:39], off nt
	s_nop 0
	global_load_dword v40, v[40:41], off nt
	v_add_co_u32_e32 v26, vcc, 0x30000, v24
	s_nop 1
	v_addc_co_u32_e32 v27, vcc, 0, v25, vcc
	v_add_co_u32_e32 v28, vcc, 0x32000, v24
	s_nop 1
	v_addc_co_u32_e32 v29, vcc, 0, v25, vcc
	v_add_co_u32_e32 v30, vcc, 0x34000, v24
	s_nop 1
	v_addc_co_u32_e32 v31, vcc, 0, v25, vcc
	v_add_co_u32_e32 v32, vcc, 0x36000, v24
	s_nop 1
	v_addc_co_u32_e32 v33, vcc, 0, v25, vcc
	v_add_co_u32_e32 v34, vcc, 0x38000, v24
	s_nop 1
	v_addc_co_u32_e32 v35, vcc, 0, v25, vcc
	v_add_co_u32_e32 v36, vcc, 0x3a000, v24
	s_nop 1
	v_addc_co_u32_e32 v37, vcc, 0, v25, vcc
	v_add_co_u32_e32 v38, vcc, 0x3c000, v24
	s_nop 1
	v_addc_co_u32_e32 v39, vcc, 0, v25, vcc
	v_add_co_u32_e32 v24, vcc, 0x3e000, v24
	s_nop 1
	v_addc_co_u32_e32 v25, vcc, 0, v25, vcc
	global_load_dword v26, v[26:27], off nt
	s_nop 0
	global_load_dword v27, v[28:29], off nt
	s_nop 0
	global_load_dword v28, v[30:31], off nt
	global_load_dword v29, v[32:33], off nt
	s_nop 0
	global_load_dword v30, v[34:35], off nt
	global_load_dword v31, v[36:37], off nt
	global_load_dword v32, v[38:39], off nt
	s_nop 0
	global_load_dword v24, v[24:25], off nt
	s_waitcnt vmcnt(0) lgkmcnt(0)
	ds_write2_b32 v10, v0, v9 offset1:66
	ds_write2_b32 v10, v23, v42 offset0:132 offset1:198
	ds_write2_b32 v12, v43, v44 offset0:8 offset1:74
	ds_write2_b32 v12, v45, v46 offset0:140 offset1:206
	ds_write2_b32 v13, v47, v48 offset0:16 offset1:82
	ds_write2_b32 v13, v49, v50 offset0:148 offset1:214
	ds_write2_b32 v14, v51, v52 offset0:24 offset1:90
	ds_write2_b32 v14, v53, v54 offset0:156 offset1:222
	ds_write2_b32 v15, v55, v56 offset0:32 offset1:98
	ds_write2_b32 v15, v57, v58 offset0:164 offset1:230
	ds_write2_b32 v16, v59, v60 offset0:40 offset1:106
	ds_write2_b32 v16, v61, v40 offset0:172 offset1:238
	ds_write2_b32 v17, v26, v27 offset0:48 offset1:114
	ds_write2_b32 v17, v28, v29 offset0:180 offset1:246
	ds_write2_b32 v18, v30, v31 offset0:56 offset1:122
	ds_write2_b32 v18, v32, v24 offset0:188 offset1:254
	s_waitcnt lgkmcnt(0)
; #define LAS __attribute__((address_space(3)))
; #define LDS_WAIT() asm volatile("s_waitcnt lgkmcnt(0)" ::: "memory")
; __device__ __forceinline__ unsigned pk2(float lo, float hi) { return f2bf(lo) | (f2bf(hi) << 16); }
; __device__ __forceinline__ void tr_item(const float* W, int N, int k0, int n0, bf16* WT, int Kd, int drow0, int dk0, LAS float* scr, int lane) {
;     ...
;     LDS_WAIT();
;     const int c = lane & 7;
; #pragma unroll
;     for (int j = 0; j < 4; ++j) { const int n = (lane >> 3) + 8 * j; const LAS float* s = scr + (8 * c) * 33 + n;
;         v4u o; o.x = pk2(s[0 * 33], s[1 * 33]); o.y = pk2(s[2 * 33], s[3 * 33]); o.z = pk2(s[4 * 33], s[5 * 33]); o.w = pk2(s[6 * 33], s[7 * 33]);
;         *(v4u*)(WT + (size_t)(drow0 + n) * Kd + dk0 + 8 * c) = o; }
;     LDS_WAIT();
	ds_read_b32 v0, v11
	ds_read_b32 v9, v11 offset:132
	ds_read_b32 v23, v11 offset:264
	ds_read_b32 v25, v11 offset:396
	ds_read_b32 v26, v11 offset:528
	ds_read_b32 v27, v11 offset:660
	ds_read_b32 v30, v11 offset:792
	ds_read_b32 v31, v11 offset:924
	s_waitcnt lgkmcnt(7)
	v_bfe_u32 v24, v0, 16, 1
	v_add3_u32 v0, v0, v24, s21
	s_waitcnt lgkmcnt(6)
	v_bfe_u32 v24, v9, 16, 1
	v_lshrrev_b32_e32 v0, 16, v0
	v_add3_u32 v9, v9, v24, s21
	v_and_or_b32 v24, v9, s35, v0
	s_waitcnt lgkmcnt(5)
	v_bfe_u32 v0, v23, 16, 1
	v_add3_u32 v0, v23, v0, s21
	s_waitcnt lgkmcnt(4)
	v_bfe_u32 v9, v25, 16, 1
	v_lshrrev_b32_e32 v0, 16, v0
	v_add3_u32 v9, v25, v9, s21
	v_and_or_b32 v25, v9, s35, v0
	s_waitcnt lgkmcnt(3)
	v_bfe_u32 v0, v26, 16, 1
	v_add3_u32 v0, v26, v0, s21
	s_waitcnt lgkmcnt(2)
	v_bfe_u32 v9, v27, 16, 1
	v_lshrrev_b32_e32 v0, 16, v0
	v_add3_u32 v9, v27, v9, s21
	v_and_or_b32 v26, v9, s35, v0
	s_waitcnt lgkmcnt(1)
	v_bfe_u32 v0, v30, 16, 1
	v_add3_u32 v0, v30, v0, s21
	s_waitcnt lgkmcnt(0)
	v_bfe_u32 v9, v31, 16, 1
	v_lshrrev_b32_e32 v0, 16, v0
	v_add3_u32 v9, v31, v9, s21
	v_lshl_add_u64 v[28:29], v[2:3], 0, s[4:5]
	v_and_or_b32 v27, v9, s35, v0
	v_lshlrev_b32_e32 v0, 11, v22
	v_lshl_add_u64 v[30:31], v[28:29], 0, v[0:1]
	global_store_dwordx4 v[30:31], v[24:27], off sc0 sc1
	ds_read_b32 v0, v11 offset:32
	ds_read_b32 v9, v11 offset:164
	ds_read_b32 v23, v11 offset:296
	ds_read_b32 v25, v11 offset:428
	ds_read_b32 v26, v11 offset:560
	ds_read_b32 v27, v11 offset:692
	ds_read_b32 v30, v11 offset:824
	ds_read_b32 v31, v11 offset:956
	s_waitcnt lgkmcnt(0)
	v_bfe_u32 v24, v0, 16, 1
	v_add3_u32 v0, v0, v24, s21
	v_bfe_u32 v24, v9, 16, 1
	v_lshrrev_b32_e32 v0, 16, v0
	v_add3_u32 v9, v9, v24, s21
	v_and_or_b32 v24, v9, s35, v0
	v_bfe_u32 v0, v23, 16, 1
	v_add3_u32 v0, v23, v0, s21
	v_bfe_u32 v9, v25, 16, 1
	v_lshrrev_b32_e32 v0, 16, v0
	v_add3_u32 v9, v25, v9, s21
	v_and_or_b32 v25, v9, s35, v0
	v_bfe_u32 v0, v26, 16, 1
	v_add3_u32 v0, v26, v0, s21
	v_bfe_u32 v9, v27, 16, 1
	v_lshrrev_b32_e32 v0, 16, v0
	v_add3_u32 v9, v27, v9, s21
	v_and_or_b32 v26, v9, s35, v0
	v_bfe_u32 v0, v30, 16, 1
	v_add3_u32 v0, v30, v0, s21
	v_bfe_u32 v9, v31, 16, 1
	v_lshrrev_b32_e32 v0, 16, v0
	v_add3_u32 v9, v31, v9, s21
	v_and_or_b32 v27, v9, s35, v0
	v_lshlrev_b32_e32 v0, 11, v21
	v_lshl_add_u64 v[30:31], v[28:29], 0, v[0:1]
	global_store_dwordx4 v[30:31], v[24:27], off sc0 sc1
	ds_read_b32 v0, v11 offset:64
	ds_read_b32 v9, v11 offset:196
	ds_read_b32 v23, v11 offset:328
	ds_read_b32 v25, v11 offset:460
	ds_read_b32 v26, v11 offset:592
	ds_read_b32 v27, v11 offset:724
	ds_read_b32 v30, v11 offset:856
	ds_read_b32 v31, v11 offset:988
	s_waitcnt lgkmcnt(0)
	v_bfe_u32 v24, v0, 16, 1
	v_add3_u32 v0, v0, v24, s21
	v_bfe_u32 v24, v9, 16, 1
	v_lshrrev_b32_e32 v0, 16, v0
	v_add3_u32 v9, v9, v24, s21
	v_and_or_b32 v24, v9, s35, v0
	v_bfe_u32 v0, v23, 16, 1
	v_add3_u32 v0, v23, v0, s21
	v_bfe_u32 v9, v25, 16, 1
	v_lshrrev_b32_e32 v0, 16, v0
	v_add3_u32 v9, v25, v9, s21
	v_and_or_b32 v25, v9, s35, v0
	v_bfe_u32 v0, v26, 16, 1
	v_add3_u32 v0, v26, v0, s21
	v_bfe_u32 v9, v27, 16, 1
	v_lshrrev_b32_e32 v0, 16, v0
	v_add3_u32 v9, v27, v9, s21
	v_and_or_b32 v26, v9, s35, v0
	v_bfe_u32 v0, v30, 16, 1
	v_add3_u32 v0, v30, v0, s21
	v_bfe_u32 v9, v31, 16, 1
	v_lshrrev_b32_e32 v0, 16, v0
	v_add3_u32 v9, v31, v9, s21
	v_and_or_b32 v27, v9, s35, v0
	v_lshlrev_b32_e32 v0, 11, v20
	v_lshl_add_u64 v[30:31], v[28:29], 0, v[0:1]
	global_store_dwordx4 v[30:31], v[24:27], off sc0 sc1
	ds_read_b32 v0, v11 offset:96
	ds_read_b32 v9, v11 offset:228
	ds_read_b32 v23, v11 offset:360
	ds_read_b32 v25, v11 offset:492
	ds_read_b32 v26, v11 offset:624
	ds_read_b32 v27, v11 offset:756
	ds_read_b32 v30, v11 offset:888
	ds_read_b32 v31, v11 offset:1020
	s_waitcnt lgkmcnt(0)
	v_bfe_u32 v24, v0, 16, 1
	v_add3_u32 v0, v0, v24, s21
	v_bfe_u32 v24, v9, 16, 1
	v_lshrrev_b32_e32 v0, 16, v0
	v_add3_u32 v9, v9, v24, s21
	v_and_or_b32 v24, v9, s35, v0
	v_bfe_u32 v0, v23, 16, 1
	v_add3_u32 v0, v23, v0, s21
	v_bfe_u32 v9, v25, 16, 1
	v_lshrrev_b32_e32 v0, 16, v0
	v_add3_u32 v9, v25, v9, s21
	v_and_or_b32 v25, v9, s35, v0
	v_bfe_u32 v0, v26, 16, 1
	v_add3_u32 v0, v26, v0, s21
	v_bfe_u32 v9, v27, 16, 1
	v_lshrrev_b32_e32 v0, 16, v0
	v_add3_u32 v9, v27, v9, s21
	v_and_or_b32 v26, v9, s35, v0
	v_bfe_u32 v0, v30, 16, 1
	v_add3_u32 v0, v30, v0, s21
	v_bfe_u32 v9, v31, 16, 1
	v_lshrrev_b32_e32 v0, 16, v0
	v_add3_u32 v9, v31, v9, s21
	v_and_or_b32 v27, v9, s35, v0
	v_lshlrev_b32_e32 v0, 11, v19
	v_lshl_add_u64 v[28:29], v[28:29], 0, v[0:1]
	global_store_dwordx4 v[28:29], v[24:27], off sc0 sc1
	s_waitcnt lgkmcnt(0)
; #define TR_TRY(CNT, NBLK, ...) if (r < (CNT)) { const int k0 = 64 * (r / (NBLK)), n0 = 32 * (r % (NBLK)); (void)k0; (void)n0; __VA_ARGS__; continue; } r -= (CNT);
; #define TR_TRY(CNT, NBLK, ...) if (r < (CNT)) { const int k0 = 64 * (r / (NBLK)), n0 = 32 * (r % (NBLK)); (void)k0; (void)n0; __VA_ARGS__; continue; } r -= (CNT);
; __device__ __forceinline__ void tr_item(const float* W, int N, int k0, int n0, bf16* WT, int Kd, int drow0, int dk0, LAS float* scr, int lane) {
;     ...
;         float wv[32]; const int n = n0 + (lane & 31); const float* wp = W + (size_t)(k0 + (lane >> 5)) * N + n;
; #pragma unroll
;         for (int i = 0; i < 32; ++i) wv[i] = (n < N) ? wp[(size_t)(2 * i) * N] : 0.f;
; #pragma unroll
;         for (int i = 0; i < 32; ++i) scr[(2 * i + (lane >> 5)) * 33 + (lane & 31)] = wv[i];
; __global__ void __launch_bounds__(NTHREADS, 2) mega_fwd(Args a_unused) {
;     ...
;                 TR_TRY(I_WD, D / 32, tr_item(ap->in[23], D, k0, n0, Wd2, FF, n0, k0, scr, lane))
.LBB0_306:
	s_andn2_b64 vcc, exec, s[6:7]
	s_cbranch_vccnz .LBB0_308
	v_mov_b64_e32 v[24:25], s[8:9]
	global_load_dwordx2 v[24:25], v[24:25], off offset:184
	s_add_i32 s4, s14, 0xb00
	s_and_b32 s4, s4, 0x7fffffc0
	v_or_b32_e32 v0, s4, v159
	v_lshlrev_b64 v[26:27], 12, v[0:1]
	v_mov_b32_e32 v9, v1
	s_lshl_b32 s4, s4, 1
	s_waitcnt vmcnt(0) lgkmcnt(0)
	v_lshl_add_u64 v[24:25], v[24:25], 0, v[26:27]
	v_lshl_add_u64 v[8:9], v[24:25], 0, v[8:9]
	v_add_co_u32_e32 v24, vcc, 0x2000, v8
	s_nop 1
	v_addc_co_u32_e32 v25, vcc, 0, v9, vcc
	v_add_co_u32_e32 v26, vcc, 0x4000, v8
	s_nop 1
	v_addc_co_u32_e32 v27, vcc, 0, v9, vcc
	v_add_co_u32_e32 v28, vcc, 0x6000, v8
	s_nop 1
	v_addc_co_u32_e32 v29, vcc, 0, v9, vcc
	v_add_co_u32_e32 v30, vcc, 0x8000, v8
	s_nop 1
	v_addc_co_u32_e32 v31, vcc, 0, v9, vcc
	v_add_co_u32_e32 v32, vcc, 0xa000, v8
	s_nop 1
	v_addc_co_u32_e32 v33, vcc, 0, v9, vcc
	v_add_co_u32_e32 v34, vcc, 0xc000, v8
	s_nop 1
	v_addc_co_u32_e32 v35, vcc, 0, v9, vcc
	v_add_co_u32_e32 v36, vcc, 0xe000, v8
	s_nop 1
	v_addc_co_u32_e32 v37, vcc, 0, v9, vcc
	v_add_co_u32_e32 v38, vcc, 0x10000, v8
	global_load_dword v0, v[8:9], off nt
	global_load_dword v23, v[24:25], off nt
	global_load_dword v40, v[26:27], off nt
	global_load_dword v41, v[28:29], off nt
	global_load_dword v42, v[30:31], off nt
	global_load_dword v43, v[32:33], off nt
	global_load_dword v44, v[34:35], off nt
	global_load_dword v45, v[36:37], off nt
	v_addc_co_u32_e32 v39, vcc, 0, v9, vcc
	v_add_co_u32_e32 v24, vcc, 0x12000, v8
	s_nop 1
	v_addc_co_u32_e32 v25, vcc, 0, v9, vcc
	v_add_co_u32_e32 v26, vcc, 0x14000, v8
	s_nop 1
	v_addc_co_u32_e32 v27, vcc, 0, v9, vcc
	v_add_co_u32_e32 v28, vcc, 0x16000, v8
	s_nop 1
	v_addc_co_u32_e32 v29, vcc, 0, v9, vcc
	v_add_co_u32_e32 v30, vcc, 0x18000, v8
	s_nop 1
	v_addc_co_u32_e32 v31, vcc, 0, v9, vcc
	v_add_co_u32_e32 v32, vcc, 0x1a000, v8
	s_nop 1
	v_addc_co_u32_e32 v33, vcc, 0, v9, vcc
	v_add_co_u32_e32 v34, vcc, 0x1c000, v8
	s_nop 1
	v_addc_co_u32_e32 v35, vcc, 0, v9, vcc
	v_add_co_u32_e32 v36, vcc, 0x1e000, v8
	s_nop 1
	v_addc_co_u32_e32 v37, vcc, 0, v9, vcc
	global_load_dword v46, v[38:39], off nt
	global_load_dword v47, v[24:25], off nt
	global_load_dword v48, v[26:27], off nt
	global_load_dword v49, v[28:29], off nt
	global_load_dword v50, v[30:31], off nt
	global_load_dword v51, v[32:33], off nt
	global_load_dword v52, v[34:35], off nt
	global_load_dword v53, v[36:37], off nt
	v_add_co_u32_e32 v24, vcc, 0x20000, v8
	s_nop 1
	v_addc_co_u32_e32 v25, vcc, 0, v9, vcc
	v_add_co_u32_e32 v26, vcc, 0x22000, v8
	s_nop 1
	v_addc_co_u32_e32 v27, vcc, 0, v9, vcc
	v_add_co_u32_e32 v28, vcc, 0x24000, v8
	s_nop 1
	v_addc_co_u32_e32 v29, vcc, 0, v9, vcc
	v_add_co_u32_e32 v30, vcc, 0x26000, v8
	s_nop 1
	v_addc_co_u32_e32 v31, vcc, 0, v9, vcc
	v_add_co_u32_e32 v32, vcc, 0x28000, v8
	s_nop 1
	v_addc_co_u32_e32 v33, vcc, 0, v9, vcc
	v_add_co_u32_e32 v34, vcc, 0x2a000, v8
	s_nop 1
	v_addc_co_u32_e32 v35, vcc, 0, v9, vcc
	v_add_co_u32_e32 v36, vcc, 0x2c000, v8
	s_nop 1
	v_addc_co_u32_e32 v37, vcc, 0, v9, vcc
	v_add_co_u32_e32 v38, vcc, 0x2e000, v8
	s_nop 1
	v_addc_co_u32_e32 v39, vcc, 0, v9, vcc
	global_load_dword v54, v[24:25], off nt
	global_load_dword v55, v[26:27], off nt
	global_load_dword v56, v[28:29], off nt
	global_load_dword v57, v[30:31], off nt
	global_load_dword v58, v[32:33], off nt
	global_load_dword v59, v[34:35], off nt
	global_load_dword v60, v[36:37], off nt
	s_nop 0
	global_load_dword v38, v[38:39], off nt
	v_add_co_u32_e32 v24, vcc, 0x30000, v8
	s_nop 1
	v_addc_co_u32_e32 v25, vcc, 0, v9, vcc
	v_add_co_u32_e32 v26, vcc, 0x32000, v8
	s_nop 1
	v_addc_co_u32_e32 v27, vcc, 0, v9, vcc
	v_add_co_u32_e32 v28, vcc, 0x34000, v8
	s_nop 1
	v_addc_co_u32_e32 v29, vcc, 0, v9, vcc
	v_add_co_u32_e32 v30, vcc, 0x36000, v8
	s_nop 1
	v_addc_co_u32_e32 v31, vcc, 0, v9, vcc
	v_add_co_u32_e32 v32, vcc, 0x38000, v8
	s_nop 1
	v_addc_co_u32_e32 v33, vcc, 0, v9, vcc
	v_add_co_u32_e32 v34, vcc, 0x3a000, v8
	s_nop 1
	v_addc_co_u32_e32 v35, vcc, 0, v9, vcc
	v_add_co_u32_e32 v36, vcc, 0x3c000, v8
	s_nop 1
	v_addc_co_u32_e32 v37, vcc, 0, v9, vcc
	v_add_co_u32_e32 v8, vcc, 0x3e000, v8
	s_nop 1
	v_addc_co_u32_e32 v9, vcc, 0, v9, vcc
	global_load_dword v24, v[24:25], off nt
	s_nop 0
	global_load_dword v25, v[26:27], off nt
	s_nop 0
	global_load_dword v26, v[28:29], off nt
	global_load_dword v27, v[30:31], off nt
	s_nop 0
	global_load_dword v28, v[32:33], off nt
	global_load_dword v29, v[34:35], off nt
	global_load_dword v30, v[36:37], off nt
	s_nop 0
	global_load_dword v8, v[8:9], off nt
	s_waitcnt vmcnt(0) lgkmcnt(0)
	ds_write2_b32 v10, v0, v23 offset1:66
	ds_write2_b32 v10, v40, v41 offset0:132 offset1:198
	ds_write2_b32 v12, v42, v43 offset0:8 offset1:74
	ds_write2_b32 v12, v44, v45 offset0:140 offset1:206
	ds_write2_b32 v13, v46, v47 offset0:16 offset1:82
	ds_write2_b32 v13, v48, v49 offset0:148 offset1:214
	ds_write2_b32 v14, v50, v51 offset0:24 offset1:90
	ds_write2_b32 v14, v52, v53 offset0:156 offset1:222
	ds_write2_b32 v15, v54, v55 offset0:32 offset1:98
	ds_write2_b32 v15, v56, v57 offset0:164 offset1:230
	ds_write2_b32 v16, v58, v59 offset0:40 offset1:106
	ds_write2_b32 v16, v60, v38 offset0:172 offset1:238
	ds_write2_b32 v17, v24, v25 offset0:48 offset1:114
	ds_write2_b32 v17, v26, v27 offset0:180 offset1:246
	ds_write2_b32 v18, v28, v29 offset0:56 offset1:122
	ds_write2_b32 v18, v30, v8 offset0:188 offset1:254
	s_waitcnt lgkmcnt(0)
; #define LAS __attribute__((address_space(3)))
; #define LDS_WAIT() asm volatile("s_waitcnt lgkmcnt(0)" ::: "memory")
; __device__ __forceinline__ unsigned pk2(float lo, float hi) { return f2bf(lo) | (f2bf(hi) << 16); }
; __device__ __forceinline__ void tr_item(const float* W, int N, int k0, int n0, bf16* WT, int Kd, int drow0, int dk0, LAS float* scr, int lane) {
;     ...
;     LDS_WAIT();
;     const int c = lane & 7;
; #pragma unroll
;     for (int j = 0; j < 4; ++j) { const int n = (lane >> 3) + 8 * j; const LAS float* s = scr + (8 * c) * 33 + n;
;         v4u o; o.x = pk2(s[0 * 33], s[1 * 33]); o.y = pk2(s[2 * 33], s[3 * 33]); o.z = pk2(s[4 * 33], s[5 * 33]); o.w = pk2(s[6 * 33], s[7 * 33]);
;         *(v4u*)(WT + (size_t)(drow0 + n) * Kd + dk0 + 8 * c) = o; }
;     LDS_WAIT();
	ds_read_b32 v0, v11
	ds_read_b32 v23, v11 offset:132
	ds_read_b32 v25, v11 offset:264
	ds_read_b32 v26, v11 offset:396
	ds_read_b32 v27, v11 offset:528
	ds_read_b32 v28, v11 offset:660
	ds_read_b32 v29, v11 offset:792
	ds_read_b32 v30, v11 offset:924
	s_waitcnt lgkmcnt(7)
	v_bfe_u32 v24, v0, 16, 1
	v_add3_u32 v0, v0, v24, s21
	s_waitcnt lgkmcnt(6)
	v_bfe_u32 v24, v23, 16, 1
	v_lshrrev_b32_e32 v0, 16, v0
	v_add3_u32 v23, v23, v24, s21
	v_and_or_b32 v24, v23, s35, v0
	s_waitcnt lgkmcnt(5)
	v_bfe_u32 v0, v25, 16, 1
	v_add3_u32 v0, v25, v0, s21
	s_waitcnt lgkmcnt(4)
	v_bfe_u32 v23, v26, 16, 1
	v_lshrrev_b32_e32 v0, 16, v0
	v_add3_u32 v23, v26, v23, s21
	v_and_or_b32 v25, v23, s35, v0
	s_waitcnt lgkmcnt(3)
	v_bfe_u32 v0, v27, 16, 1
	v_add3_u32 v0, v27, v0, s21
	s_waitcnt lgkmcnt(2)
	v_bfe_u32 v23, v28, 16, 1
	v_lshrrev_b32_e32 v0, 16, v0
	v_add3_u32 v23, v28, v23, s21
	v_and_or_b32 v26, v23, s35, v0
	s_waitcnt lgkmcnt(1)
	v_bfe_u32 v0, v29, 16, 1
	v_add3_u32 v0, v29, v0, s21
	s_waitcnt lgkmcnt(0)
	v_bfe_u32 v23, v30, 16, 1
	v_lshrrev_b32_e32 v0, 16, v0
	v_add3_u32 v23, v30, v23, s21
	v_and_or_b32 v27, v23, s35, v0
	v_mul_u32_u24_e32 v0, 0xb00, v22
	v_lshl_add_u64 v[8:9], v[4:5], 0, s[4:5]
	v_lshlrev_b32_e32 v0, 1, v0
	v_lshl_add_u64 v[22:23], v[8:9], 0, v[0:1]
	global_store_dwordx4 v[22:23], v[24:27], off sc0 sc1
	ds_read_b32 v0, v11 offset:32
	ds_read_b32 v22, v11 offset:164
	ds_read_b32 v23, v11 offset:296
	ds_read_b32 v24, v11 offset:428
	ds_read_b32 v25, v11 offset:560
	ds_read_b32 v26, v11 offset:692
	ds_read_b32 v27, v11 offset:824
	ds_read_b32 v28, v11 offset:956
	s_waitcnt lgkmcnt(0)
	v_bfe_u32 v29, v0, 16, 1
	v_add3_u32 v0, v0, v29, s21
	v_bfe_u32 v29, v22, 16, 1
	v_lshrrev_b32_e32 v0, 16, v0
	v_add3_u32 v22, v22, v29, s21
	v_and_or_b32 v22, v22, s35, v0
	v_bfe_u32 v0, v23, 16, 1
	v_add3_u32 v0, v23, v0, s21
	v_bfe_u32 v23, v24, 16, 1
	v_lshrrev_b32_e32 v0, 16, v0
	v_add3_u32 v23, v24, v23, s21
	v_and_or_b32 v23, v23, s35, v0
	v_bfe_u32 v0, v25, 16, 1
	v_add3_u32 v0, v25, v0, s21
	v_bfe_u32 v24, v26, 16, 1
	v_lshrrev_b32_e32 v0, 16, v0
	v_add3_u32 v24, v26, v24, s21
	v_and_or_b32 v24, v24, s35, v0
	v_bfe_u32 v0, v27, 16, 1
	v_add3_u32 v0, v27, v0, s21
	v_bfe_u32 v25, v28, 16, 1
	v_lshrrev_b32_e32 v0, 16, v0
	v_add3_u32 v25, v28, v25, s21
	v_and_or_b32 v25, v25, s35, v0
	v_mul_u32_u24_e32 v0, 0xb00, v21
	v_lshlrev_b32_e32 v0, 1, v0
	v_lshl_add_u64 v[26:27], v[8:9], 0, v[0:1]
	global_store_dwordx4 v[26:27], v[22:25], off sc0 sc1
	ds_read_b32 v0, v11 offset:64
	ds_read_b32 v21, v11 offset:196
	ds_read_b32 v23, v11 offset:328
	ds_read_b32 v24, v11 offset:460
	ds_read_b32 v25, v11 offset:592
	ds_read_b32 v26, v11 offset:724
	ds_read_b32 v27, v11 offset:856
	ds_read_b32 v28, v11 offset:988
	s_waitcnt lgkmcnt(0)
	v_bfe_u32 v22, v0, 16, 1
	v_add3_u32 v0, v0, v22, s21
	v_bfe_u32 v22, v21, 16, 1
	v_lshrrev_b32_e32 v0, 16, v0
	v_add3_u32 v21, v21, v22, s21
	v_and_or_b32 v22, v21, s35, v0
	v_bfe_u32 v0, v23, 16, 1
	v_add3_u32 v0, v23, v0, s21
	v_bfe_u32 v21, v24, 16, 1
	v_lshrrev_b32_e32 v0, 16, v0
	v_add3_u32 v21, v24, v21, s21
	v_and_or_b32 v23, v21, s35, v0
	v_bfe_u32 v0, v25, 16, 1
	v_add3_u32 v0, v25, v0, s21
	v_bfe_u32 v21, v26, 16, 1
	v_lshrrev_b32_e32 v0, 16, v0
	v_add3_u32 v21, v26, v21, s21
	v_and_or_b32 v24, v21, s35, v0
	v_bfe_u32 v0, v27, 16, 1
	v_add3_u32 v0, v27, v0, s21
	v_bfe_u32 v21, v28, 16, 1
	v_lshrrev_b32_e32 v0, 16, v0
	v_add3_u32 v21, v28, v21, s21
	v_and_or_b32 v25, v21, s35, v0
	v_mul_u32_u24_e32 v0, 0xb00, v20
	v_lshlrev_b32_e32 v0, 1, v0
	v_lshl_add_u64 v[20:21], v[8:9], 0, v[0:1]
	global_store_dwordx4 v[20:21], v[22:25], off sc0 sc1
	ds_read_b32 v0, v11 offset:96
	ds_read_b32 v20, v11 offset:228
	ds_read_b32 v21, v11 offset:360
	ds_read_b32 v22, v11 offset:492
	ds_read_b32 v23, v11 offset:624
	ds_read_b32 v24, v11 offset:756
	ds_read_b32 v25, v11 offset:888
	ds_read_b32 v26, v11 offset:1020
	s_waitcnt lgkmcnt(0)
	v_bfe_u32 v27, v0, 16, 1
	v_add3_u32 v0, v0, v27, s21
	v_bfe_u32 v27, v20, 16, 1
	v_lshrrev_b32_e32 v0, 16, v0
	v_add3_u32 v20, v20, v27, s21
	v_and_or_b32 v20, v20, s35, v0
	v_bfe_u32 v0, v21, 16, 1
	v_add3_u32 v0, v21, v0, s21
	v_bfe_u32 v21, v22, 16, 1
	v_lshrrev_b32_e32 v0, 16, v0
	v_add3_u32 v21, v22, v21, s21
	v_and_or_b32 v21, v21, s35, v0
	v_bfe_u32 v0, v23, 16, 1
	v_add3_u32 v0, v23, v0, s21
	v_bfe_u32 v22, v24, 16, 1
	v_lshrrev_b32_e32 v0, 16, v0
	v_add3_u32 v22, v24, v22, s21
	v_and_or_b32 v22, v22, s35, v0
	v_bfe_u32 v0, v25, 16, 1
	v_add3_u32 v0, v25, v0, s21
	v_bfe_u32 v23, v26, 16, 1
	v_lshrrev_b32_e32 v0, 16, v0
	v_add3_u32 v23, v26, v23, s21
	v_and_or_b32 v23, v23, s35, v0
	v_mul_u32_u24_e32 v0, 0xb00, v19
	v_lshlrev_b32_e32 v0, 1, v0
	v_lshl_add_u64 v[8:9], v[8:9], 0, v[0:1]
	global_store_dwordx4 v[8:9], v[20:23], off sc0 sc1
	s_waitcnt lgkmcnt(0)

; #define TR_TRY(CNT, NBLK, ...) if (r < (CNT)) { const int k0 = 64 * (r / (NBLK)), n0 = 32 * (r % (NBLK)); (void)k0; (void)n0; __VA_ARGS__; continue; } r -= (CNT);
; #define TR_TRY(CNT, NBLK, ...) if (r < (CNT)) { const int k0 = 64 * (r / (NBLK)), n0 = 32 * (r % (NBLK)); (void)k0; (void)n0; __VA_ARGS__; continue; } r -= (CNT);
; __device__ __forceinline__ void tr_item(const float* W, int N, int k0, int n0, bf16* WT, int Kd, int drow0, int dk0, LAS float* scr, int lane) {
;     ...
;         float wv[32]; const int n = n0 + (lane & 31); const float* wp = W + (size_t)(k0 + (lane >> 5)) * N + n;
; #pragma unroll
;         for (int i = 0; i < 32; ++i) wv[i] = (n < N) ? wp[(size_t)(2 * i) * N] : 0.f;
; #pragma unroll
;         for (int i = 0; i < 32; ++i) scr[(2 * i + (lane >> 5)) * 33 + (lane & 31)] = wv[i];
; __global__ void __launch_bounds__(NTHREADS, 2) mega_fwd(Args a_unused) {
;     ...
;                 TR_TRY(I_GU, FF / 32, tr_item(ap->in[22], FF, k0, n0, Wgu2, D, (n0 / 128) * 256 + 128 + (n0 % 128), k0, scr, lane))
.LBB0_309:
	s_andn2_b64 vcc, exec, s[6:7]
	s_cbranch_vccnz .LBB0_311
	v_mov_b64_e32 v[8:9], s[8:9]
	global_load_dwordx2 v[8:9], v[8:9], off offset:176
	s_add_i32 s6, s12, 0xfa80
	s_and_b32 s4, s6, 0xffff
	s_mul_i32 s4, s4, 0xba2f
	s_lshr_b32 s7, s4, 22
	s_lshr_b32 s4, s4, 16
	s_mulk_i32 s7, 0x58
	s_and_b32 s4, s4, 0xffc0
	s_sub_i32 s6, s6, s7
	v_or_b32_e32 v0, s4, v159
	s_and_b32 s6, s6, 0xffff
	v_mul_u32_u24_e32 v0, 0xb00, v0
	s_lshl_b32 s7, s6, 5
	v_lshlrev_b32_e32 v0, 2, v0
	v_or_b32_e32 v19, s7, v158
	s_lshl_b32 s6, s6, 6
	s_and_b32 s6, s6, 0x1f00
	s_and_b32 s7, s7, 0x60
	s_or_b32 s6, s7, s6
	s_bitset1_b32 s6, 7
	s_lshl_b32 s4, s4, 1
	s_waitcnt vmcnt(0) lgkmcnt(0)
	v_lshl_add_u64 v[8:9], v[8:9], 0, v[0:1]
	v_lshlrev_b32_e32 v0, 2, v19
	v_lshl_add_u64 v[8:9], v[8:9], 0, v[0:1]
	v_add_co_u32_e32 v20, vcc, s38, v8
	s_nop 1
	v_addc_co_u32_e32 v21, vcc, 0, v9, vcc
	v_add_co_u32_e32 v22, vcc, s39, v8
	s_nop 1
	v_addc_co_u32_e32 v23, vcc, 0, v9, vcc
	v_add_co_u32_e32 v24, vcc, s16, v8
	s_nop 1
	v_addc_co_u32_e32 v25, vcc, 0, v9, vcc
	v_add_co_u32_e32 v26, vcc, s17, v8
	s_nop 1
	v_addc_co_u32_e32 v27, vcc, 0, v9, vcc
	v_add_co_u32_e32 v28, vcc, s40, v8
	s_nop 1
	v_addc_co_u32_e32 v29, vcc, 0, v9, vcc
	v_add_co_u32_e32 v30, vcc, s41, v8
	s_nop 1
	v_addc_co_u32_e32 v31, vcc, 0, v9, vcc
	v_add_co_u32_e32 v32, vcc, s18, v8
	s_nop 1
	v_addc_co_u32_e32 v33, vcc, 0, v9, vcc
	v_add_co_u32_e32 v34, vcc, s19, v8
	global_load_dword v0, v[8:9], off nt
	global_load_dword v19, v[20:21], off offset:2048 nt
	global_load_dword v48, v[22:23], off nt
	global_load_dword v49, v[24:25], off offset:2048 nt
	global_load_dword v50, v[26:27], off nt
	global_load_dword v51, v[28:29], off offset:2048 nt
	global_load_dword v52, v[30:31], off nt
	global_load_dword v53, v[32:33], off offset:2048 nt
	v_addc_co_u32_e32 v35, vcc, 0, v9, vcc
	v_add_co_u32_e32 v36, vcc, s42, v8
	s_nop 1
	v_addc_co_u32_e32 v37, vcc, 0, v9, vcc
	v_add_co_u32_e32 v38, vcc, s43, v8
	s_nop 1
	v_addc_co_u32_e32 v39, vcc, 0, v9, vcc
	v_add_co_u32_e32 v40, vcc, s20, v8
	s_nop 1
	v_addc_co_u32_e32 v41, vcc, 0, v9, vcc
	v_add_co_u32_e32 v42, vcc, s44, v8
	s_nop 1
	v_addc_co_u32_e32 v43, vcc, 0, v9, vcc
	v_add_co_u32_e32 v44, vcc, s45, v8
	s_nop 1
	v_addc_co_u32_e32 v45, vcc, 0, v9, vcc
	v_add_co_u32_e32 v46, vcc, s46, v8
	s_nop 1
	v_addc_co_u32_e32 v47, vcc, 0, v9, vcc
	v_add_co_u32_e32 v20, vcc, s47, v8
	s_nop 1
	v_addc_co_u32_e32 v21, vcc, 0, v9, vcc
	global_load_dword v54, v[34:35], off nt
	s_nop 0
	global_load_dword v36, v[36:37], off offset:2048 nt
	s_nop 0
	global_load_dword v37, v[38:39], off nt
	s_nop 0
	global_load_dword v38, v[40:41], off offset:2048 nt
	global_load_dword v39, v[42:43], off nt
	s_nop 0
	global_load_dword v40, v[44:45], off offset:2048 nt
	global_load_dword v41, v[46:47], off nt
	global_load_dword v42, v[20:21], off offset:2048 nt
	v_add_co_u32_e32 v20, vcc, s48, v8
	s_nop 1
	v_addc_co_u32_e32 v21, vcc, 0, v9, vcc
	v_add_co_u32_e32 v22, vcc, s49, v8
	s_nop 1
	v_addc_co_u32_e32 v23, vcc, 0, v9, vcc
	v_add_co_u32_e32 v24, vcc, s50, v8
	s_nop 1
	v_addc_co_u32_e32 v25, vcc, 0, v9, vcc
	v_add_co_u32_e32 v26, vcc, s51, v8
	s_nop 1
	v_addc_co_u32_e32 v27, vcc, 0, v9, vcc
	v_add_co_u32_e32 v28, vcc, s52, v8
	s_nop 1
	v_addc_co_u32_e32 v29, vcc, 0, v9, vcc
	v_add_co_u32_e32 v30, vcc, s53, v8
	s_nop 1
	v_addc_co_u32_e32 v31, vcc, 0, v9, vcc
	v_add_co_u32_e32 v32, vcc, s54, v8
	s_nop 1
	v_addc_co_u32_e32 v33, vcc, 0, v9, vcc
	v_add_co_u32_e32 v34, vcc, s55, v8
	s_nop 1
	v_addc_co_u32_e32 v35, vcc, 0, v9, vcc
	global_load_dword v43, v[20:21], off nt
	global_load_dword v44, v[22:23], off offset:2048 nt
	global_load_dword v45, v[24:25], off nt
	global_load_dword v46, v[26:27], off offset:2048 nt
	global_load_dword v47, v[28:29], off nt
	global_load_dword v55, v[30:31], off offset:2048 nt
	global_load_dword v56, v[32:33], off nt
	s_nop 0
	global_load_dword v34, v[34:35], off offset:2048 nt
	v_add_co_u32_e32 v20, vcc, s56, v8
	s_nop 1
	v_addc_co_u32_e32 v21, vcc, 0, v9, vcc
	v_add_co_u32_e32 v22, vcc, s57, v8
	s_nop 1
	v_addc_co_u32_e32 v23, vcc, 0, v9, vcc
	v_add_co_u32_e32 v24, vcc, s58, v8
	s_nop 1
	v_addc_co_u32_e32 v25, vcc, 0, v9, vcc
	v_add_co_u32_e32 v26, vcc, s59, v8
	s_nop 1
	v_addc_co_u32_e32 v27, vcc, 0, v9, vcc
	v_add_co_u32_e32 v28, vcc, s60, v8
	s_nop 1
	v_addc_co_u32_e32 v29, vcc, 0, v9, vcc
	v_add_co_u32_e32 v30, vcc, s61, v8
	s_nop 1
	v_addc_co_u32_e32 v31, vcc, 0, v9, vcc
	v_add_co_u32_e32 v32, vcc, s62, v8
	s_nop 1
	v_addc_co_u32_e32 v33, vcc, 0, v9, vcc
	v_add_co_u32_e32 v8, vcc, s63, v8
	s_nop 1
	v_addc_co_u32_e32 v9, vcc, 0, v9, vcc
	global_load_dword v20, v[20:21], off nt
	s_nop 0
	global_load_dword v21, v[22:23], off offset:2048 nt
	s_nop 0
	global_load_dword v22, v[24:25], off nt
	global_load_dword v23, v[26:27], off offset:2048 nt
	s_nop 0
	global_load_dword v24, v[28:29], off nt
	global_load_dword v25, v[30:31], off offset:2048 nt
	global_load_dword v26, v[32:33], off nt
	s_nop 0
	global_load_dword v8, v[8:9], off offset:2048 nt
	s_waitcnt vmcnt(0) lgkmcnt(0)
; #define LAS __attribute__((address_space(3)))
; #define LDS_WAIT() asm volatile("s_waitcnt lgkmcnt(0)" ::: "memory")
; __device__ __forceinline__ unsigned pk2(float lo, float hi) { return f2bf(lo) | (f2bf(hi) << 16); }
; __device__ __forceinline__ void tr_item(const float* W, int N, int k0, int n0, bf16* WT, int Kd, int drow0, int dk0, LAS float* scr, int lane) {
;     ...
;         for (int i = 0; i < 32; ++i) scr[(2 * i + (lane >> 5)) * 33 + (lane & 31)] = wv[i];
;     }
;     LDS_WAIT();
;     const int c = lane & 7;
; #pragma unroll
;     for (int j = 0; j < 4; ++j) { const int n = (lane >> 3) + 8 * j; const LAS float* s = scr + (8 * c) * 33 + n;
;         v4u o; o.x = pk2(s[0 * 33], s[1 * 33]); o.y = pk2(s[2 * 33], s[3 * 33]); o.z = pk2(s[4 * 33], s[5 * 33]); o.w = pk2(s[6 * 33], s[7 * 33]);
;         *(v4u*)(WT + (size_t)(drow0 + n) * Kd + dk0 + 8 * c) = o; }
;     LDS_WAIT();
	ds_write2_b32 v10, v0, v19 offset1:66
	ds_write2_b32 v10, v48, v49 offset0:132 offset1:198
	ds_write2_b32 v12, v50, v51 offset0:8 offset1:74
	ds_write2_b32 v12, v52, v53 offset0:140 offset1:206
	ds_write2_b32 v13, v54, v36 offset0:16 offset1:82
	ds_write2_b32 v13, v37, v38 offset0:148 offset1:214
	ds_write2_b32 v14, v39, v40 offset0:24 offset1:90
	ds_write2_b32 v14, v41, v42 offset0:156 offset1:222
	ds_write2_b32 v15, v43, v44 offset0:32 offset1:98
	ds_write2_b32 v15, v45, v46 offset0:164 offset1:230
	ds_write2_b32 v16, v47, v55 offset0:40 offset1:106
	ds_write2_b32 v16, v56, v34 offset0:172 offset1:238
	ds_write2_b32 v17, v20, v21 offset0:48 offset1:114
	ds_write2_b32 v17, v22, v23 offset0:180 offset1:246
	ds_write2_b32 v18, v24, v25 offset0:56 offset1:122
	ds_write2_b32 v18, v26, v8 offset0:188 offset1:254
	s_waitcnt lgkmcnt(0)
	ds_read_b32 v0, v11
	ds_read_b32 v19, v11 offset:132
	ds_read_b32 v21, v11 offset:264
	ds_read_b32 v22, v11 offset:396
	ds_read_b32 v23, v11 offset:528
	ds_read_b32 v24, v11 offset:660
	ds_read_b32 v25, v11 offset:792
	ds_read_b32 v26, v11 offset:924
	s_waitcnt lgkmcnt(7)
	v_bfe_u32 v20, v0, 16, 1
	v_add3_u32 v0, v0, v20, s21
	s_waitcnt lgkmcnt(6)
	v_bfe_u32 v20, v19, 16, 1
	v_lshrrev_b32_e32 v0, 16, v0
	v_add3_u32 v19, v19, v20, s21
	v_and_or_b32 v20, v19, s35, v0
	s_waitcnt lgkmcnt(5)
	v_bfe_u32 v0, v21, 16, 1
	v_add3_u32 v0, v21, v0, s21
	s_waitcnt lgkmcnt(4)
	v_bfe_u32 v19, v22, 16, 1
	v_lshrrev_b32_e32 v0, 16, v0
	v_add3_u32 v19, v22, v19, s21
	v_and_or_b32 v21, v19, s35, v0
	s_waitcnt lgkmcnt(3)
	v_bfe_u32 v0, v23, 16, 1
	v_add3_u32 v0, v23, v0, s21
	s_waitcnt lgkmcnt(2)
	v_bfe_u32 v19, v24, 16, 1
	v_lshrrev_b32_e32 v0, 16, v0
	v_add3_u32 v19, v24, v19, s21
	v_and_or_b32 v22, v19, s35, v0
	s_waitcnt lgkmcnt(1)
	v_bfe_u32 v0, v25, 16, 1
	v_add3_u32 v0, v25, v0, s21
	s_waitcnt lgkmcnt(0)
	v_bfe_u32 v19, v26, 16, 1
	v_lshrrev_b32_e32 v0, 16, v0
	v_add3_u32 v19, v26, v19, s21
	v_and_or_b32 v23, v19, s35, v0
	v_or_b32_e32 v0, s6, v160
	v_lshl_add_u64 v[8:9], v[6:7], 0, s[4:5]
	v_lshlrev_b32_e32 v0, 11, v0
	v_lshl_add_u64 v[24:25], v[8:9], 0, v[0:1]
	global_store_dwordx4 v[24:25], v[20:23], off sc0 sc1
	ds_read_b32 v0, v11 offset:32
	ds_read_b32 v19, v11 offset:164
	ds_read_b32 v21, v11 offset:296
	ds_read_b32 v22, v11 offset:428
	ds_read_b32 v23, v11 offset:560
	ds_read_b32 v24, v11 offset:692
	ds_read_b32 v25, v11 offset:824
	ds_read_b32 v26, v11 offset:956
	s_waitcnt lgkmcnt(0)
	v_bfe_u32 v20, v0, 16, 1
	v_add3_u32 v0, v0, v20, s21
	v_bfe_u32 v20, v19, 16, 1
	v_lshrrev_b32_e32 v0, 16, v0
	v_add3_u32 v19, v19, v20, s21
	v_and_or_b32 v20, v19, s35, v0
	v_bfe_u32 v0, v21, 16, 1
	v_add3_u32 v0, v21, v0, s21
	v_bfe_u32 v19, v22, 16, 1
	v_lshrrev_b32_e32 v0, 16, v0
	v_add3_u32 v19, v22, v19, s21
	v_and_or_b32 v21, v19, s35, v0
	v_bfe_u32 v0, v23, 16, 1
	v_add3_u32 v0, v23, v0, s21
	v_bfe_u32 v19, v24, 16, 1
	v_lshrrev_b32_e32 v0, 16, v0
	v_add3_u32 v19, v24, v19, s21
	v_and_or_b32 v22, v19, s35, v0
	v_bfe_u32 v0, v25, 16, 1
	v_add3_u32 v0, v25, v0, s21
	v_bfe_u32 v19, v26, 16, 1
	v_lshrrev_b32_e32 v0, 16, v0
	v_add3_u32 v19, v26, v19, s21
	v_and_or_b32 v23, v19, s35, v0
	v_or_b32_e32 v0, s6, v161
	v_lshlrev_b32_e32 v0, 11, v0
	v_lshl_add_u64 v[24:25], v[8:9], 0, v[0:1]
	global_store_dwordx4 v[24:25], v[20:23], off sc0 sc1
	ds_read_b32 v0, v11 offset:64
	ds_read_b32 v19, v11 offset:196
	ds_read_b32 v21, v11 offset:328
	ds_read_b32 v22, v11 offset:460
	ds_read_b32 v23, v11 offset:592
	ds_read_b32 v24, v11 offset:724
	ds_read_b32 v25, v11 offset:856
	ds_read_b32 v26, v11 offset:988
	s_waitcnt lgkmcnt(0)
	v_bfe_u32 v20, v0, 16, 1
	v_add3_u32 v0, v0, v20, s21
	v_bfe_u32 v20, v19, 16, 1
	v_lshrrev_b32_e32 v0, 16, v0
	v_add3_u32 v19, v19, v20, s21
	v_and_or_b32 v20, v19, s35, v0
	v_bfe_u32 v0, v21, 16, 1
	v_add3_u32 v0, v21, v0, s21
	v_bfe_u32 v19, v22, 16, 1
	v_lshrrev_b32_e32 v0, 16, v0
	v_add3_u32 v19, v22, v19, s21
	v_and_or_b32 v21, v19, s35, v0
	v_bfe_u32 v0, v23, 16, 1
	v_add3_u32 v0, v23, v0, s21
	v_bfe_u32 v19, v24, 16, 1
	v_lshrrev_b32_e32 v0, 16, v0
	v_add3_u32 v19, v24, v19, s21
	v_and_or_b32 v22, v19, s35, v0
	v_bfe_u32 v0, v25, 16, 1
	v_add3_u32 v0, v25, v0, s21
	v_bfe_u32 v19, v26, 16, 1
	v_lshrrev_b32_e32 v0, 16, v0
	v_add3_u32 v19, v26, v19, s21
	v_and_or_b32 v23, v19, s35, v0
	v_or_b32_e32 v0, s6, v162
	v_lshlrev_b32_e32 v0, 11, v0
	v_lshl_add_u64 v[24:25], v[8:9], 0, v[0:1]
	global_store_dwordx4 v[24:25], v[20:23], off sc0 sc1
	ds_read_b32 v0, v11 offset:96
	ds_read_b32 v19, v11 offset:228
	ds_read_b32 v21, v11 offset:360
	ds_read_b32 v22, v11 offset:492
	ds_read_b32 v23, v11 offset:624
	ds_read_b32 v24, v11 offset:756
	ds_read_b32 v25, v11 offset:888
	ds_read_b32 v26, v11 offset:1020
	s_waitcnt lgkmcnt(0)
	v_bfe_u32 v20, v0, 16, 1
	v_add3_u32 v0, v0, v20, s21
	v_bfe_u32 v20, v19, 16, 1
	v_lshrrev_b32_e32 v0, 16, v0
	v_add3_u32 v19, v19, v20, s21
	v_and_or_b32 v20, v19, s35, v0
	v_bfe_u32 v0, v21, 16, 1
	v_add3_u32 v0, v21, v0, s21
	v_bfe_u32 v19, v22, 16, 1
	v_lshrrev_b32_e32 v0, 16, v0
	v_add3_u32 v19, v22, v19, s21
	v_and_or_b32 v21, v19, s35, v0
	v_bfe_u32 v0, v23, 16, 1
	v_add3_u32 v0, v23, v0, s21
	v_bfe_u32 v19, v24, 16, 1
	v_lshrrev_b32_e32 v0, 16, v0
	v_add3_u32 v19, v24, v19, s21
	v_and_or_b32 v22, v19, s35, v0
	v_bfe_u32 v0, v25, 16, 1
	v_add3_u32 v0, v25, v0, s21
	v_bfe_u32 v19, v26, 16, 1
	v_lshrrev_b32_e32 v0, 16, v0
	v_add3_u32 v19, v26, v19, s21
	v_and_or_b32 v23, v19, s35, v0
	v_or_b32_e32 v0, s6, v163
	v_lshlrev_b32_e32 v0, 11, v0
	v_lshl_add_u64 v[8:9], v[8:9], 0, v[0:1]
	global_store_dwordx4 v[8:9], v[20:23], off sc0 sc1
	s_waitcnt lgkmcnt(0)

; #define TR_TRY(CNT, NBLK, ...) if (r < (CNT)) { const int k0 = 64 * (r / (NBLK)), n0 = 32 * (r % (NBLK)); (void)k0; (void)n0; __VA_ARGS__; continue; } r -= (CNT);
; #define TR_TRY(CNT, NBLK, ...) if (r < (CNT)) { const int k0 = 64 * (r / (NBLK)), n0 = 32 * (r % (NBLK)); (void)k0; (void)n0; __VA_ARGS__; continue; } r -= (CNT);
; __device__ __forceinline__ void tr_item(const float* W, int N, int k0, int n0, bf16* WT, int Kd, int drow0, int dk0, LAS float* scr, int lane) {
;     ...
;         float wv[32]; const int n = n0 + (lane & 31); const float* wp = W + (size_t)(k0 + (lane >> 5)) * N + n;
; #pragma unroll
;         for (int i = 0; i < 32; ++i) wv[i] = (n < N) ? wp[(size_t)(2 * i) * N] : 0.f;
; #pragma unroll
;         for (int i = 0; i < 32; ++i) scr[(2 * i + (lane >> 5)) * 33 + (lane & 31)] = wv[i];
; __global__ void __launch_bounds__(NTHREADS, 2) mega_fwd(Args a_unused) {
;     ...
;                 TR_TRY(I_GU, FF / 32, tr_item(ap->in[21], FF, k0, n0, Wgu2, D, (n0 / 128) * 256 + (n0 % 128), k0, scr, lane))
.LBB0_312:
	s_andn2_b64 vcc, exec, s[6:7]
	s_cbranch_vccnz .LBB0_301
	v_mov_b64_e32 v[8:9], s[8:9]
	global_load_dwordx2 v[8:9], v[8:9], off offset:168
	s_mul_hi_i32 s4, s12, 0x2e8ba2e9
	s_lshr_b32 s6, s4, 31
	s_ashr_i32 s7, s4, 4
	s_add_i32 s7, s7, s6
	s_mul_i32 s4, s7, 0xfffff500
	s_lshl_b32 s6, s7, 6
	s_add_i32 s4, s11, s4
	v_or_b32_e32 v0, s6, v159
	v_add_u32_e32 v20, s4, v158
	v_ashrrev_i32_e32 v21, 31, v20
	s_mulk_i32 s7, 0xffa8
	s_add_i32 s7, s12, s7
	s_bfe_i32 s65, s7, 0x80000
	s_bfe_u32 s65, s65, 0x2000d
	s_add_i32 s7, s7, s65
	s_bfe_u32 s65, s4, 0x70018
	s_bfe_i32 s7, s7, 0x80000
	s_add_i32 s65, s4, s65
	s_sext_i32_i16 s7, s7
	s_and_b32 s65, s65, 0xff80
	s_lshl_b32 s7, s7, 6
	s_sub_i32 s4, s4, s65
	s_and_b32 s7, s7, 0xffffff00
	s_sext_i32_i16 s4, s4
	s_add_i32 s4, s7, s4
	s_ashr_i32 s7, s6, 31
	s_waitcnt vmcnt(0) lgkmcnt(0)
	v_mad_i64_i32 v[8:9], s[66:67], v0, s64, v[8:9]
	v_lshl_add_u64 v[8:9], v[20:21], 2, v[8:9]
	v_add_co_u32_e32 v20, vcc, s38, v8
	s_nop 1
	v_addc_co_u32_e32 v21, vcc, 0, v9, vcc
	v_add_co_u32_e32 v22, vcc, s39, v8
	s_nop 1
	v_addc_co_u32_e32 v23, vcc, 0, v9, vcc
	v_add_co_u32_e32 v24, vcc, s16, v8
	s_nop 1
	v_addc_co_u32_e32 v25, vcc, 0, v9, vcc
	v_add_co_u32_e32 v26, vcc, s17, v8
	s_nop 1
	v_addc_co_u32_e32 v27, vcc, 0, v9, vcc
	v_add_co_u32_e32 v28, vcc, s40, v8
	s_nop 1
	v_addc_co_u32_e32 v29, vcc, 0, v9, vcc
	v_add_co_u32_e32 v30, vcc, s41, v8
	s_nop 1
	v_addc_co_u32_e32 v31, vcc, 0, v9, vcc
	v_add_co_u32_e32 v32, vcc, s18, v8
	s_nop 1
	v_addc_co_u32_e32 v33, vcc, 0, v9, vcc
	v_add_co_u32_e32 v34, vcc, s19, v8
	s_nop 1
	v_addc_co_u32_e32 v35, vcc, 0, v9, vcc
	v_add_co_u32_e32 v36, vcc, s42, v8
	s_nop 1
	v_addc_co_u32_e32 v37, vcc, 0, v9, vcc
	v_add_co_u32_e32 v38, vcc, s43, v8
	s_nop 1
	v_addc_co_u32_e32 v39, vcc, 0, v9, vcc
	v_add_co_u32_e32 v40, vcc, s20, v8
	s_nop 1
	v_addc_co_u32_e32 v41, vcc, 0, v9, vcc
	v_add_co_u32_e32 v42, vcc, s44, v8
	s_nop 1
	v_addc_co_u32_e32 v43, vcc, 0, v9, vcc
	v_add_co_u32_e32 v44, vcc, s45, v8
	s_nop 1
	v_addc_co_u32_e32 v45, vcc, 0, v9, vcc
	v_add_co_u32_e32 v46, vcc, s46, v8
	s_nop 1
	v_addc_co_u32_e32 v47, vcc, 0, v9, vcc
	v_add_co_u32_e32 v48, vcc, s47, v8
	s_nop 1
	v_addc_co_u32_e32 v49, vcc, 0, v9, vcc
	global_load_dword v0, v[8:9], off nt
	global_load_dword v19, v[20:21], off offset:2048 nt
	global_load_dword v50, v[22:23], off nt
	global_load_dword v51, v[24:25], off offset:2048 nt
	global_load_dword v52, v[26:27], off nt
	global_load_dword v53, v[28:29], off offset:2048 nt
	global_load_dword v54, v[30:31], off nt
	global_load_dword v55, v[32:33], off offset:2048 nt
	global_load_dword v56, v[34:35], off nt
	s_nop 0
	global_load_dword v36, v[36:37], off offset:2048 nt
	s_nop 0
	global_load_dword v37, v[38:39], off nt
	s_nop 0
	global_load_dword v38, v[40:41], off offset:2048 nt
	global_load_dword v39, v[42:43], off nt
	s_nop 0
	global_load_dword v40, v[44:45], off offset:2048 nt
	global_load_dword v41, v[46:47], off nt
	global_load_dword v42, v[48:49], off offset:2048 nt
	v_add_co_u32_e32 v20, vcc, s48, v8
	s_nop 1
	v_addc_co_u32_e32 v21, vcc, 0, v9, vcc
	v_add_co_u32_e32 v22, vcc, s49, v8
	s_nop 1
	v_addc_co_u32_e32 v23, vcc, 0, v9, vcc
	v_add_co_u32_e32 v24, vcc, s50, v8
	s_nop 1
	v_addc_co_u32_e32 v25, vcc, 0, v9, vcc
	v_add_co_u32_e32 v26, vcc, s51, v8
	s_nop 1
	v_addc_co_u32_e32 v27, vcc, 0, v9, vcc
	v_add_co_u32_e32 v28, vcc, s52, v8
	s_nop 1
	v_addc_co_u32_e32 v29, vcc, 0, v9, vcc
	v_add_co_u32_e32 v30, vcc, s53, v8
	s_nop 1
	v_addc_co_u32_e32 v31, vcc, 0, v9, vcc
	v_add_co_u32_e32 v32, vcc, s54, v8
	s_nop 1
	v_addc_co_u32_e32 v33, vcc, 0, v9, vcc
	v_add_co_u32_e32 v34, vcc, s55, v8
	s_nop 1
	v_addc_co_u32_e32 v35, vcc, 0, v9, vcc
	global_load_dword v43, v[20:21], off nt
	global_load_dword v44, v[22:23], off offset:2048 nt
	global_load_dword v45, v[24:25], off nt
	global_load_dword v46, v[26:27], off offset:2048 nt
	global_load_dword v47, v[28:29], off nt
	global_load_dword v48, v[30:31], off offset:2048 nt
	global_load_dword v49, v[32:33], off nt
	s_nop 0
	global_load_dword v34, v[34:35], off offset:2048 nt
	v_add_co_u32_e32 v20, vcc, s56, v8
	s_nop 1
	v_addc_co_u32_e32 v21, vcc, 0, v9, vcc
	v_add_co_u32_e32 v22, vcc, s57, v8
	s_nop 1
	v_addc_co_u32_e32 v23, vcc, 0, v9, vcc
	v_add_co_u32_e32 v24, vcc, s58, v8
	s_nop 1
	v_addc_co_u32_e32 v25, vcc, 0, v9, vcc
	v_add_co_u32_e32 v26, vcc, s59, v8
	s_nop 1
	v_addc_co_u32_e32 v27, vcc, 0, v9, vcc
	v_add_co_u32_e32 v28, vcc, s60, v8
	s_nop 1
	v_addc_co_u32_e32 v29, vcc, 0, v9, vcc
	v_add_co_u32_e32 v30, vcc, s61, v8
	s_nop 1
	v_addc_co_u32_e32 v31, vcc, 0, v9, vcc
	v_add_co_u32_e32 v32, vcc, s62, v8
	s_nop 1
	v_addc_co_u32_e32 v33, vcc, 0, v9, vcc
	v_add_co_u32_e32 v8, vcc, s63, v8
	s_nop 1
	v_addc_co_u32_e32 v9, vcc, 0, v9, vcc
	global_load_dword v20, v[20:21], off nt
	s_nop 0
	global_load_dword v21, v[22:23], off offset:2048 nt
	s_nop 0
	global_load_dword v22, v[24:25], off nt
	global_load_dword v23, v[26:27], off offset:2048 nt
	s_nop 0
	global_load_dword v24, v[28:29], off nt
	global_load_dword v25, v[30:31], off offset:2048 nt
	global_load_dword v26, v[32:33], off nt
	s_nop 0
	global_load_dword v8, v[8:9], off offset:2048 nt
	s_waitcnt vmcnt(0) lgkmcnt(0)
; #define LAS __attribute__((address_space(3)))
; #define LDS_WAIT() asm volatile("s_waitcnt lgkmcnt(0)" ::: "memory")
; __device__ __forceinline__ unsigned pk2(float lo, float hi) { return f2bf(lo) | (f2bf(hi) << 16); }
; #define TR_TRY(CNT, NBLK, ...) if (r < (CNT)) { const int k0 = 64 * (r / (NBLK)), n0 = 32 * (r % (NBLK)); (void)k0; (void)n0; __VA_ARGS__; continue; } r -= (CNT);
; #define TR_TRY(CNT, NBLK, ...) if (r < (CNT)) { const int k0 = 64 * (r / (NBLK)), n0 = 32 * (r % (NBLK)); (void)k0; (void)n0; __VA_ARGS__; continue; } r -= (CNT);
; __device__ __forceinline__ void tr_item(const float* W, int N, int k0, int n0, bf16* WT, int Kd, int drow0, int dk0, LAS float* scr, int lane) {
;     ...
;         for (int i = 0; i < 32; ++i) scr[(2 * i + (lane >> 5)) * 33 + (lane & 31)] = wv[i];
;     }
;     LDS_WAIT();
;     const int c = lane & 7;
; #pragma unroll
;     for (int j = 0; j < 4; ++j) { const int n = (lane >> 3) + 8 * j; const LAS float* s = scr + (8 * c) * 33 + n;
;         v4u o; o.x = pk2(s[0 * 33], s[1 * 33]); o.y = pk2(s[2 * 33], s[3 * 33]); o.z = pk2(s[4 * 33], s[5 * 33]); o.w = pk2(s[6 * 33], s[7 * 33]);
;         *(v4u*)(WT + (size_t)(drow0 + n) * Kd + dk0 + 8 * c) = o; }
;     LDS_WAIT();
; __global__ void __launch_bounds__(NTHREADS, 2) mega_fwd(Args a_unused) {
;     ...
;             for (int it = hb * 8 + wave; it < NIT2; it += nh * 8) {
;                 int r = it;
;     ...
;                 TR_TRY(I_GU, FF / 32, tr_item(ap->in[21], FF, k0, n0, Wgu2, D, (n0 / 128) * 256 + (n0 % 128), k0, scr, lane))
	ds_write2_b32 v10, v0, v19 offset1:66
	ds_write2_b32 v10, v50, v51 offset0:132 offset1:198
	ds_write2_b32 v12, v52, v53 offset0:8 offset1:74
	ds_write2_b32 v12, v54, v55 offset0:140 offset1:206
	ds_write2_b32 v13, v56, v36 offset0:16 offset1:82
	ds_write2_b32 v13, v37, v38 offset0:148 offset1:214
	ds_write2_b32 v14, v39, v40 offset0:24 offset1:90
	ds_write2_b32 v14, v41, v42 offset0:156 offset1:222
	ds_write2_b32 v15, v43, v44 offset0:32 offset1:98
	ds_write2_b32 v15, v45, v46 offset0:164 offset1:230
	ds_write2_b32 v16, v47, v48 offset0:40 offset1:106
	ds_write2_b32 v16, v49, v34 offset0:172 offset1:238
	ds_write2_b32 v17, v20, v21 offset0:48 offset1:114
	ds_write2_b32 v17, v22, v23 offset0:180 offset1:246
	ds_write2_b32 v18, v24, v25 offset0:56 offset1:122
	ds_write2_b32 v18, v26, v8 offset0:188 offset1:254
	s_waitcnt lgkmcnt(0)
	ds_read_b32 v0, v11
	ds_read_b32 v19, v11 offset:132
	ds_read_b32 v21, v11 offset:264
	ds_read_b32 v22, v11 offset:396
	ds_read_b32 v23, v11 offset:528
	ds_read_b32 v24, v11 offset:660
	ds_read_b32 v25, v11 offset:792
	ds_read_b32 v26, v11 offset:924
	s_waitcnt lgkmcnt(7)
	v_bfe_u32 v20, v0, 16, 1
	v_add3_u32 v0, v0, v20, s21
	s_waitcnt lgkmcnt(6)
	v_bfe_u32 v20, v19, 16, 1
	v_lshrrev_b32_e32 v0, 16, v0
	v_add3_u32 v19, v19, v20, s21
	v_and_or_b32 v20, v19, s35, v0
	s_waitcnt lgkmcnt(5)
	v_bfe_u32 v0, v21, 16, 1
	v_add3_u32 v0, v21, v0, s21
	s_waitcnt lgkmcnt(4)
	v_bfe_u32 v19, v22, 16, 1
	v_lshrrev_b32_e32 v0, 16, v0
	v_add3_u32 v19, v22, v19, s21
	v_and_or_b32 v21, v19, s35, v0
	s_waitcnt lgkmcnt(3)
	v_bfe_u32 v0, v23, 16, 1
	v_add3_u32 v0, v23, v0, s21
	s_waitcnt lgkmcnt(2)
	v_bfe_u32 v19, v24, 16, 1
	v_lshrrev_b32_e32 v0, 16, v0
	v_add3_u32 v19, v24, v19, s21
	v_and_or_b32 v22, v19, s35, v0
	s_waitcnt lgkmcnt(1)
	v_bfe_u32 v0, v25, 16, 1
	v_or_b32_e32 v24, s4, v160
	v_add3_u32 v0, v25, v0, s21
	s_waitcnt lgkmcnt(0)
	v_bfe_u32 v19, v26, 16, 1
	v_ashrrev_i32_e32 v25, 31, v24
	v_lshl_add_u64 v[8:9], s[6:7], 1, v[6:7]
	v_lshrrev_b32_e32 v0, 16, v0
	v_add3_u32 v19, v26, v19, s21
	v_lshlrev_b64 v[24:25], 11, v[24:25]
	v_and_or_b32 v23, v19, s35, v0
	v_lshl_add_u64 v[24:25], v[8:9], 0, v[24:25]
	global_store_dwordx4 v[24:25], v[20:23], off sc0 sc1
	ds_read_b32 v0, v11 offset:32
	ds_read_b32 v19, v11 offset:164
	ds_read_b32 v21, v11 offset:296
	ds_read_b32 v22, v11 offset:428
	ds_read_b32 v23, v11 offset:560
	ds_read_b32 v24, v11 offset:692
	ds_read_b32 v25, v11 offset:824
	ds_read_b32 v26, v11 offset:956
	s_waitcnt lgkmcnt(0)
	v_bfe_u32 v20, v0, 16, 1
	v_add3_u32 v0, v0, v20, s21
	v_bfe_u32 v20, v19, 16, 1
	v_lshrrev_b32_e32 v0, 16, v0
	v_add3_u32 v19, v19, v20, s21
	v_and_or_b32 v20, v19, s35, v0
	v_bfe_u32 v0, v21, 16, 1
	v_add3_u32 v0, v21, v0, s21
	v_bfe_u32 v19, v22, 16, 1
	v_lshrrev_b32_e32 v0, 16, v0
	v_add3_u32 v19, v22, v19, s21
	v_and_or_b32 v21, v19, s35, v0
	v_bfe_u32 v0, v23, 16, 1
	v_add3_u32 v0, v23, v0, s21
	v_bfe_u32 v19, v24, 16, 1
	v_lshrrev_b32_e32 v0, 16, v0
	v_add3_u32 v19, v24, v19, s21
	v_and_or_b32 v22, v19, s35, v0
	v_bfe_u32 v0, v25, 16, 1
	v_or_b32_e32 v24, s4, v161
	v_add3_u32 v0, v25, v0, s21
	v_bfe_u32 v19, v26, 16, 1
	v_ashrrev_i32_e32 v25, 31, v24
	v_lshrrev_b32_e32 v0, 16, v0
	v_add3_u32 v19, v26, v19, s21
	v_lshlrev_b64 v[24:25], 11, v[24:25]
	v_and_or_b32 v23, v19, s35, v0
	v_lshl_add_u64 v[24:25], v[8:9], 0, v[24:25]
	global_store_dwordx4 v[24:25], v[20:23], off sc0 sc1
	ds_read_b32 v0, v11 offset:64
	ds_read_b32 v19, v11 offset:196
	ds_read_b32 v21, v11 offset:328
	ds_read_b32 v22, v11 offset:460
	ds_read_b32 v23, v11 offset:592
	ds_read_b32 v24, v11 offset:724
	ds_read_b32 v25, v11 offset:856
	ds_read_b32 v26, v11 offset:988
	s_waitcnt lgkmcnt(0)
	v_bfe_u32 v20, v0, 16, 1
	v_add3_u32 v0, v0, v20, s21
	v_bfe_u32 v20, v19, 16, 1
	v_lshrrev_b32_e32 v0, 16, v0
	v_add3_u32 v19, v19, v20, s21
	v_and_or_b32 v20, v19, s35, v0
	v_bfe_u32 v0, v21, 16, 1
	v_add3_u32 v0, v21, v0, s21
	v_bfe_u32 v19, v22, 16, 1
	v_lshrrev_b32_e32 v0, 16, v0
	v_add3_u32 v19, v22, v19, s21
	v_and_or_b32 v21, v19, s35, v0
	v_bfe_u32 v0, v23, 16, 1
	v_add3_u32 v0, v23, v0, s21
	v_bfe_u32 v19, v24, 16, 1
	v_lshrrev_b32_e32 v0, 16, v0
	v_add3_u32 v19, v24, v19, s21
	v_and_or_b32 v22, v19, s35, v0
	v_bfe_u32 v0, v25, 16, 1
	v_or_b32_e32 v24, s4, v162
	v_add3_u32 v0, v25, v0, s21
	v_bfe_u32 v19, v26, 16, 1
	v_ashrrev_i32_e32 v25, 31, v24
	v_lshrrev_b32_e32 v0, 16, v0
	v_add3_u32 v19, v26, v19, s21
	v_lshlrev_b64 v[24:25], 11, v[24:25]
	v_and_or_b32 v23, v19, s35, v0
	v_lshl_add_u64 v[24:25], v[8:9], 0, v[24:25]
	global_store_dwordx4 v[24:25], v[20:23], off sc0 sc1
	ds_read_b32 v0, v11 offset:96
	ds_read_b32 v19, v11 offset:228
	ds_read_b32 v21, v11 offset:360
	ds_read_b32 v22, v11 offset:492
	ds_read_b32 v23, v11 offset:624
	ds_read_b32 v24, v11 offset:756
	ds_read_b32 v25, v11 offset:888
	ds_read_b32 v26, v11 offset:1020
	s_waitcnt lgkmcnt(0)
	v_bfe_u32 v20, v0, 16, 1
	v_add3_u32 v0, v0, v20, s21
	v_bfe_u32 v20, v19, 16, 1
	v_lshrrev_b32_e32 v0, 16, v0
	v_add3_u32 v19, v19, v20, s21
	v_and_or_b32 v20, v19, s35, v0
	v_bfe_u32 v0, v21, 16, 1
	v_add3_u32 v0, v21, v0, s21
	v_bfe_u32 v19, v22, 16, 1
	v_lshrrev_b32_e32 v0, 16, v0
	v_add3_u32 v19, v22, v19, s21
	v_and_or_b32 v21, v19, s35, v0
	v_bfe_u32 v0, v23, 16, 1
	v_add3_u32 v0, v23, v0, s21
	v_bfe_u32 v19, v24, 16, 1
	v_lshrrev_b32_e32 v0, 16, v0
	v_add3_u32 v19, v24, v19, s21
	v_and_or_b32 v22, v19, s35, v0
	v_bfe_u32 v0, v25, 16, 1
	v_or_b32_e32 v24, s4, v163
	v_add3_u32 v0, v25, v0, s21
	v_bfe_u32 v19, v26, 16, 1
	v_ashrrev_i32_e32 v25, 31, v24
	v_lshrrev_b32_e32 v0, 16, v0
	v_add3_u32 v19, v26, v19, s21
	v_lshlrev_b64 v[24:25], 11, v[24:25]
	v_and_or_b32 v23, v19, s35, v0
	v_lshl_add_u64 v[8:9], v[8:9], 0, v[24:25]
	global_store_dwordx4 v[8:9], v[20:23], off sc0 sc1
	s_waitcnt lgkmcnt(0)
	s_branch .LBB0_301

; #define LAS __attribute__((address_space(3)))
; __device__ __forceinline__ void sel_pass(LAS unsigned char* lds, const bf16* K0, const bf16* V, int thi, const bf16x8 (&qf)[2][2], const int (&tpos)[2], const int (&tok)[2], int wave_tmin, int wave_tmax,
;         f32x4 (&o)[2][4], float (&mfin)[2], float (&linv)[2], int tid, int fr, int fq) {
;     ...
;         for (int u = 0; u < 2; ++u) {
;             const int t = 2 * g + u;
;             if (t > thi) continue;
;             LAS unsigned char* buf = lds + (2 * par + u) * SEL_SLOT;
;             const int kbase = 64 * t;
;             if (kbase > wave_tmax) continue;
;             const bool full = kbase + 63 <= wave_tmin;
;             bool rowsel[2];
; #pragma unroll
;             for (int i = 0; i < 2; ++i) { const unsigned w = ((const LAS unsigned*)(lds + OFF_SEL))[tok[i] * 4 + (t >> 5)]; rowsel[i] = ((w >> (t & 31)) & 1u) != 0u; }
;             const bool n0 = __any(rowsel[0] ? 1 : 0) != 0, n1 = __any(rowsel[1] ? 1 : 0) != 0;
;             if (n0 && n1) { if (full) tile_x<64, SEL, true, 0, 2>(buf, qf, kbase, tpos, rowsel, m, l, o, s, fr, fq); else tile_x<64, SEL, false, 0, 2>(buf, qf, kbase, tpos, rowsel, m, l, o, s, fr, fq);
;                             tile_y<0, 2, SEL_V>(buf, l, o, s, fr, fq); }
;             else if (n0) { if (full) tile_x<64, SEL, true, 0, 1>(buf, qf, kbase, tpos, rowsel, m, l, o, s, fr, fq); else tile_x<64, SEL, false, 0, 1>(buf, qf, kbase, tpos, rowsel, m, l, o, s, fr, fq);
;                            tile_y<0, 1, SEL_V>(buf, l, o, s, fr, fq); }
;             else if (n1) { if (full) tile_x<64, SEL, true, 1, 1>(buf, qf, kbase, tpos, rowsel, m, l, o, s, fr, fq); else tile_x<64, SEL, false, 1, 1>(buf, qf, kbase, tpos, rowsel, m, l, o, s, fr, fq);
;                            tile_y<1, 1, SEL_V>(buf, l, o, s, fr, fq); }
;         }
.LBB0_1087:
	s_lshr_b32 s6, s90, 2
	s_and_b32 s92, s94, 2
	s_and_b32 s6, s6, 0x3ffffffc
	s_add_i32 s95, s6, 0
	s_mul_i32 s6, s92, 0x4800
	s_add_i32 s95, s95, 0x12000
	s_add_i32 s93, s6, 0
	v_add_u32_e32 v155, s95, v180
	v_add_u32_e32 v162, s95, v177
	ds_read_b32 v151, v155
	ds_read_b32 v153, v162
	s_mov_b32 s32, s94
	s_mov_b32 s67, s93
	s_and_b32 s96, s94, 30
	s_mov_b32 s93, 0
	s_mov_b32 s95, 0
	s_waitcnt lgkmcnt(0)
.Lsel_tile:
	s_cmp_gt_u32 s32, s72
	s_cbranch_scc1 .Lsel_done
	v_bfe_u32 v155, v151, s96, 1
	v_bfe_u32 v162, v153, s96, 1
	s_cmp_eq_u32 s32, s72
	s_cselect_b32 s97, 1, 0
	s_lshl_b32 s94, s32, 6
	v_cmp_ne_u32_e64 s[8:9], 0, v155
	v_cmp_ne_u32_e64 s[10:11], 0, v162
	s_cmp_lg_u64 s[8:9], 0
	s_cbranch_scc0 .Lsel_noA
	s_cmp_lg_u64 s[10:11], 0
	s_cbranch_scc1 .Lsel_both
	s_branch .Lsel_blkA
.Lsel_noA:
.Lsel_retA:
	s_cmp_lg_u64 s[10:11], 0
	s_cbranch_scc1 .Lsel_blkB
.Lsel_retB:
	s_add_i32 s93, s93, 1
	s_add_i32 s32, s32, 1
	s_addk_i32 s67, 0x4800
	s_add_i32 s96, s96, 1
	s_cmp_lt_u32 s93, 2
	s_cbranch_scc1 .Lsel_tile

; #define LAS __attribute__((address_space(3)))
; #define IMX3(a, b, c) imax2(imax2((a), __builtin_bit_cast(int, (b))), __builtin_bit_cast(int, (c)))
; template <int DQK, int MODE, bool FULL, int I0, int NQ> __device__ __forceinline__ void tile_x(LAS unsigned char* lds, const bf16x8 (&qf)[2][DQK / 32], int kbase, const int (&tpos)[2], const bool (&rowsel)[2],
;         float (&m)[2], float (&l)[2], f32x4 (&o)[2][4], f32x4 (&s)[2][4], int fr, int fq) {
;     ...
;     for (int ss = 0; ss < 4; ++ss)
; #pragma unroll
;         for (int ks = 0; ks < NKS; ++ks) {
;             const bf16x8 kf = *(const LAS bf16x8*)(lds + k_off<DQK>(16 * ss + fr, 4 * ks + fq));
; #pragma unroll
;             for (int q = 0; q < NQ; ++q) s[I0 + q][ss] = __builtin_amdgcn_mfma_f32_16x16x32_bf16(kf, qf[I0 + q][ks], s[I0 + q][ss], 0, 0, 0);
;         }
; #pragma unroll
;     for (int q = 0; q < NQ; ++q) {
;         f32x4 (&sq)[4] = s[I0 + q];
;         const float mo = m[I0 + q];
;         bool slow = true;
;         if (FULL) {
;             int ia = __builtin_bit_cast(int, sq[0][0]);
;     ...
;             ia = IMX3(ia, sq[0][1], sq[0][2]); ia = IMX3(ia, sq[0][3], sq[1][0]); ia = IMX3(ia, sq[1][1], sq[1][2]); ia = IMX3(ia, sq[1][3], sq[2][0]);
;             int ib = __builtin_bit_cast(int, sq[2][1]);
;             ib = IMX3(ib, sq[2][2], sq[2][3]); ib = IMX3(ib, sq[3][0], sq[3][1]); ib = IMX3(ib, sq[3][2], sq[3][3]);
;     ...
;             const bool big = !(mo > -1e29f) || (imax2(ia, ib) > __builtin_bit_cast(int, RESCALE_THR));
;             slow = __any(big ? 1 : 0) != 0;
;         }
;         if (slow) {
;             float mx;
;             if (FULL) {
;                 mx = fmaxf(fmaxf(sq[0][0], sq[0][1]), fmaxf(sq[0][2], sq[0][3]));
; #pragma unroll
;                 for (int ss = 1; ss < 4; ++ss) mx = fmaxf(mx, fmaxf(fmaxf(sq[ss][0], sq[ss][1]), fmaxf(sq[ss][2], sq[ss][3])));
;             } else {
;                 mx = NEG;
; #pragma unroll
;                 for (int ss = 0; ss < 4; ++ss)
; #pragma unroll
;                     for (int i = 0; i < 4; ++i) { const bool ok = key_ok<MODE>(kbase + 16 * ss + 4 * fq + i, tpos[I0 + q], rowsel[I0 + q]); const float v = ok ? sq[ss][i] : NEG; sq[ss][i] = v; mx = fmaxf(mx, v); }
;             }
;             mx = rows_max(mx);
;             const bool need = (mo > -1e29f) ? (mx > RESCALE_THR) : (mx > -1e29f);
;             if (__any(need ? 1 : 0)) {
.Lsel_blkA:
	v_cmp_lt_f32_e64 s[12:13], s77, v160
	v_add_u32_e32 v167, s67, v139
	v_add_u32_e32 v196, s67, v143
	v_add_u32_e32 v195, v167, v141
	v_add_u32_e32 v167, v167, v140
	v_cndmask_b32_e64 v163, 0, v160, s[12:13]
	ds_read_b128 v[68:71], v167
	ds_read_b128 v[72:75], v195
	ds_read_b128 v[76:79], v167 offset:2048
	ds_read_b128 v[80:83], v195 offset:2048
	ds_read_b128 v[84:87], v167 offset:4096
	ds_read_b128 v[88:91], v195 offset:4096
	ds_read_b128 v[92:95], v167 offset:6144
	ds_read_b128 v[240:243], v195 offset:6144
	v_cndmask_b32_e64 v228, v183, -v163, s[8:9]
	v_mov_b32_e32 v229, v228
	v_mov_b32_e32 v230, v228
	v_mov_b32_e32 v231, v228
	s_nop 1
	s_waitcnt lgkmcnt(7)
	v_mfma_f32_16x16x32_bf16 v[212:215], v[68:71], v[20:23], v[228:231]
	s_waitcnt lgkmcnt(6)
	v_mfma_f32_16x16x32_bf16 v[212:215], v[72:75], v[24:27], v[212:215]
	s_waitcnt lgkmcnt(5)
	v_mfma_f32_16x16x32_bf16 v[216:219], v[76:79], v[20:23], v[228:231]
	s_waitcnt lgkmcnt(4)
	v_mfma_f32_16x16x32_bf16 v[216:219], v[80:83], v[24:27], v[216:219]
	s_waitcnt lgkmcnt(3)
	v_mfma_f32_16x16x32_bf16 v[220:223], v[84:87], v[20:23], v[228:231]
	s_waitcnt lgkmcnt(2)
	v_mfma_f32_16x16x32_bf16 v[220:223], v[88:91], v[24:27], v[220:223]
	s_waitcnt lgkmcnt(1)
	v_mfma_f32_16x16x32_bf16 v[224:227], v[92:95], v[20:23], v[228:231]
	s_waitcnt lgkmcnt(0)
	v_mfma_f32_16x16x32_bf16 v[224:227], v[240:243], v[24:27], v[224:227]
	ds_read_b64_tr_b16 v[68:69], v196 offset:8192
	ds_read_b64_tr_b16 v[70:71], v196 offset:10752
	ds_read_b64_tr_b16 v[72:73], v196 offset:13312
	ds_read_b64_tr_b16 v[74:75], v196 offset:15872
	ds_read_b64_tr_b16 v[76:77], v196 offset:8224
	ds_read_b64_tr_b16 v[78:79], v196 offset:10784
	ds_read_b64_tr_b16 v[80:81], v196 offset:13344
	ds_read_b64_tr_b16 v[82:83], v196 offset:15904
	s_cmp_lg_u32 s97, 0
	s_cbranch_scc1 .Lsel_maskA
	v_max_i32_e32 v198, v212, v216
	v_max3_i32 v198, v220, v224, v198
	v_cmp_lt_i32_e32 vcc, s80, v198
	s_orn2_b64 vcc, vcc, s[12:13]
	s_cbranch_vccz .Lsel_yA
.Lsel_slowA:
	v_max3_f32 v198, v212, v213, v214
	v_max3_f32 v198, v198, v215, v216
	v_max3_f32 v198, v198, v217, v218
	v_max3_f32 v198, v198, v219, v220
	v_max3_f32 v198, v198, v221, v222
	v_max3_f32 v198, v198, v223, v224
	v_max3_f32 v198, v198, v225, v226
	v_max_f32_e32 v198, v198, v227
	v_mov_b32_e32 v199, v198
	s_nop 1
	v_permlane16_swap_b32_e32 v198, v199
	v_max_f32_e32 v198, v198, v199
	v_mov_b32_e32 v199, v198
	s_nop 1
	v_permlane32_swap_b32_e32 v198, v199
	v_max_f32_e32 v201, v198, v199
	v_cmp_lt_f32_e64 s[20:21], s80, v201
	v_cmp_lt_f32_e64 s[64:65], s77, v201
	s_and_b64 s[20:21], s[20:21], s[12:13]
	s_andn2_b64 s[64:65], s[64:65], s[12:13]
	s_or_b64 s[14:15], s[20:21], s[64:65]
	s_cmp_lg_u64 s[14:15], 0
	s_cbranch_scc0 .Lsel_slowA_done
	v_add_f32_e32 v198, v163, v201
	v_cndmask_b32_e64 v210, 0, v201, s[14:15]
	v_cndmask_b32_e64 v252, v160, v198, s[14:15]
	v_sub_f32_e32 v198, v160, v252
	v_exp_f32_e32 v198, v198
	v_mov_b32_e32 v160, v252
	v_cndmask_b32_e64 v253, 1.0, v198, s[14:15]
	v_mul_f32_e32 v135, v135, v253
	v_mul_f32_e32 v28, v28, v253
	v_mul_f32_e32 v29, v29, v253
	v_mul_f32_e32 v30, v30, v253
	v_mul_f32_e32 v31, v31, v253
	v_mul_f32_e32 v8, v8, v253
	v_mul_f32_e32 v9, v9, v253
	v_mul_f32_e32 v10, v10, v253
	v_mul_f32_e32 v11, v11, v253
	v_mul_f32_e32 v4, v4, v253
	v_mul_f32_e32 v5, v5, v253
	v_mul_f32_e32 v6, v6, v253
	v_mul_f32_e32 v7, v7, v253
	v_mul_f32_e32 v0, v0, v253
	v_mul_f32_e32 v1, v1, v253
	v_mul_f32_e32 v2, v2, v253
	v_mul_f32_e32 v3, v3, v253
	v_sub_f32_e32 v212, v212, v210
	v_sub_f32_e32 v213, v213, v210
	v_sub_f32_e32 v214, v214, v210
	v_sub_f32_e32 v215, v215, v210
	v_sub_f32_e32 v216, v216, v210
	v_sub_f32_e32 v217, v217, v210
	v_sub_f32_e32 v218, v218, v210
	v_sub_f32_e32 v219, v219, v210
	v_sub_f32_e32 v220, v220, v210
	v_sub_f32_e32 v221, v221, v210
	v_sub_f32_e32 v222, v222, v210
	v_sub_f32_e32 v223, v223, v210
	v_sub_f32_e32 v224, v224, v210
	v_sub_f32_e32 v225, v225, v210
	v_sub_f32_e32 v226, v226, v210
	v_sub_f32_e32 v227, v227, v210
.Lsel_slowA_done:
	s_cmp_lg_u32 s95, 0
	s_cbranch_scc1 .Lboth_chkB
.Lsel_yA:
	v_exp_f32_e32 v212, v212
	v_exp_f32_e32 v213, v213
	v_exp_f32_e32 v214, v214
	v_exp_f32_e32 v215, v215
	v_exp_f32_e32 v216, v216
	v_exp_f32_e32 v217, v217
	v_exp_f32_e32 v218, v218
	v_exp_f32_e32 v219, v219
	v_exp_f32_e32 v220, v220
	v_exp_f32_e32 v221, v221
	v_exp_f32_e32 v222, v222
	v_exp_f32_e32 v223, v223
	v_exp_f32_e32 v224, v224
	v_exp_f32_e32 v225, v225
	v_exp_f32_e32 v226, v226
	v_exp_f32_e32 v227, v227
	s_waitcnt lgkmcnt(7)
	ds_read_b64_tr_b16 v[84:85], v196 offset:8256
	ds_read_b64_tr_b16 v[86:87], v196 offset:10816
	ds_read_b64_tr_b16 v[88:89], v196 offset:13376
	ds_read_b64_tr_b16 v[90:91], v196 offset:15936
	ds_read_b64_tr_b16 v[92:93], v196 offset:8288
	ds_read_b64_tr_b16 v[94:95], v196 offset:10848
	ds_read_b64_tr_b16 v[240:241], v196 offset:13408
	ds_read_b64_tr_b16 v[242:243], v196 offset:15968
	v_cvt_pk_bf16_f32 v232, v212, v213
	v_cvt_pk_bf16_f32 v233, v214, v215
	v_cvt_pk_bf16_f32 v234, v216, v217
	v_cvt_pk_bf16_f32 v235, v218, v219
	v_cvt_pk_bf16_f32 v236, v220, v221
	v_cvt_pk_bf16_f32 v237, v222, v223
	v_cvt_pk_bf16_f32 v238, v224, v225
	v_cvt_pk_bf16_f32 v239, v226, v227
	v_pk_add_f32 v[248:249], v[212:213], v[214:215]
	v_pk_add_f32 v[208:209], v[216:217], v[218:219]
	v_pk_add_f32 v[202:203], v[220:221], v[222:223]
	v_pk_add_f32 v[248:249], v[248:249], v[208:209]
	v_pk_add_f32 v[208:209], v[224:225], v[226:227]
	v_pk_add_f32 v[202:203], v[202:203], v[208:209]
	v_pk_add_f32 v[248:249], v[248:249], v[202:203]
	v_add_f32_e32 v248, v248, v249
	v_add_f32_e32 v135, v135, v248
	s_waitcnt lgkmcnt(14)
	v_mfma_f32_16x16x32_bf16 v[28:31], v[68:71], v[232:235], v[28:31]
	s_waitcnt lgkmcnt(12)
	v_mfma_f32_16x16x32_bf16 v[28:31], v[72:75], v[236:239], v[28:31]
	s_waitcnt lgkmcnt(10)
	v_mfma_f32_16x16x32_bf16 v[8:11], v[76:79], v[232:235], v[8:11]
	s_waitcnt lgkmcnt(8)
	v_mfma_f32_16x16x32_bf16 v[8:11], v[80:83], v[236:239], v[8:11]
	s_waitcnt lgkmcnt(6)
	v_mfma_f32_16x16x32_bf16 v[4:7], v[84:87], v[232:235], v[4:7]
	s_waitcnt lgkmcnt(4)
	v_mfma_f32_16x16x32_bf16 v[4:7], v[88:91], v[236:239], v[4:7]
	s_waitcnt lgkmcnt(2)
	v_mfma_f32_16x16x32_bf16 v[0:3], v[92:95], v[232:235], v[0:3]
	s_waitcnt lgkmcnt(0)
	v_mfma_f32_16x16x32_bf16 v[0:3], v[240:243], v[236:239], v[0:3]
	s_branch .Lsel_retA
; #define LAS __attribute__((address_space(3)))
; #define IMX3(a, b, c) imax2(imax2((a), __builtin_bit_cast(int, (b))), __builtin_bit_cast(int, (c)))
; template <int DQK, int MODE, bool FULL, int I0, int NQ> __device__ __forceinline__ void tile_x(LAS unsigned char* lds, const bf16x8 (&qf)[2][DQK / 32], int kbase, const int (&tpos)[2], const bool (&rowsel)[2],
;         float (&m)[2], float (&l)[2], f32x4 (&o)[2][4], f32x4 (&s)[2][4], int fr, int fq) {
;     constexpr int NKS = DQK / 32;
;     float meff[NQ];
; #pragma unroll
;     for (int q = 0; q < NQ; ++q) { meff[q] = (m[I0 + q] > -1e29f) ? m[I0 + q] : 0.f; const float c = (MODE == SEL && !rowsel[I0 + q]) ? NEG : -meff[q];
; #pragma unroll
;         for (int ss = 0; ss < 4; ++ss) s[I0 + q][ss] = (f32x4){c, c, c, c}; }
; #pragma unroll
;     for (int ss = 0; ss < 4; ++ss)
; #pragma unroll
;         for (int ks = 0; ks < NKS; ++ks) {
;             const bf16x8 kf = *(const LAS bf16x8*)(lds + k_off<DQK>(16 * ss + fr, 4 * ks + fq));
; #pragma unroll
;             for (int q = 0; q < NQ; ++q) s[I0 + q][ss] = __builtin_amdgcn_mfma_f32_16x16x32_bf16(kf, qf[I0 + q][ks], s[I0 + q][ss], 0, 0, 0);
;         }
; #pragma unroll
;     for (int q = 0; q < NQ; ++q) {
;         f32x4 (&sq)[4] = s[I0 + q];
;         const float mo = m[I0 + q];
;         bool slow = true;
;         if (FULL) {
;             int ia = __builtin_bit_cast(int, sq[0][0]);
;     ...
;             ia = IMX3(ia, sq[0][1], sq[0][2]); ia = IMX3(ia, sq[0][3], sq[1][0]); ia = IMX3(ia, sq[1][1], sq[1][2]); ia = IMX3(ia, sq[1][3], sq[2][0]);
;             int ib = __builtin_bit_cast(int, sq[2][1]);
;             ib = IMX3(ib, sq[2][2], sq[2][3]); ib = IMX3(ib, sq[3][0], sq[3][1]); ib = IMX3(ib, sq[3][2], sq[3][3]);
;     ...
;             const bool big = !(mo > -1e29f) || (imax2(ia, ib) > __builtin_bit_cast(int, RESCALE_THR));
;             slow = __any(big ? 1 : 0) != 0;
;         }
;         if (slow) {
;             float mx;
;             if (FULL) {
;                 mx = fmaxf(fmaxf(sq[0][0], sq[0][1]), fmaxf(sq[0][2], sq[0][3]));
; #pragma unroll
;                 for (int ss = 1; ss < 4; ++ss) mx = fmaxf(mx, fmaxf(fmaxf(sq[ss][0], sq[ss][1]), fmaxf(sq[ss][2], sq[ss][3])));
;             } else {
;                 mx = NEG;
; #pragma unroll
;                 for (int ss = 0; ss < 4; ++ss)
; #pragma unroll
.Lsel_maskA:
	v_add_u32_e32 v254, s94, v142
	v_sub_u32_e32 v255, v116, v254
	v_cmp_le_i32_e64 s[100:101], 0, v255
	v_cmp_le_i32_e64 s[20:21], 1, v255
	v_cmp_le_i32_e64 s[64:65], 2, v255
	v_cndmask_b32_e64 v212, v183, v212, s[100:101]
	v_cmp_le_i32_e64 s[100:101], 3, v255
	v_cndmask_b32_e64 v213, v183, v213, s[20:21]
	v_cmp_le_i32_e64 s[20:21], 16, v255
	v_cndmask_b32_e64 v214, v183, v214, s[64:65]
	v_cmp_le_i32_e64 s[64:65], 17, v255
	v_cndmask_b32_e64 v215, v183, v215, s[100:101]
	v_cmp_le_i32_e64 s[100:101], 18, v255
	v_cndmask_b32_e64 v216, v183, v216, s[20:21]
	v_cmp_le_i32_e64 s[20:21], 19, v255
	v_cndmask_b32_e64 v217, v183, v217, s[64:65]
	v_cmp_le_i32_e64 s[64:65], 32, v255
	v_cndmask_b32_e64 v218, v183, v218, s[100:101]
	v_cmp_le_i32_e64 s[100:101], 33, v255
	v_cndmask_b32_e64 v219, v183, v219, s[20:21]
	v_cmp_le_i32_e64 s[20:21], 34, v255
	v_cndmask_b32_e64 v220, v183, v220, s[64:65]
	v_cmp_le_i32_e64 s[64:65], 35, v255
	v_cndmask_b32_e64 v221, v183, v221, s[100:101]
	v_cmp_le_i32_e64 s[100:101], 48, v255
	v_cndmask_b32_e64 v222, v183, v222, s[20:21]
	v_cmp_le_i32_e64 s[20:21], 49, v255
	v_cndmask_b32_e64 v223, v183, v223, s[64:65]
	v_cmp_le_i32_e64 s[64:65], 50, v255
	v_cndmask_b32_e64 v224, v183, v224, s[100:101]
	v_cmp_le_i32_e64 s[100:101], 51, v255
	s_nop 1
	v_cndmask_b32_e64 v225, v183, v225, s[20:21]
	v_cndmask_b32_e64 v226, v183, v226, s[64:65]
	v_cndmask_b32_e64 v227, v183, v227, s[100:101]
	s_branch .Lsel_slowA
.Lsel_blkB:
	v_cmp_lt_f32_e64 s[6:7], s77, v161
	v_add_u32_e32 v167, s67, v139
	v_add_u32_e32 v196, s67, v143
	v_add_u32_e32 v195, v167, v141
	v_add_u32_e32 v167, v167, v140
	v_cndmask_b32_e64 v166, 0, v161, s[6:7]
	ds_read_b128 v[68:71], v167
	ds_read_b128 v[72:75], v195
	ds_read_b128 v[76:79], v167 offset:2048
	ds_read_b128 v[80:83], v195 offset:2048
	ds_read_b128 v[84:87], v167 offset:4096
	ds_read_b128 v[88:91], v195 offset:4096
	ds_read_b128 v[92:95], v167 offset:6144
	ds_read_b128 v[240:243], v195 offset:6144
	v_cndmask_b32_e64 v228, v183, -v166, s[10:11]
	v_mov_b32_e32 v229, v228
	v_mov_b32_e32 v230, v228
	v_mov_b32_e32 v231, v228
	s_nop 1
	s_waitcnt lgkmcnt(7)
	v_mfma_f32_16x16x32_bf16 v[212:215], v[68:71], v[12:15], v[228:231]
	s_waitcnt lgkmcnt(6)
	v_mfma_f32_16x16x32_bf16 v[212:215], v[72:75], v[16:19], v[212:215]
	s_waitcnt lgkmcnt(5)
	v_mfma_f32_16x16x32_bf16 v[216:219], v[76:79], v[12:15], v[228:231]
	s_waitcnt lgkmcnt(4)
	v_mfma_f32_16x16x32_bf16 v[216:219], v[80:83], v[16:19], v[216:219]
	s_waitcnt lgkmcnt(3)
	v_mfma_f32_16x16x32_bf16 v[220:223], v[84:87], v[12:15], v[228:231]
	s_waitcnt lgkmcnt(2)
	v_mfma_f32_16x16x32_bf16 v[220:223], v[88:91], v[16:19], v[220:223]
	s_waitcnt lgkmcnt(1)
	v_mfma_f32_16x16x32_bf16 v[224:227], v[92:95], v[12:15], v[228:231]
	s_waitcnt lgkmcnt(0)
	v_mfma_f32_16x16x32_bf16 v[224:227], v[240:243], v[16:19], v[224:227]
	ds_read_b64_tr_b16 v[68:69], v196 offset:8192
	ds_read_b64_tr_b16 v[70:71], v196 offset:10752
	ds_read_b64_tr_b16 v[72:73], v196 offset:13312
	ds_read_b64_tr_b16 v[74:75], v196 offset:15872
	ds_read_b64_tr_b16 v[76:77], v196 offset:8224
	ds_read_b64_tr_b16 v[78:79], v196 offset:10784
	ds_read_b64_tr_b16 v[80:81], v196 offset:13344
	ds_read_b64_tr_b16 v[82:83], v196 offset:15904
	s_cmp_lg_u32 s97, 0
	s_cbranch_scc1 .Lsel_maskB
	v_max_i32_e32 v198, v212, v216
	v_max3_i32 v198, v220, v224, v198
	v_cmp_lt_i32_e32 vcc, s80, v198
	s_orn2_b64 vcc, vcc, s[6:7]
	s_cbranch_vccz .Lsel_yB
.Lsel_slowB:
	v_max3_f32 v198, v212, v213, v214
	v_max3_f32 v198, v198, v215, v216
	v_max3_f32 v198, v198, v217, v218
	v_max3_f32 v198, v198, v219, v220
	v_max3_f32 v198, v198, v221, v222
	v_max3_f32 v198, v198, v223, v224
	v_max3_f32 v198, v198, v225, v226
	v_max_f32_e32 v198, v198, v227
	v_mov_b32_e32 v199, v198
	s_nop 1
	v_permlane16_swap_b32_e32 v198, v199
	v_max_f32_e32 v198, v198, v199
	v_mov_b32_e32 v199, v198
	s_nop 1
	v_permlane32_swap_b32_e32 v198, v199
	v_max_f32_e32 v201, v198, v199
	v_cmp_lt_f32_e64 s[20:21], s80, v201
	v_cmp_lt_f32_e64 s[64:65], s77, v201
	s_and_b64 s[20:21], s[20:21], s[6:7]
	s_andn2_b64 s[64:65], s[64:65], s[6:7]
	s_or_b64 s[14:15], s[20:21], s[64:65]
	s_cmp_lg_u64 s[14:15], 0
	s_cbranch_scc0 .Lsel_yB
	v_add_f32_e32 v198, v166, v201
	v_cndmask_b32_e64 v210, 0, v201, s[14:15]
	v_cndmask_b32_e64 v252, v161, v198, s[14:15]
	v_sub_f32_e32 v198, v161, v252
	v_exp_f32_e32 v198, v198
	v_mov_b32_e32 v161, v252
	v_cndmask_b32_e64 v253, 1.0, v198, s[14:15]
	v_mul_f32_e32 v134, v134, v253
	v_mul_f32_e32 v60, v60, v253
	v_mul_f32_e32 v61, v61, v253
	v_mul_f32_e32 v62, v62, v253
	v_mul_f32_e32 v63, v63, v253
	v_mul_f32_e32 v56, v56, v253
	v_mul_f32_e32 v57, v57, v253
	v_mul_f32_e32 v58, v58, v253
	v_mul_f32_e32 v59, v59, v253
	v_mul_f32_e32 v52, v52, v253
	v_mul_f32_e32 v53, v53, v253
	v_mul_f32_e32 v54, v54, v253
	v_mul_f32_e32 v55, v55, v253
	v_mul_f32_e32 v40, v40, v253
	v_mul_f32_e32 v41, v41, v253
	v_mul_f32_e32 v42, v42, v253
	v_mul_f32_e32 v43, v43, v253
	v_sub_f32_e32 v212, v212, v210
	v_sub_f32_e32 v213, v213, v210
	v_sub_f32_e32 v214, v214, v210
	v_sub_f32_e32 v215, v215, v210
	v_sub_f32_e32 v216, v216, v210
	v_sub_f32_e32 v217, v217, v210
	v_sub_f32_e32 v218, v218, v210
	v_sub_f32_e32 v219, v219, v210
	v_sub_f32_e32 v220, v220, v210
	v_sub_f32_e32 v221, v221, v210
	v_sub_f32_e32 v222, v222, v210
	v_sub_f32_e32 v223, v223, v210
	v_sub_f32_e32 v224, v224, v210
	v_sub_f32_e32 v225, v225, v210
	v_sub_f32_e32 v226, v226, v210
	v_sub_f32_e32 v227, v227, v210
; template <int DQK, int MODE, bool FULL, int I0, int NQ> __device__ __forceinline__ void tile_x(LAS unsigned char* lds, const bf16x8 (&qf)[2][DQK / 32], int kbase, const int (&tpos)[2], const bool (&rowsel)[2],
;         float (&m)[2], float (&l)[2], f32x4 (&o)[2][4], f32x4 (&s)[2][4], int fr, int fq) {
;     ...
;     for (int ss = 0; ss < 4; ++ss)
; #pragma unroll
;         for (int ks = 0; ks < NKS; ++ks) {
;             const bf16x8 kf = *(const LAS bf16x8*)(lds + k_off<DQK>(16 * ss + fr, 4 * ks + fq));
; #pragma unroll
;             for (int q = 0; q < NQ; ++q) s[I0 + q][ss] = __builtin_amdgcn_mfma_f32_16x16x32_bf16(kf, qf[I0 + q][ks], s[I0 + q][ss], 0, 0, 0);
;         }
; template <int I0, int NQ, int VO> __device__ __forceinline__ void tile_y(LAS unsigned char* lds, float (&l)[2], f32x4 (&o)[2][4], f32x4 (&s)[2][4], int fr, int fq) {
;     bf16x8 pb[NQ][2];
; #pragma unroll
;     for (int q = 0; q < NQ; ++q) {
;         f32x4 (&sq)[4] = s[I0 + q];
;         f32x2_t rs2 = {0.f, 0.f};
; #pragma unroll
;         for (int ss = 0; ss < 4; ++ss) {
; #pragma unroll
;             for (int i = 0; i < 4; ++i) sq[ss][i] = __builtin_amdgcn_exp2f(sq[ss][i]);
;             rs2 += (f32x2_t){sq[ss][0], sq[ss][1]}; rs2 += (f32x2_t){sq[ss][2], sq[ss][3]};
;         }
;         l[I0 + q] += rs2.x + rs2.y;
; #pragma unroll
;         for (int j = 0; j < 2; ++j) {
;             const v4u w = (v4u){cvtpk(sq[2 * j][0], sq[2 * j][1]), cvtpk(sq[2 * j][2], sq[2 * j][3]), cvtpk(sq[2 * j + 1][0], sq[2 * j + 1][1]), cvtpk(sq[2 * j + 1][2], sq[2 * j + 1][3])};
;             pb[q][j] = __builtin_bit_cast(bf16x8, w);
;         }
;     }
; #pragma unroll
;     for (int dt = 0; dt < 4; ++dt)
; #pragma unroll
;         for (int j = 0; j < 2; ++j) {
;             LAS unsigned char* vp = lds + VO + ((32 * j + 4 * fq + (fr >> 2)) * VSTR + 16 * dt + 4 * (fr & 3)) * 2;
;             const s16x4 lo = __builtin_bit_cast(s16x4, __builtin_amdgcn_ds_read_tr16_b64_v4i16((LAS v4i16_t*)vp));
;             const s16x4 hi = __builtin_bit_cast(s16x4, __builtin_amdgcn_ds_read_tr16_b64_v4i16((LAS v4i16_t*)(vp + 16 * VSTR * 2)));
;             const bf16x8 vf = (bf16x8){lo[0], lo[1], lo[2], lo[3], hi[0], hi[1], hi[2], hi[3]};
; #pragma unroll
;             for (int q = 0; q < NQ; ++q) o[I0 + q][dt] = __builtin_amdgcn_mfma_f32_16x16x32_bf16(vf, pb[q][j], o[I0 + q][dt], 0, 0, 0);
;         }
.Lsel_yB:
	v_exp_f32_e32 v212, v212
	v_exp_f32_e32 v213, v213
	v_exp_f32_e32 v214, v214
	v_exp_f32_e32 v215, v215
	v_exp_f32_e32 v216, v216
	v_exp_f32_e32 v217, v217
	v_exp_f32_e32 v218, v218
	v_exp_f32_e32 v219, v219
	v_exp_f32_e32 v220, v220
	v_exp_f32_e32 v221, v221
	v_exp_f32_e32 v222, v222
	v_exp_f32_e32 v223, v223
	v_exp_f32_e32 v224, v224
	v_exp_f32_e32 v225, v225
	v_exp_f32_e32 v226, v226
	v_exp_f32_e32 v227, v227
	s_waitcnt lgkmcnt(7)
	ds_read_b64_tr_b16 v[84:85], v196 offset:8256
	ds_read_b64_tr_b16 v[86:87], v196 offset:10816
	ds_read_b64_tr_b16 v[88:89], v196 offset:13376
	ds_read_b64_tr_b16 v[90:91], v196 offset:15936
	ds_read_b64_tr_b16 v[92:93], v196 offset:8288
	ds_read_b64_tr_b16 v[94:95], v196 offset:10848
	ds_read_b64_tr_b16 v[240:241], v196 offset:13408
	ds_read_b64_tr_b16 v[242:243], v196 offset:15968
	v_cvt_pk_bf16_f32 v232, v212, v213
	v_cvt_pk_bf16_f32 v233, v214, v215
	v_cvt_pk_bf16_f32 v234, v216, v217
	v_cvt_pk_bf16_f32 v235, v218, v219
	v_cvt_pk_bf16_f32 v236, v220, v221
	v_cvt_pk_bf16_f32 v237, v222, v223
	v_cvt_pk_bf16_f32 v238, v224, v225
	v_cvt_pk_bf16_f32 v239, v226, v227
	v_pk_add_f32 v[248:249], v[212:213], v[214:215]
	v_pk_add_f32 v[208:209], v[216:217], v[218:219]
	v_pk_add_f32 v[202:203], v[220:221], v[222:223]
	v_pk_add_f32 v[248:249], v[248:249], v[208:209]
	v_pk_add_f32 v[208:209], v[224:225], v[226:227]
	v_pk_add_f32 v[202:203], v[202:203], v[208:209]
	v_pk_add_f32 v[248:249], v[248:249], v[202:203]
	v_add_f32_e32 v248, v248, v249
	v_add_f32_e32 v134, v134, v248
	s_waitcnt lgkmcnt(14)
	v_mfma_f32_16x16x32_bf16 v[60:63], v[68:71], v[232:235], v[60:63]
	s_waitcnt lgkmcnt(12)
	v_mfma_f32_16x16x32_bf16 v[60:63], v[72:75], v[236:239], v[60:63]
	s_waitcnt lgkmcnt(10)
	v_mfma_f32_16x16x32_bf16 v[56:59], v[76:79], v[232:235], v[56:59]
	s_waitcnt lgkmcnt(8)
	v_mfma_f32_16x16x32_bf16 v[56:59], v[80:83], v[236:239], v[56:59]
	s_waitcnt lgkmcnt(6)
	v_mfma_f32_16x16x32_bf16 v[52:55], v[84:87], v[232:235], v[52:55]
	s_waitcnt lgkmcnt(4)
	v_mfma_f32_16x16x32_bf16 v[52:55], v[88:91], v[236:239], v[52:55]
	s_waitcnt lgkmcnt(2)
	v_mfma_f32_16x16x32_bf16 v[40:43], v[92:95], v[232:235], v[40:43]
	s_waitcnt lgkmcnt(0)
	v_mfma_f32_16x16x32_bf16 v[40:43], v[240:243], v[236:239], v[40:43]
	s_branch .Lsel_retB
.Lsel_maskB:
	v_add_u32_e32 v254, s94, v142
	v_sub_u32_e32 v255, v114, v254
	v_cmp_le_i32_e64 s[100:101], 0, v255
	v_cmp_le_i32_e64 s[20:21], 1, v255
	v_cmp_le_i32_e64 s[64:65], 2, v255
	v_cndmask_b32_e64 v212, v183, v212, s[100:101]
	v_cmp_le_i32_e64 s[100:101], 3, v255
	v_cndmask_b32_e64 v213, v183, v213, s[20:21]
	v_cmp_le_i32_e64 s[20:21], 16, v255
	v_cndmask_b32_e64 v214, v183, v214, s[64:65]
	v_cmp_le_i32_e64 s[64:65], 17, v255
	v_cndmask_b32_e64 v215, v183, v215, s[100:101]
	v_cmp_le_i32_e64 s[100:101], 18, v255
	v_cndmask_b32_e64 v216, v183, v216, s[20:21]
	v_cmp_le_i32_e64 s[20:21], 19, v255
	v_cndmask_b32_e64 v217, v183, v217, s[64:65]
	v_cmp_le_i32_e64 s[64:65], 32, v255
	v_cndmask_b32_e64 v218, v183, v218, s[100:101]
	v_cmp_le_i32_e64 s[100:101], 33, v255
	v_cndmask_b32_e64 v219, v183, v219, s[20:21]
	v_cmp_le_i32_e64 s[20:21], 34, v255
	v_cndmask_b32_e64 v220, v183, v220, s[64:65]
	v_cmp_le_i32_e64 s[64:65], 35, v255
	v_cndmask_b32_e64 v221, v183, v221, s[100:101]
	v_cmp_le_i32_e64 s[100:101], 48, v255
	v_cndmask_b32_e64 v222, v183, v222, s[20:21]
	v_cmp_le_i32_e64 s[20:21], 49, v255
	v_cndmask_b32_e64 v223, v183, v223, s[64:65]
	v_cmp_le_i32_e64 s[64:65], 50, v255
	v_cndmask_b32_e64 v224, v183, v224, s[100:101]
	v_cmp_le_i32_e64 s[100:101], 51, v255
	s_nop 1
	v_cndmask_b32_e64 v225, v183, v225, s[20:21]
	v_cndmask_b32_e64 v226, v183, v226, s[64:65]
	v_cndmask_b32_e64 v227, v183, v227, s[100:101]
	s_branch .Lsel_slowB
.Lsel_both:
	v_cmp_lt_f32_e64 s[12:13], s77, v160
	v_cmp_lt_f32_e64 s[6:7], s77, v161
	v_add_u32_e32 v167, s67, v139
	v_add_u32_e32 v196, s67, v143
	v_add_u32_e32 v195, v167, v141
	v_add_u32_e32 v167, v167, v140
	v_cndmask_b32_e64 v163, 0, v160, s[12:13]
	v_cndmask_b32_e64 v166, 0, v161, s[6:7]
	ds_read_b128 v[68:71], v167
	ds_read_b128 v[72:75], v195
	ds_read_b128 v[76:79], v167 offset:2048
	ds_read_b128 v[80:83], v195 offset:2048
	ds_read_b128 v[84:87], v167 offset:4096
	ds_read_b128 v[88:91], v195 offset:4096
	ds_read_b128 v[92:95], v167 offset:6144
	ds_read_b128 v[240:243], v195 offset:6144
	v_cndmask_b32_e64 v228, v183, -v163, s[8:9]
	v_mov_b32_e32 v229, v228
	v_mov_b32_e32 v230, v228
	v_mov_b32_e32 v231, v228
	v_cndmask_b32_e64 v244, v183, -v166, s[10:11]
	v_mov_b32_e32 v245, v244
	v_mov_b32_e32 v246, v244
	v_mov_b32_e32 v247, v244
	s_nop 1
	s_waitcnt lgkmcnt(7)
	v_mfma_f32_16x16x32_bf16 v[212:215], v[68:71], v[20:23], v[228:231]
	v_mfma_f32_16x16x32_bf16 v[64:67], v[68:71], v[12:15], v[244:247]
	s_waitcnt lgkmcnt(6)
	v_mfma_f32_16x16x32_bf16 v[212:215], v[72:75], v[24:27], v[212:215]
	v_mfma_f32_16x16x32_bf16 v[64:67], v[72:75], v[16:19], v[64:67]
	s_waitcnt lgkmcnt(5)
	v_mfma_f32_16x16x32_bf16 v[216:219], v[76:79], v[20:23], v[228:231]
	v_mfma_f32_16x16x32_bf16 v[96:99], v[76:79], v[12:15], v[244:247]
	s_waitcnt lgkmcnt(4)
	v_mfma_f32_16x16x32_bf16 v[216:219], v[80:83], v[24:27], v[216:219]
	v_mfma_f32_16x16x32_bf16 v[96:99], v[80:83], v[16:19], v[96:99]
	s_waitcnt lgkmcnt(3)
	v_mfma_f32_16x16x32_bf16 v[220:223], v[84:87], v[20:23], v[228:231]
	v_mfma_f32_16x16x32_bf16 v[104:107], v[84:87], v[12:15], v[244:247]
	s_waitcnt lgkmcnt(2)
	v_mfma_f32_16x16x32_bf16 v[220:223], v[88:91], v[24:27], v[220:223]
	v_mfma_f32_16x16x32_bf16 v[104:107], v[88:91], v[16:19], v[104:107]
	s_waitcnt lgkmcnt(1)
	v_mfma_f32_16x16x32_bf16 v[224:227], v[92:95], v[20:23], v[228:231]
	v_mfma_f32_16x16x32_bf16 v[108:111], v[92:95], v[12:15], v[244:247]
	s_waitcnt lgkmcnt(0)
	v_mfma_f32_16x16x32_bf16 v[224:227], v[240:243], v[24:27], v[224:227]
	v_mfma_f32_16x16x32_bf16 v[108:111], v[240:243], v[16:19], v[108:111]
	ds_read_b64_tr_b16 v[68:69], v196 offset:8192
	ds_read_b64_tr_b16 v[70:71], v196 offset:10752
	ds_read_b64_tr_b16 v[72:73], v196 offset:13312
	ds_read_b64_tr_b16 v[74:75], v196 offset:15872
	ds_read_b64_tr_b16 v[76:77], v196 offset:8224
	ds_read_b64_tr_b16 v[78:79], v196 offset:10784
	ds_read_b64_tr_b16 v[80:81], v196 offset:13344
	ds_read_b64_tr_b16 v[82:83], v196 offset:15904
	s_mov_b32 s95, 1
	s_cmp_lg_u32 s97, 0
	s_cbranch_scc1 .Lboth_mask
	v_max_i32_e32 v198, v212, v216
	v_max3_i32 v198, v220, v224, v198
	v_cmp_lt_i32_e32 vcc, s80, v198
	s_orn2_b64 vcc, vcc, s[12:13]
	s_cbranch_vccz .Lboth_chkB
	s_branch .Lsel_slowA
; #define LAS __attribute__((address_space(3)))
; template <int DQK, int MODE, bool FULL, int I0, int NQ> __device__ __forceinline__ void tile_x(LAS unsigned char* lds, const bf16x8 (&qf)[2][DQK / 32], int kbase, const int (&tpos)[2], const bool (&rowsel)[2],
;         float (&m)[2], float (&l)[2], f32x4 (&o)[2][4], f32x4 (&s)[2][4], int fr, int fq) {
;     ...
;         if (slow) {
;             float mx;
;             if (FULL) {
;                 mx = fmaxf(fmaxf(sq[0][0], sq[0][1]), fmaxf(sq[0][2], sq[0][3]));
; #pragma unroll
;                 for (int ss = 1; ss < 4; ++ss) mx = fmaxf(mx, fmaxf(fmaxf(sq[ss][0], sq[ss][1]), fmaxf(sq[ss][2], sq[ss][3])));
;             } else {
;                 mx = NEG;
; #pragma unroll
;                 for (int ss = 0; ss < 4; ++ss)
; #pragma unroll
;                     for (int i = 0; i < 4; ++i) { const bool ok = key_ok<MODE>(kbase + 16 * ss + 4 * fq + i, tpos[I0 + q], rowsel[I0 + q]); const float v = ok ? sq[ss][i] : NEG; sq[ss][i] = v; mx = fmaxf(mx, v); }
;             }
;             mx = rows_max(mx);
;             const bool need = (mo > -1e29f) ? (mx > RESCALE_THR) : (mx > -1e29f);
;             if (__any(need ? 1 : 0)) {
;                 const float delta = need ? mx : 0.f; const float mnew = need ? meff[q] + delta : mo; const float alpha = need ? __builtin_amdgcn_exp2f(mo - mnew) : 1.0f;
;                 l[I0 + q] *= alpha; m[I0 + q] = mnew;
; #pragma unroll
;                 for (int dt = 0; dt < 4; ++dt) o[I0 + q][dt] = o[I0 + q][dt] * alpha;
; #pragma unroll
;                 for (int ss = 0; ss < 4; ++ss) sq[ss] = sq[ss] - delta;
;             }
;         }
;     }
; }
; template <int I0, int NQ, int VO> __device__ __forceinline__ void tile_y(LAS unsigned char* lds, float (&l)[2], f32x4 (&o)[2][4], f32x4 (&s)[2][4], int fr, int fq) {
;     bf16x8 pb[NQ][2];
; #pragma unroll
;     for (int q = 0; q < NQ; ++q) {
;         f32x4 (&sq)[4] = s[I0 + q];
;         f32x2_t rs2 = {0.f, 0.f};
; #pragma unroll
;         for (int ss = 0; ss < 4; ++ss) {
; #pragma unroll
;             for (int i = 0; i < 4; ++i) sq[ss][i] = __builtin_amdgcn_exp2f(sq[ss][i]);
;             rs2 += (f32x2_t){sq[ss][0], sq[ss][1]}; rs2 += (f32x2_t){sq[ss][2], sq[ss][3]};
;         }
;         l[I0 + q] += rs2.x + rs2.y;
; #pragma unroll
;         for (int j = 0; j < 2; ++j) {
.Lboth_chkB:
	s_cmp_lg_u32 s97, 0
	s_cbranch_scc1 .Lboth_slowB
	v_max_i32_e32 v198, v64, v96
	v_max3_i32 v198, v104, v108, v198
	v_cmp_lt_i32_e32 vcc, s80, v198
	s_orn2_b64 vcc, vcc, s[6:7]
	s_cbranch_vccz .Lboth_y
.Lboth_slowB:
	v_max3_f32 v198, v64, v65, v66
	v_max3_f32 v198, v198, v67, v96
	v_max3_f32 v198, v198, v97, v98
	v_max3_f32 v198, v198, v99, v104
	v_max3_f32 v198, v198, v105, v106
	v_max3_f32 v198, v198, v107, v108
	v_max3_f32 v198, v198, v109, v110
	v_max_f32_e32 v198, v198, v111
	v_mov_b32_e32 v199, v198
	s_nop 1
	v_permlane16_swap_b32_e32 v198, v199
	v_max_f32_e32 v198, v198, v199
	v_mov_b32_e32 v199, v198
	s_nop 1
	v_permlane32_swap_b32_e32 v198, v199
	v_max_f32_e32 v201, v198, v199
	v_cmp_lt_f32_e64 s[20:21], s80, v201
	v_cmp_lt_f32_e64 s[64:65], s77, v201
	s_and_b64 s[20:21], s[20:21], s[6:7]
	s_andn2_b64 s[64:65], s[64:65], s[6:7]
	s_or_b64 s[14:15], s[20:21], s[64:65]
	s_cmp_lg_u64 s[14:15], 0
	s_cbranch_scc0 .Lboth_y
	v_add_f32_e32 v198, v166, v201
	v_cndmask_b32_e64 v210, 0, v201, s[14:15]
	v_cndmask_b32_e64 v252, v161, v198, s[14:15]
	v_sub_f32_e32 v198, v161, v252
	v_exp_f32_e32 v198, v198
	v_mov_b32_e32 v161, v252
	v_cndmask_b32_e64 v253, 1.0, v198, s[14:15]
	v_mul_f32_e32 v134, v134, v253
	v_mul_f32_e32 v60, v60, v253
	v_mul_f32_e32 v61, v61, v253
	v_mul_f32_e32 v62, v62, v253
	v_mul_f32_e32 v63, v63, v253
	v_mul_f32_e32 v56, v56, v253
	v_mul_f32_e32 v57, v57, v253
	v_mul_f32_e32 v58, v58, v253
	v_mul_f32_e32 v59, v59, v253
	v_mul_f32_e32 v52, v52, v253
	v_mul_f32_e32 v53, v53, v253
	v_mul_f32_e32 v54, v54, v253
	v_mul_f32_e32 v55, v55, v253
	v_mul_f32_e32 v40, v40, v253
	v_mul_f32_e32 v41, v41, v253
	v_mul_f32_e32 v42, v42, v253
	v_mul_f32_e32 v43, v43, v253
	v_sub_f32_e32 v64, v64, v210
	v_sub_f32_e32 v65, v65, v210
	v_sub_f32_e32 v66, v66, v210
	v_sub_f32_e32 v67, v67, v210
	v_sub_f32_e32 v96, v96, v210
	v_sub_f32_e32 v97, v97, v210
	v_sub_f32_e32 v98, v98, v210
	v_sub_f32_e32 v99, v99, v210
	v_sub_f32_e32 v104, v104, v210
	v_sub_f32_e32 v105, v105, v210
	v_sub_f32_e32 v106, v106, v210
	v_sub_f32_e32 v107, v107, v210
	v_sub_f32_e32 v108, v108, v210
	v_sub_f32_e32 v109, v109, v210
	v_sub_f32_e32 v110, v110, v210
	v_sub_f32_e32 v111, v111, v210
.Lboth_y:
	s_mov_b32 s95, 0
	v_exp_f32_e32 v212, v212
	v_exp_f32_e32 v213, v213
	v_exp_f32_e32 v214, v214
	v_exp_f32_e32 v215, v215
	v_exp_f32_e32 v216, v216
	v_exp_f32_e32 v217, v217
	v_exp_f32_e32 v218, v218
	v_exp_f32_e32 v219, v219
	v_exp_f32_e32 v220, v220
	v_exp_f32_e32 v221, v221
	v_exp_f32_e32 v222, v222
	v_exp_f32_e32 v223, v223
	v_exp_f32_e32 v224, v224
	v_exp_f32_e32 v225, v225
	v_exp_f32_e32 v226, v226
	v_exp_f32_e32 v227, v227
	s_waitcnt lgkmcnt(7)
	ds_read_b64_tr_b16 v[84:85], v196 offset:8256
	ds_read_b64_tr_b16 v[86:87], v196 offset:10816
	ds_read_b64_tr_b16 v[88:89], v196 offset:13376
	ds_read_b64_tr_b16 v[90:91], v196 offset:15936
	ds_read_b64_tr_b16 v[92:93], v196 offset:8288
	ds_read_b64_tr_b16 v[94:95], v196 offset:10848
	ds_read_b64_tr_b16 v[240:241], v196 offset:13408
	ds_read_b64_tr_b16 v[242:243], v196 offset:15968
	v_cvt_pk_bf16_f32 v232, v212, v213
	v_cvt_pk_bf16_f32 v233, v214, v215
	v_cvt_pk_bf16_f32 v234, v216, v217
	v_cvt_pk_bf16_f32 v235, v218, v219
	v_cvt_pk_bf16_f32 v236, v220, v221
	v_cvt_pk_bf16_f32 v237, v222, v223
	v_cvt_pk_bf16_f32 v238, v224, v225
	v_cvt_pk_bf16_f32 v239, v226, v227
	v_exp_f32_e32 v64, v64
	v_exp_f32_e32 v65, v65
	v_exp_f32_e32 v66, v66
	v_exp_f32_e32 v67, v67
	v_exp_f32_e32 v96, v96
	v_exp_f32_e32 v97, v97
	v_exp_f32_e32 v98, v98
	v_exp_f32_e32 v99, v99
	v_exp_f32_e32 v104, v104
	v_exp_f32_e32 v105, v105
	v_exp_f32_e32 v106, v106
	v_exp_f32_e32 v107, v107
	v_exp_f32_e32 v108, v108
	v_exp_f32_e32 v109, v109
	v_exp_f32_e32 v110, v110
	v_exp_f32_e32 v111, v111
	v_pk_add_f32 v[248:249], v[212:213], v[214:215]
	v_pk_add_f32 v[208:209], v[216:217], v[218:219]
	v_pk_add_f32 v[202:203], v[220:221], v[222:223]
	v_pk_add_f32 v[248:249], v[248:249], v[208:209]
	v_pk_add_f32 v[208:209], v[224:225], v[226:227]
	v_pk_add_f32 v[202:203], v[202:203], v[208:209]
	v_pk_add_f32 v[248:249], v[248:249], v[202:203]
	v_add_f32_e32 v248, v248, v249
	v_add_f32_e32 v135, v135, v248
	v_cvt_pk_bf16_f32 v156, v64, v65
	v_cvt_pk_bf16_f32 v157, v66, v67
	v_cvt_pk_bf16_f32 v158, v96, v97
	v_cvt_pk_bf16_f32 v159, v98, v99
	v_cvt_pk_bf16_f32 v204, v104, v105
	v_cvt_pk_bf16_f32 v205, v106, v107
	v_cvt_pk_bf16_f32 v206, v108, v109
	v_cvt_pk_bf16_f32 v207, v110, v111
	v_pk_add_f32 v[248:249], v[64:65], v[66:67]
	v_pk_add_f32 v[208:209], v[96:97], v[98:99]
	v_pk_add_f32 v[202:203], v[104:105], v[106:107]
	v_pk_add_f32 v[248:249], v[248:249], v[208:209]
	v_pk_add_f32 v[208:209], v[108:109], v[110:111]
	v_pk_add_f32 v[202:203], v[202:203], v[208:209]
	v_pk_add_f32 v[248:249], v[248:249], v[202:203]
	v_add_f32_e32 v248, v248, v249
	v_add_f32_e32 v134, v134, v248
	s_waitcnt lgkmcnt(14)
	v_mfma_f32_16x16x32_bf16 v[28:31], v[68:71], v[232:235], v[28:31]
	v_mfma_f32_16x16x32_bf16 v[60:63], v[68:71], v[156:159], v[60:63]
	s_waitcnt lgkmcnt(12)
	v_mfma_f32_16x16x32_bf16 v[28:31], v[72:75], v[236:239], v[28:31]
	v_mfma_f32_16x16x32_bf16 v[60:63], v[72:75], v[204:207], v[60:63]
	s_waitcnt lgkmcnt(10)
	v_mfma_f32_16x16x32_bf16 v[8:11], v[76:79], v[232:235], v[8:11]
	v_mfma_f32_16x16x32_bf16 v[56:59], v[76:79], v[156:159], v[56:59]
	s_waitcnt lgkmcnt(8)
	v_mfma_f32_16x16x32_bf16 v[8:11], v[80:83], v[236:239], v[8:11]
	v_mfma_f32_16x16x32_bf16 v[56:59], v[80:83], v[204:207], v[56:59]
	s_waitcnt lgkmcnt(6)
	v_mfma_f32_16x16x32_bf16 v[4:7], v[84:87], v[232:235], v[4:7]
	v_mfma_f32_16x16x32_bf16 v[52:55], v[84:87], v[156:159], v[52:55]
	s_waitcnt lgkmcnt(4)
	v_mfma_f32_16x16x32_bf16 v[4:7], v[88:91], v[236:239], v[4:7]
	v_mfma_f32_16x16x32_bf16 v[52:55], v[88:91], v[204:207], v[52:55]
	s_waitcnt lgkmcnt(2)
	v_mfma_f32_16x16x32_bf16 v[0:3], v[92:95], v[232:235], v[0:3]
	v_mfma_f32_16x16x32_bf16 v[40:43], v[92:95], v[156:159], v[40:43]
	s_waitcnt lgkmcnt(0)
	v_mfma_f32_16x16x32_bf16 v[0:3], v[240:243], v[236:239], v[0:3]
	v_mfma_f32_16x16x32_bf16 v[40:43], v[240:243], v[204:207], v[40:43]
	s_branch .Lsel_retB
; template <int MODE> __device__ __forceinline__ bool key_ok(int kpos, int tpos, bool rowsel) {
;     if (MODE == CAUSAL) return kpos <= tpos;
;     if (MODE == WINDOW) return kpos <= tpos && kpos + 512 > tpos;
;     if (MODE == CMP) return 16 * kpos + 31 <= tpos;
;     return rowsel && kpos <= tpos;
; }
; template <int DQK, int MODE, bool FULL, int I0, int NQ> __device__ __forceinline__ void tile_x(LAS unsigned char* lds, const bf16x8 (&qf)[2][DQK / 32], int kbase, const int (&tpos)[2], const bool (&rowsel)[2],
;         float (&m)[2], float (&l)[2], f32x4 (&o)[2][4], f32x4 (&s)[2][4], int fr, int fq) {
;     ...
;             } else {
;                 mx = NEG;
; #pragma unroll
;                 for (int ss = 0; ss < 4; ++ss)
; #pragma unroll
;                     for (int i = 0; i < 4; ++i) { const bool ok = key_ok<MODE>(kbase + 16 * ss + 4 * fq + i, tpos[I0 + q], rowsel[I0 + q]); const float v = ok ? sq[ss][i] : NEG; sq[ss][i] = v; mx = fmaxf(mx, v); }
;             }
.Lboth_mask:
	v_add_u32_e32 v254, s94, v142
	v_sub_u32_e32 v255, v116, v254
	v_cmp_le_i32_e64 s[100:101], 0, v255
	v_cmp_le_i32_e64 s[20:21], 1, v255
	v_cmp_le_i32_e64 s[64:65], 2, v255
	v_cndmask_b32_e64 v212, v183, v212, s[100:101]
	v_cmp_le_i32_e64 s[100:101], 3, v255
	v_cndmask_b32_e64 v213, v183, v213, s[20:21]
	v_cmp_le_i32_e64 s[20:21], 16, v255
	v_cndmask_b32_e64 v214, v183, v214, s[64:65]
	v_cmp_le_i32_e64 s[64:65], 17, v255
	v_cndmask_b32_e64 v215, v183, v215, s[100:101]
	v_cmp_le_i32_e64 s[100:101], 18, v255
	v_cndmask_b32_e64 v216, v183, v216, s[20:21]
	v_cmp_le_i32_e64 s[20:21], 19, v255
	v_cndmask_b32_e64 v217, v183, v217, s[64:65]
	v_cmp_le_i32_e64 s[64:65], 32, v255
	v_cndmask_b32_e64 v218, v183, v218, s[100:101]
	v_cmp_le_i32_e64 s[100:101], 33, v255
	v_cndmask_b32_e64 v219, v183, v219, s[20:21]
	v_cmp_le_i32_e64 s[20:21], 34, v255
	v_cndmask_b32_e64 v220, v183, v220, s[64:65]
	v_cmp_le_i32_e64 s[64:65], 35, v255
	v_cndmask_b32_e64 v221, v183, v221, s[100:101]
	v_cmp_le_i32_e64 s[100:101], 48, v255
	v_cndmask_b32_e64 v222, v183, v222, s[20:21]
	v_cmp_le_i32_e64 s[20:21], 49, v255
	v_cndmask_b32_e64 v223, v183, v223, s[64:65]
	v_cmp_le_i32_e64 s[64:65], 50, v255
	v_cndmask_b32_e64 v224, v183, v224, s[100:101]
	v_cmp_le_i32_e64 s[100:101], 51, v255
	s_nop 1
	v_cndmask_b32_e64 v225, v183, v225, s[20:21]
	v_cndmask_b32_e64 v226, v183, v226, s[64:65]
	v_cndmask_b32_e64 v227, v183, v227, s[100:101]
	v_add_u32_e32 v254, s94, v142
	v_sub_u32_e32 v255, v114, v254
	v_cmp_le_i32_e64 s[100:101], 0, v255
	v_cmp_le_i32_e64 s[20:21], 1, v255
	v_cmp_le_i32_e64 s[64:65], 2, v255
	v_cndmask_b32_e64 v64, v183, v64, s[100:101]
	v_cmp_le_i32_e64 s[100:101], 3, v255
	v_cndmask_b32_e64 v65, v183, v65, s[20:21]
	v_cmp_le_i32_e64 s[20:21], 16, v255
	v_cndmask_b32_e64 v66, v183, v66, s[64:65]
	v_cmp_le_i32_e64 s[64:65], 17, v255
	v_cndmask_b32_e64 v67, v183, v67, s[100:101]
	v_cmp_le_i32_e64 s[100:101], 18, v255
	v_cndmask_b32_e64 v96, v183, v96, s[20:21]
	v_cmp_le_i32_e64 s[20:21], 19, v255
	v_cndmask_b32_e64 v97, v183, v97, s[64:65]
	v_cmp_le_i32_e64 s[64:65], 32, v255
	v_cndmask_b32_e64 v98, v183, v98, s[100:101]
	v_cmp_le_i32_e64 s[100:101], 33, v255
	v_cndmask_b32_e64 v99, v183, v99, s[20:21]
	v_cmp_le_i32_e64 s[20:21], 34, v255
	v_cndmask_b32_e64 v104, v183, v104, s[64:65]
	v_cmp_le_i32_e64 s[64:65], 35, v255
	v_cndmask_b32_e64 v105, v183, v105, s[100:101]
	v_cmp_le_i32_e64 s[100:101], 48, v255
	v_cndmask_b32_e64 v106, v183, v106, s[20:21]
	v_cmp_le_i32_e64 s[20:21], 49, v255
	v_cndmask_b32_e64 v107, v183, v107, s[64:65]
	v_cmp_le_i32_e64 s[64:65], 50, v255
	v_cndmask_b32_e64 v108, v183, v108, s[100:101]
	v_cmp_le_i32_e64 s[100:101], 51, v255
	s_nop 1
	v_cndmask_b32_e64 v109, v183, v109, s[20:21]
	v_cndmask_b32_e64 v110, v183, v110, s[64:65]
	v_cndmask_b32_e64 v111, v183, v111, s[100:101]
	s_branch .Lsel_slowA

; __device__ __forceinline__ unsigned cvt_pk_bf16(float lo, float hi) { unsigned r; asm volatile("v_cvt_pk_bf16_f32 %0, %1, %2" : "=v"(r) : "v"(lo), "v"(hi)); return r; }
;     __device__ __forceinline__ void fused(f32x4 (&acc)[2][2][4][2], const Unit& u, int wr, int wc, int fr, int fq, PG8_LAS unsigned char* lds, int wid, int lane) const {
;     ...
; #pragma unroll
;         for (int bj = 0; bj < 2; ++bj)
; #pragma unroll
;             for (int n = 0; n < 2; ++n) {
;                 const int col = col0 + bj * HALF + n * 16;
;                 const f32x4 lg = *(const f32x4*)(lng + col), lb = *(const f32x4*)(lnb + col);
;                 f32x4 sc1 = (f32x4){1.f, 1.f, 1.f, 1.f}, sh = (f32x4){0.f, 0.f, 0.f, 0.f};
;                 if (DO_U) { sc1 = *(const f32x4*)(msc + mo + col) + 1.0f; sh = *(const f32x4*)(msh + mo + col); }
; #pragma unroll
;                 for (int ai = 0; ai < 2; ++ai)
; #pragma unroll
;                     for (int m = 0; m < 4; ++m) { const int r = ai * HALF + wr * 64 + m * 16 + fr; const f32x2v sr = S[r]; const size_t off = (size_t)(u.pm * BM + r) * 1024 + col;
;                         f32x4 y = (acc[ai][bj][m][n] - sr.x) * sr.y * lg + lb; if (bad) y = (f32x4){qnan, qnan, qnan, qnan};
;                         *(f32x4*)(out + off) = y;
;                         if (DO_U) { const f32x4 uu = y * sc1 + sh; u32x2v w; w.x = cvt_pk_bf16(uu[0], uu[1]); w.y = cvt_pk_bf16(uu[2], uu[3]); *(u32x2v*)(U + off) = w; } }
.LBB0_1530:
	s_or_b64 exec, exec, s[4:5]
	s_mov_b64 s[0:1], 0x2000
	v_lshl_add_u64 v[144:145], v[0:1], 0, s[0:1]
	v_lshl_add_u64 v[142:143], v[2:3], 0, s[0:1]
	s_waitcnt lgkmcnt(0)
	s_barrier
	v_lshl_add_u64 v[0:1], v[144:145], 0, v[140:141]
	v_lshl_add_u64 v[132:133], v[142:143], 0, v[140:141]
	global_load_dwordx4 v[0:3], v[0:1], off
	v_lshl_add_u32 v139, v162, 3, 0
	global_load_dwordx4 v[132:135], v[132:133], off
	ds_read_b64 v[154:155], v139 offset:8192
	v_add_u32_e32 v150, s16, v162
	v_ashrrev_i32_e32 v151, 31, v150
	v_lshlrev_b64 v[148:149], 12, v[150:151]
	v_mov_b32_e32 v152, 0x7fc00000
	s_waitcnt lgkmcnt(0)
	v_sub_f32_e32 v83, v83, v154
	v_sub_f32_e32 v82, v82, v154
	v_sub_f32_e32 v81, v81, v154
	v_sub_f32_e32 v80, v80, v154
	v_pk_mul_f32 v[80:81], v[154:155], v[80:81] op_sel:[1,0]
	v_pk_mul_f32 v[82:83], v[154:155], v[82:83] op_sel:[1,0]
	v_lshl_add_u64 v[148:149], v[136:137], 0, v[148:149]
	v_cmp_eq_u32_e32 vcc, 0, v146
	v_lshl_add_u64 v[148:149], v[148:149], 0, v[140:141]
	v_add_u32_e32 v156, 16, v150
	v_ashrrev_i32_e32 v157, 31, v156
	v_add_u32_e32 v158, 32, v150
	v_ashrrev_i32_e32 v159, 31, v158
	v_add_u32_e32 v160, 48, v150
	v_ashrrev_i32_e32 v161, 31, v160
	v_add_u32_e32 v162, 0x80, v150
	v_ashrrev_i32_e32 v163, 31, v162
	v_add_u32_e32 v164, 0x90, v150
	v_ashrrev_i32_e32 v165, 31, v164
	s_waitcnt vmcnt(0)
	v_pk_fma_f32 v[82:83], v[2:3], v[82:83], v[134:135]
	v_pk_fma_f32 v[80:81], v[0:1], v[80:81], v[132:133]
	v_cndmask_b32_e32 v83, v152, v83, vcc
	v_cndmask_b32_e32 v82, v152, v82, vcc
	v_cndmask_b32_e32 v81, v152, v81, vcc
	v_cndmask_b32_e32 v80, v152, v80, vcc
	global_store_dwordx4 v[148:149], v[80:83], off sc0 sc1 nt
	ds_read_b64 v[80:81], v139 offset:8320
	s_waitcnt lgkmcnt(0)
	v_sub_f32_e32 v89, v89, v80
	v_lshlrev_b64 v[82:83], 12, v[156:157]
	v_lshl_add_u64 v[82:83], v[136:137], 0, v[82:83]
	v_lshl_add_u64 v[146:147], v[82:83], 0, v[140:141]
	v_sub_f32_e32 v83, v91, v80
	v_sub_f32_e32 v82, v90, v80
	v_sub_f32_e32 v88, v88, v80
	v_pk_mul_f32 v[88:89], v[80:81], v[88:89] op_sel:[1,0]
	v_pk_mul_f32 v[80:81], v[80:81], v[82:83] op_sel:[1,0]
	v_pk_fma_f32 v[88:89], v[0:1], v[88:89], v[132:133]
	v_pk_fma_f32 v[80:81], v[2:3], v[80:81], v[134:135]
	s_nop 0
	v_cndmask_b32_e32 v83, v152, v81, vcc
	v_cndmask_b32_e32 v82, v152, v80, vcc
	v_cndmask_b32_e32 v81, v152, v89, vcc
	v_cndmask_b32_e32 v80, v152, v88, vcc
	global_store_dwordx4 v[146:147], v[80:83], off sc0 sc1 nt
	ds_read_b64 v[80:81], v139 offset:8448
	s_waitcnt lgkmcnt(0)
	v_sub_f32_e32 v91, v101, v80
	v_lshlrev_b64 v[82:83], 12, v[158:159]
	v_lshl_add_u64 v[82:83], v[136:137], 0, v[82:83]
	v_lshl_add_u64 v[88:89], v[82:83], 0, v[140:141]
	v_sub_f32_e32 v83, v103, v80
	v_sub_f32_e32 v82, v102, v80
	v_sub_f32_e32 v90, v100, v80
	v_pk_mul_f32 v[90:91], v[80:81], v[90:91] op_sel:[1,0]
	v_pk_mul_f32 v[80:81], v[80:81], v[82:83] op_sel:[1,0]
	v_pk_fma_f32 v[90:91], v[0:1], v[90:91], v[132:133]
	v_pk_fma_f32 v[80:81], v[2:3], v[80:81], v[134:135]
	s_nop 0
	v_cndmask_b32_e32 v83, v152, v81, vcc
	v_cndmask_b32_e32 v82, v152, v80, vcc
	v_cndmask_b32_e32 v81, v152, v91, vcc
	v_cndmask_b32_e32 v80, v152, v90, vcc
	global_store_dwordx4 v[88:89], v[80:83], off sc0 sc1 nt
	ds_read_b64 v[80:81], v139 offset:8576
	s_waitcnt lgkmcnt(0)
	v_sub_f32_e32 v91, v107, v80
	v_sub_f32_e32 v90, v106, v80
	v_sub_f32_e32 v101, v105, v80
	v_sub_f32_e32 v100, v104, v80
	v_lshlrev_b64 v[82:83], 12, v[160:161]
	v_pk_mul_f32 v[100:101], v[80:81], v[100:101] op_sel:[1,0]
	v_pk_mul_f32 v[80:81], v[80:81], v[90:91] op_sel:[1,0]
	v_lshl_add_u64 v[82:83], v[136:137], 0, v[82:83]
	v_pk_fma_f32 v[80:81], v[2:3], v[80:81], v[134:135]
	v_pk_fma_f32 v[90:91], v[0:1], v[100:101], v[132:133]
	v_lshl_add_u64 v[82:83], v[82:83], 0, v[140:141]
	v_cndmask_b32_e32 v103, v152, v81, vcc
	v_cndmask_b32_e32 v102, v152, v80, vcc
	v_cndmask_b32_e32 v101, v152, v91, vcc
	v_cndmask_b32_e32 v100, v152, v90, vcc
	global_store_dwordx4 v[82:83], v[100:103], off sc0 sc1 nt
	ds_read_b64 v[90:91], v139 offset:9216
	v_lshlrev_b64 v[80:81], 12, v[162:163]
	v_lshl_add_u64 v[80:81], v[136:137], 0, v[80:81]
	v_lshl_add_u64 v[80:81], v[80:81], 0, v[140:141]
	s_waitcnt lgkmcnt(0)
	v_sub_f32_e32 v101, v115, v90
	v_sub_f32_e32 v100, v114, v90
	v_sub_f32_e32 v103, v113, v90
	v_sub_f32_e32 v102, v112, v90
	v_pk_mul_f32 v[102:103], v[90:91], v[102:103] op_sel:[1,0]
	v_pk_mul_f32 v[90:91], v[90:91], v[100:101] op_sel:[1,0]
	v_pk_fma_f32 v[100:101], v[0:1], v[102:103], v[132:133]
	v_pk_fma_f32 v[90:91], v[2:3], v[90:91], v[134:135]
	v_cndmask_b32_e32 v101, v152, v101, vcc
	v_cndmask_b32_e32 v103, v152, v91, vcc
	v_cndmask_b32_e32 v102, v152, v90, vcc
	v_cndmask_b32_e32 v100, v152, v100, vcc
	global_store_dwordx4 v[80:81], v[100:103], off sc0 sc1 nt
	ds_read_b64 v[100:101], v139 offset:9344
	v_lshlrev_b64 v[90:91], 12, v[164:165]
	v_lshl_add_u64 v[90:91], v[136:137], 0, v[90:91]
	v_lshl_add_u64 v[90:91], v[90:91], 0, v[140:141]
	s_waitcnt lgkmcnt(0)
	v_sub_f32_e32 v103, v123, v100
	v_sub_f32_e32 v102, v122, v100
	v_sub_f32_e32 v105, v121, v100
	v_sub_f32_e32 v104, v120, v100
	v_pk_mul_f32 v[104:105], v[100:101], v[104:105] op_sel:[1,0]
	v_pk_mul_f32 v[100:101], v[100:101], v[102:103] op_sel:[1,0]
	v_pk_fma_f32 v[104:105], v[0:1], v[104:105], v[132:133]
	v_pk_fma_f32 v[100:101], v[2:3], v[100:101], v[134:135]
	s_nop 0
	v_cndmask_b32_e32 v103, v152, v101, vcc
	v_cndmask_b32_e32 v102, v152, v100, vcc
	v_cndmask_b32_e32 v101, v152, v105, vcc
	v_cndmask_b32_e32 v100, v152, v104, vcc
	global_store_dwordx4 v[90:91], v[100:103], off sc0 sc1 nt
	ds_read_b64 v[100:101], v139 offset:9472
	s_waitcnt lgkmcnt(0)
; __device__ __forceinline__ unsigned cvt_pk_bf16(float lo, float hi) { unsigned r; asm volatile("v_cvt_pk_bf16_f32 %0, %1, %2" : "=v"(r) : "v"(lo), "v"(hi)); return r; }
;     __device__ __forceinline__ void fused(f32x4 (&acc)[2][2][4][2], const Unit& u, int wr, int wc, int fr, int fq, PG8_LAS unsigned char* lds, int wid, int lane) const {
;     ...
; #pragma unroll
;         for (int bj = 0; bj < 2; ++bj)
; #pragma unroll
;             for (int n = 0; n < 2; ++n) {
;                 const int col = col0 + bj * HALF + n * 16;
;                 const f32x4 lg = *(const f32x4*)(lng + col), lb = *(const f32x4*)(lnb + col);
;                 f32x4 sc1 = (f32x4){1.f, 1.f, 1.f, 1.f}, sh = (f32x4){0.f, 0.f, 0.f, 0.f};
;                 if (DO_U) { sc1 = *(const f32x4*)(msc + mo + col) + 1.0f; sh = *(const f32x4*)(msh + mo + col); }
; #pragma unroll
;                 for (int ai = 0; ai < 2; ++ai)
; #pragma unroll
;                     for (int m = 0; m < 4; ++m) { const int r = ai * HALF + wr * 64 + m * 16 + fr; const f32x2v sr = S[r]; const size_t off = (size_t)(u.pm * BM + r) * 1024 + col;
;                         f32x4 y = (acc[ai][bj][m][n] - sr.x) * sr.y * lg + lb; if (bad) y = (f32x4){qnan, qnan, qnan, qnan};
;                         *(f32x4*)(out + off) = y;
;                         if (DO_U) { const f32x4 uu = y * sc1 + sh; u32x2v w; w.x = cvt_pk_bf16(uu[0], uu[1]); w.y = cvt_pk_bf16(uu[2], uu[3]); *(u32x2v*)(U + off) = w; } }
	v_sub_f32_e32 v105, v129, v100
	v_add_u32_e32 v102, 0xa0, v150
	v_ashrrev_i32_e32 v103, 31, v102
	v_lshlrev_b64 v[102:103], 12, v[102:103]
	v_lshl_add_u64 v[106:107], v[136:137], 0, v[102:103]
	v_sub_f32_e32 v103, v131, v100
	v_sub_f32_e32 v102, v130, v100
	v_sub_f32_e32 v104, v128, v100
	v_pk_mul_f32 v[104:105], v[100:101], v[104:105] op_sel:[1,0]
	v_pk_mul_f32 v[100:101], v[100:101], v[102:103] op_sel:[1,0]
	v_pk_fma_f32 v[102:103], v[0:1], v[104:105], v[132:133]
	v_pk_fma_f32 v[100:101], v[2:3], v[100:101], v[134:135]
	v_cndmask_b32_e32 v103, v152, v103, vcc
	v_cndmask_b32_e32 v105, v152, v101, vcc
	v_cndmask_b32_e32 v104, v152, v100, vcc
	v_cndmask_b32_e32 v102, v152, v102, vcc
	v_lshl_add_u64 v[100:101], v[106:107], 0, v[140:141]
	global_store_dwordx4 v[100:101], v[102:105], off sc0 sc1 nt
	ds_read_b64 v[102:103], v139 offset:9600
	v_add_u32_e32 v106, 0xb0, v150
	v_ashrrev_i32_e32 v107, 31, v106
	s_waitcnt lgkmcnt(0)
	v_sub_f32_e32 v105, v127, v102
	v_sub_f32_e32 v104, v126, v102
	v_sub_f32_e32 v113, v125, v102
	v_sub_f32_e32 v112, v124, v102
	v_pk_mul_f32 v[112:113], v[102:103], v[112:113] op_sel:[1,0]
	v_pk_mul_f32 v[102:103], v[102:103], v[104:105] op_sel:[1,0]
	v_pk_fma_f32 v[0:1], v[0:1], v[112:113], v[132:133]
	v_pk_fma_f32 v[2:3], v[2:3], v[102:103], v[134:135]
	v_cndmask_b32_e32 v103, v152, v1, vcc
	v_cndmask_b32_e32 v104, v152, v2, vcc
	v_cndmask_b32_e32 v102, v152, v0, vcc
	v_lshlrev_b64 v[0:1], 12, v[106:107]
	v_or_b32_e32 v2, 16, v138
	v_cndmask_b32_e32 v105, v152, v3, vcc
	v_lshl_add_u64 v[0:1], v[136:137], 0, v[0:1]
	v_ashrrev_i32_e32 v3, 31, v2
	v_lshl_add_u64 v[0:1], v[0:1], 0, v[140:141]
	v_lshlrev_b64 v[2:3], 2, v[2:3]
	global_store_dwordx4 v[0:1], v[102:105], off sc0 sc1 nt
	s_nop 1
	v_lshl_add_u64 v[102:103], v[144:145], 0, v[2:3]
	v_lshl_add_u64 v[2:3], v[142:143], 0, v[2:3]
	global_load_dwordx4 v[102:105], v[102:103], off
	s_nop 0
	global_load_dwordx4 v[112:115], v[2:3], off
	ds_read_b64 v[2:3], v139 offset:8192
	s_waitcnt lgkmcnt(0)
	v_sub_f32_e32 v47, v47, v2
	v_sub_f32_e32 v46, v46, v2
	v_sub_f32_e32 v45, v45, v2
	v_sub_f32_e32 v44, v44, v2
	v_pk_mul_f32 v[44:45], v[2:3], v[44:45] op_sel:[1,0]
	v_pk_mul_f32 v[2:3], v[2:3], v[46:47] op_sel:[1,0]
	s_waitcnt vmcnt(0)
	v_pk_fma_f32 v[44:45], v[102:103], v[44:45], v[112:113]
	v_pk_fma_f32 v[2:3], v[104:105], v[2:3], v[114:115]
	v_cndmask_b32_e32 v45, v152, v45, vcc
	v_cndmask_b32_e32 v47, v152, v3, vcc
	v_cndmask_b32_e32 v46, v152, v2, vcc
	v_cndmask_b32_e32 v44, v152, v44, vcc
	global_store_dwordx4 v[148:149], v[44:47], off offset:64 sc0 sc1 nt
	ds_read_b64 v[2:3], v139 offset:8320
	s_waitcnt lgkmcnt(0)
	v_sub_f32_e32 v45, v59, v2
	v_sub_f32_e32 v44, v58, v2
	v_sub_f32_e32 v47, v57, v2
	v_sub_f32_e32 v46, v56, v2
	v_pk_mul_f32 v[46:47], v[2:3], v[46:47] op_sel:[1,0]
	v_pk_mul_f32 v[2:3], v[2:3], v[44:45] op_sel:[1,0]
	v_pk_fma_f32 v[44:45], v[102:103], v[46:47], v[112:113]
	v_pk_fma_f32 v[2:3], v[104:105], v[2:3], v[114:115]
	v_cndmask_b32_e32 v45, v152, v45, vcc
	v_cndmask_b32_e32 v47, v152, v3, vcc
	v_cndmask_b32_e32 v46, v152, v2, vcc
	v_cndmask_b32_e32 v44, v152, v44, vcc
	global_store_dwordx4 v[146:147], v[44:47], off offset:64 sc0 sc1 nt
	ds_read_b64 v[2:3], v139 offset:8448
	v_or_b32_e32 v56, 0x80, v138
	v_ashrrev_i32_e32 v57, 31, v56
	s_waitcnt lgkmcnt(0)
	v_sub_f32_e32 v45, v71, v2
	v_sub_f32_e32 v44, v70, v2
	v_sub_f32_e32 v47, v69, v2
	v_sub_f32_e32 v46, v68, v2
	v_pk_mul_f32 v[46:47], v[2:3], v[46:47] op_sel:[1,0]
	v_pk_mul_f32 v[2:3], v[2:3], v[44:45] op_sel:[1,0]
	v_pk_fma_f32 v[44:45], v[102:103], v[46:47], v[112:113]
	v_pk_fma_f32 v[2:3], v[104:105], v[2:3], v[114:115]
	v_cndmask_b32_e32 v45, v152, v45, vcc
	v_cndmask_b32_e32 v47, v152, v3, vcc
	v_cndmask_b32_e32 v46, v152, v2, vcc
	v_cndmask_b32_e32 v44, v152, v44, vcc
	global_store_dwordx4 v[88:89], v[44:47], off offset:64 sc0 sc1 nt
	ds_read_b64 v[2:3], v139 offset:8576
	s_waitcnt lgkmcnt(0)
	v_sub_f32_e32 v45, v75, v2
	v_sub_f32_e32 v44, v74, v2
	v_sub_f32_e32 v47, v73, v2
	v_sub_f32_e32 v46, v72, v2
	v_pk_mul_f32 v[46:47], v[2:3], v[46:47] op_sel:[1,0]
	v_pk_mul_f32 v[2:3], v[2:3], v[44:45] op_sel:[1,0]
	v_pk_fma_f32 v[44:45], v[102:103], v[46:47], v[112:113]
	v_pk_fma_f32 v[2:3], v[104:105], v[2:3], v[114:115]
	v_cndmask_b32_e32 v45, v152, v45, vcc
	v_cndmask_b32_e32 v47, v152, v3, vcc
	v_cndmask_b32_e32 v46, v152, v2, vcc
	v_cndmask_b32_e32 v44, v152, v44, vcc
	global_store_dwordx4 v[82:83], v[44:47], off offset:64 sc0 sc1 nt
	ds_read_b64 v[2:3], v139 offset:9216
	s_waitcnt lgkmcnt(0)
	v_sub_f32_e32 v45, v87, v2
	v_sub_f32_e32 v44, v86, v2
	v_sub_f32_e32 v47, v85, v2
	v_sub_f32_e32 v46, v84, v2
	v_pk_mul_f32 v[46:47], v[2:3], v[46:47] op_sel:[1,0]
	v_pk_mul_f32 v[2:3], v[2:3], v[44:45] op_sel:[1,0]
	v_pk_fma_f32 v[44:45], v[102:103], v[46:47], v[112:113]
	v_pk_fma_f32 v[2:3], v[104:105], v[2:3], v[114:115]
	v_cndmask_b32_e32 v45, v152, v45, vcc
	v_cndmask_b32_e32 v47, v152, v3, vcc
	v_cndmask_b32_e32 v46, v152, v2, vcc
	v_cndmask_b32_e32 v44, v152, v44, vcc
	global_store_dwordx4 v[80:81], v[44:47], off offset:64 sc0 sc1 nt
	ds_read_b64 v[2:3], v139 offset:9344
	s_waitcnt lgkmcnt(0)
	v_sub_f32_e32 v45, v99, v2
	v_sub_f32_e32 v44, v98, v2
	v_sub_f32_e32 v47, v97, v2
	v_sub_f32_e32 v46, v96, v2
	v_pk_mul_f32 v[46:47], v[2:3], v[46:47] op_sel:[1,0]
	v_pk_mul_f32 v[2:3], v[2:3], v[44:45] op_sel:[1,0]
	v_pk_fma_f32 v[44:45], v[102:103], v[46:47], v[112:113]
	v_pk_fma_f32 v[2:3], v[104:105], v[2:3], v[114:115]
	v_cndmask_b32_e32 v45, v152, v45, vcc
	v_cndmask_b32_e32 v47, v152, v3, vcc
	v_cndmask_b32_e32 v46, v152, v2, vcc
	v_cndmask_b32_e32 v44, v152, v44, vcc
	global_store_dwordx4 v[90:91], v[44:47], off offset:64 sc0 sc1 nt
	ds_read_b64 v[2:3], v139 offset:9472
	s_waitcnt lgkmcnt(0)
; __device__ __forceinline__ unsigned cvt_pk_bf16(float lo, float hi) { unsigned r; asm volatile("v_cvt_pk_bf16_f32 %0, %1, %2" : "=v"(r) : "v"(lo), "v"(hi)); return r; }
;     __device__ __forceinline__ void fused(f32x4 (&acc)[2][2][4][2], const Unit& u, int wr, int wc, int fr, int fq, PG8_LAS unsigned char* lds, int wid, int lane) const {
;     ...
; #pragma unroll
;         for (int bj = 0; bj < 2; ++bj)
; #pragma unroll
;             for (int n = 0; n < 2; ++n) {
;                 const int col = col0 + bj * HALF + n * 16;
;                 const f32x4 lg = *(const f32x4*)(lng + col), lb = *(const f32x4*)(lnb + col);
;                 f32x4 sc1 = (f32x4){1.f, 1.f, 1.f, 1.f}, sh = (f32x4){0.f, 0.f, 0.f, 0.f};
;                 if (DO_U) { sc1 = *(const f32x4*)(msc + mo + col) + 1.0f; sh = *(const f32x4*)(msh + mo + col); }
; #pragma unroll
;                 for (int ai = 0; ai < 2; ++ai)
; #pragma unroll
;                     for (int m = 0; m < 4; ++m) { const int r = ai * HALF + wr * 64 + m * 16 + fr; const f32x2v sr = S[r]; const size_t off = (size_t)(u.pm * BM + r) * 1024 + col;
;                         f32x4 y = (acc[ai][bj][m][n] - sr.x) * sr.y * lg + lb; if (bad) y = (f32x4){qnan, qnan, qnan, qnan};
;                         *(f32x4*)(out + off) = y;
;                         if (DO_U) { const f32x4 uu = y * sc1 + sh; u32x2v w; w.x = cvt_pk_bf16(uu[0], uu[1]); w.y = cvt_pk_bf16(uu[2], uu[3]); *(u32x2v*)(U + off) = w; } }
	v_sub_f32_e32 v45, v111, v2
	v_sub_f32_e32 v44, v110, v2
	v_sub_f32_e32 v47, v109, v2
	v_sub_f32_e32 v46, v108, v2
	v_pk_mul_f32 v[46:47], v[2:3], v[46:47] op_sel:[1,0]
	v_pk_mul_f32 v[2:3], v[2:3], v[44:45] op_sel:[1,0]
	v_pk_fma_f32 v[44:45], v[102:103], v[46:47], v[112:113]
	v_pk_fma_f32 v[2:3], v[104:105], v[2:3], v[114:115]
	v_cndmask_b32_e32 v45, v152, v45, vcc
	v_cndmask_b32_e32 v47, v152, v3, vcc
	v_cndmask_b32_e32 v46, v152, v2, vcc
	v_cndmask_b32_e32 v44, v152, v44, vcc
	global_store_dwordx4 v[100:101], v[44:47], off offset:64 sc0 sc1 nt
	ds_read_b64 v[2:3], v139 offset:9600
	s_nop 0
	v_lshlrev_b64 v[44:45], 2, v[56:57]
	v_lshl_add_u64 v[56:57], v[144:145], 0, v[44:45]
	v_lshl_add_u64 v[58:59], v[142:143], 0, v[44:45]
	s_waitcnt lgkmcnt(0)
	v_sub_f32_e32 v45, v119, v2
	v_sub_f32_e32 v44, v118, v2
	v_sub_f32_e32 v47, v117, v2
	v_sub_f32_e32 v46, v116, v2
	v_pk_mul_f32 v[46:47], v[2:3], v[46:47] op_sel:[1,0]
	v_pk_mul_f32 v[2:3], v[2:3], v[44:45] op_sel:[1,0]
	v_pk_fma_f32 v[44:45], v[102:103], v[46:47], v[112:113]
	v_pk_fma_f32 v[2:3], v[104:105], v[2:3], v[114:115]
	v_cndmask_b32_e32 v45, v152, v45, vcc
	v_cndmask_b32_e32 v47, v152, v3, vcc
	v_cndmask_b32_e32 v46, v152, v2, vcc
	v_cndmask_b32_e32 v44, v152, v44, vcc
	global_store_dwordx4 v[0:1], v[44:47], off offset:64 sc0 sc1 nt
	global_load_dwordx4 v[44:47], v[56:57], off
	s_nop 0
	global_load_dwordx4 v[56:59], v[58:59], off
	ds_read_b64 v[2:3], v139 offset:8192
	s_waitcnt lgkmcnt(0)
	v_sub_f32_e32 v23, v23, v2
	v_sub_f32_e32 v22, v22, v2
	v_sub_f32_e32 v21, v21, v2
	v_sub_f32_e32 v20, v20, v2
	v_pk_mul_f32 v[20:21], v[2:3], v[20:21] op_sel:[1,0]
	v_pk_mul_f32 v[2:3], v[2:3], v[22:23] op_sel:[1,0]
	s_waitcnt vmcnt(0)
	v_pk_fma_f32 v[20:21], v[44:45], v[20:21], v[56:57]
	v_pk_fma_f32 v[2:3], v[46:47], v[2:3], v[58:59]
	v_cndmask_b32_e32 v21, v152, v21, vcc
	v_cndmask_b32_e32 v23, v152, v3, vcc
	v_cndmask_b32_e32 v22, v152, v2, vcc
	v_cndmask_b32_e32 v20, v152, v20, vcc
	global_store_dwordx4 v[148:149], v[20:23], off offset:512 sc0 sc1 nt
	ds_read_b64 v[2:3], v139 offset:8320
	s_waitcnt lgkmcnt(0)
	v_sub_f32_e32 v21, v31, v2
	v_sub_f32_e32 v20, v30, v2
	v_sub_f32_e32 v23, v29, v2
	v_sub_f32_e32 v22, v28, v2
	v_pk_mul_f32 v[22:23], v[2:3], v[22:23] op_sel:[1,0]
	v_pk_mul_f32 v[2:3], v[2:3], v[20:21] op_sel:[1,0]
	v_pk_fma_f32 v[20:21], v[44:45], v[22:23], v[56:57]
	v_pk_fma_f32 v[2:3], v[46:47], v[2:3], v[58:59]
	v_cndmask_b32_e32 v21, v152, v21, vcc
	v_cndmask_b32_e32 v23, v152, v3, vcc
	v_cndmask_b32_e32 v22, v152, v2, vcc
	v_cndmask_b32_e32 v20, v152, v20, vcc
	global_store_dwordx4 v[146:147], v[20:23], off offset:512 sc0 sc1 nt
	ds_read_b64 v[2:3], v139 offset:8448
	v_or_b32_e32 v28, 0x90, v138
	v_ashrrev_i32_e32 v29, 31, v28
	s_waitcnt lgkmcnt(0)
	v_sub_f32_e32 v21, v39, v2
	v_sub_f32_e32 v20, v38, v2
	v_sub_f32_e32 v23, v37, v2
	v_sub_f32_e32 v22, v36, v2
	v_pk_mul_f32 v[22:23], v[2:3], v[22:23] op_sel:[1,0]
	v_pk_mul_f32 v[2:3], v[2:3], v[20:21] op_sel:[1,0]
	v_pk_fma_f32 v[20:21], v[44:45], v[22:23], v[56:57]
	v_pk_fma_f32 v[2:3], v[46:47], v[2:3], v[58:59]
	v_cndmask_b32_e32 v21, v152, v21, vcc
	v_cndmask_b32_e32 v23, v152, v3, vcc
	v_cndmask_b32_e32 v22, v152, v2, vcc
	v_cndmask_b32_e32 v20, v152, v20, vcc
	global_store_dwordx4 v[88:89], v[20:23], off offset:512 sc0 sc1 nt
	ds_read_b64 v[2:3], v139 offset:8576
	s_waitcnt lgkmcnt(0)
	v_sub_f32_e32 v21, v43, v2
	v_sub_f32_e32 v20, v42, v2
	v_sub_f32_e32 v23, v41, v2
	v_sub_f32_e32 v22, v40, v2
	v_pk_mul_f32 v[22:23], v[2:3], v[22:23] op_sel:[1,0]
	v_pk_mul_f32 v[2:3], v[2:3], v[20:21] op_sel:[1,0]
	v_pk_fma_f32 v[20:21], v[44:45], v[22:23], v[56:57]
	v_pk_fma_f32 v[2:3], v[46:47], v[2:3], v[58:59]
	v_cndmask_b32_e32 v21, v152, v21, vcc
	v_cndmask_b32_e32 v23, v152, v3, vcc
	v_cndmask_b32_e32 v22, v152, v2, vcc
	v_cndmask_b32_e32 v20, v152, v20, vcc
	global_store_dwordx4 v[82:83], v[20:23], off offset:512 sc0 sc1 nt
	ds_read_b64 v[2:3], v139 offset:9216
	s_waitcnt lgkmcnt(0)
	v_sub_f32_e32 v21, v55, v2
	v_sub_f32_e32 v20, v54, v2
	v_sub_f32_e32 v23, v53, v2
	v_sub_f32_e32 v22, v52, v2
	v_pk_mul_f32 v[22:23], v[2:3], v[22:23] op_sel:[1,0]
	v_pk_mul_f32 v[2:3], v[2:3], v[20:21] op_sel:[1,0]
	v_pk_fma_f32 v[20:21], v[44:45], v[22:23], v[56:57]
	v_pk_fma_f32 v[2:3], v[46:47], v[2:3], v[58:59]
	v_cndmask_b32_e32 v21, v152, v21, vcc
	v_cndmask_b32_e32 v23, v152, v3, vcc
	v_cndmask_b32_e32 v22, v152, v2, vcc
	v_cndmask_b32_e32 v20, v152, v20, vcc
	global_store_dwordx4 v[80:81], v[20:23], off offset:512 sc0 sc1 nt
	ds_read_b64 v[2:3], v139 offset:9344
	s_waitcnt lgkmcnt(0)
	v_sub_f32_e32 v21, v63, v2
	v_sub_f32_e32 v20, v62, v2
	v_sub_f32_e32 v23, v61, v2
	v_sub_f32_e32 v22, v60, v2
	v_pk_mul_f32 v[22:23], v[2:3], v[22:23] op_sel:[1,0]
	v_pk_mul_f32 v[2:3], v[2:3], v[20:21] op_sel:[1,0]
	v_pk_fma_f32 v[20:21], v[44:45], v[22:23], v[56:57]
	v_pk_fma_f32 v[2:3], v[46:47], v[2:3], v[58:59]
	v_cndmask_b32_e32 v21, v152, v21, vcc
	v_cndmask_b32_e32 v23, v152, v3, vcc
	v_cndmask_b32_e32 v22, v152, v2, vcc
	v_cndmask_b32_e32 v20, v152, v20, vcc
	global_store_dwordx4 v[90:91], v[20:23], off offset:512 sc0 sc1 nt
	ds_read_b64 v[2:3], v139 offset:9472
	s_waitcnt lgkmcnt(0)
	v_sub_f32_e32 v21, v79, v2
	v_sub_f32_e32 v20, v78, v2
	v_sub_f32_e32 v23, v77, v2
	v_sub_f32_e32 v22, v76, v2
	v_pk_mul_f32 v[22:23], v[2:3], v[22:23] op_sel:[1,0]
	v_pk_mul_f32 v[2:3], v[2:3], v[20:21] op_sel:[1,0]
	v_pk_fma_f32 v[20:21], v[44:45], v[22:23], v[56:57]
	v_pk_fma_f32 v[2:3], v[46:47], v[2:3], v[58:59]
	v_cndmask_b32_e32 v21, v152, v21, vcc
	v_cndmask_b32_e32 v23, v152, v3, vcc
	v_cndmask_b32_e32 v22, v152, v2, vcc
	v_cndmask_b32_e32 v20, v152, v20, vcc
	global_store_dwordx4 v[100:101], v[20:23], off offset:512 sc0 sc1 nt
	ds_read_b64 v[2:3], v139 offset:9600
	s_nop 0
	v_lshlrev_b64 v[20:21], 2, v[28:29]
	v_lshl_add_u64 v[36:37], v[144:145], 0, v[20:21]
	v_lshl_add_u64 v[38:39], v[142:143], 0, v[20:21]
	s_waitcnt lgkmcnt(0)
; __device__ __forceinline__ unsigned cvt_pk_bf16(float lo, float hi) { unsigned r; asm volatile("v_cvt_pk_bf16_f32 %0, %1, %2" : "=v"(r) : "v"(lo), "v"(hi)); return r; }
;     __device__ __forceinline__ void fused(f32x4 (&acc)[2][2][4][2], const Unit& u, int wr, int wc, int fr, int fq, PG8_LAS unsigned char* lds, int wid, int lane) const {
;     ...
; #pragma unroll
;         for (int bj = 0; bj < 2; ++bj)
; #pragma unroll
;             for (int n = 0; n < 2; ++n) {
;                 const int col = col0 + bj * HALF + n * 16;
;                 const f32x4 lg = *(const f32x4*)(lng + col), lb = *(const f32x4*)(lnb + col);
;                 f32x4 sc1 = (f32x4){1.f, 1.f, 1.f, 1.f}, sh = (f32x4){0.f, 0.f, 0.f, 0.f};
;                 if (DO_U) { sc1 = *(const f32x4*)(msc + mo + col) + 1.0f; sh = *(const f32x4*)(msh + mo + col); }
; #pragma unroll
;                 for (int ai = 0; ai < 2; ++ai)
; #pragma unroll
;                     for (int m = 0; m < 4; ++m) { const int r = ai * HALF + wr * 64 + m * 16 + fr; const f32x2v sr = S[r]; const size_t off = (size_t)(u.pm * BM + r) * 1024 + col;
;                         f32x4 y = (acc[ai][bj][m][n] - sr.x) * sr.y * lg + lb; if (bad) y = (f32x4){qnan, qnan, qnan, qnan};
;                         *(f32x4*)(out + off) = y;
;                         if (DO_U) { const f32x4 uu = y * sc1 + sh; u32x2v w; w.x = cvt_pk_bf16(uu[0], uu[1]); w.y = cvt_pk_bf16(uu[2], uu[3]); *(u32x2v*)(U + off) = w; } }
	v_sub_f32_e32 v21, v95, v2
	v_sub_f32_e32 v20, v94, v2
	v_sub_f32_e32 v23, v93, v2
	v_sub_f32_e32 v22, v92, v2
	v_pk_mul_f32 v[22:23], v[2:3], v[22:23] op_sel:[1,0]
	v_pk_mul_f32 v[2:3], v[2:3], v[20:21] op_sel:[1,0]
	v_pk_fma_f32 v[20:21], v[44:45], v[22:23], v[56:57]
	v_pk_fma_f32 v[2:3], v[46:47], v[2:3], v[58:59]
	v_cndmask_b32_e32 v21, v152, v21, vcc
	v_cndmask_b32_e32 v23, v152, v3, vcc
	v_cndmask_b32_e32 v22, v152, v2, vcc
	v_cndmask_b32_e32 v20, v152, v20, vcc
	global_store_dwordx4 v[0:1], v[20:23], off offset:512 sc0 sc1 nt
	global_load_dwordx4 v[20:23], v[36:37], off
	s_nop 0
	global_load_dwordx4 v[28:31], v[38:39], off
	ds_read_b64 v[2:3], v139 offset:8192
	s_waitcnt lgkmcnt(0)
	v_sub_f32_e32 v7, v7, v2
	v_sub_f32_e32 v6, v6, v2
	v_sub_f32_e32 v5, v5, v2
	v_sub_f32_e32 v4, v4, v2
	v_pk_mul_f32 v[4:5], v[2:3], v[4:5] op_sel:[1,0]
	v_pk_mul_f32 v[2:3], v[2:3], v[6:7] op_sel:[1,0]
	s_waitcnt vmcnt(0)
	v_pk_fma_f32 v[6:7], v[20:21], v[4:5], v[28:29]
	v_pk_fma_f32 v[2:3], v[22:23], v[2:3], v[30:31]
	s_nop 0
	v_cndmask_b32_e32 v5, v152, v3, vcc
	v_cndmask_b32_e32 v4, v152, v2, vcc
	v_cndmask_b32_e32 v3, v152, v7, vcc
	v_cndmask_b32_e32 v2, v152, v6, vcc
	global_store_dwordx4 v[148:149], v[2:5], off offset:576 sc0 sc1 nt
	ds_read_b64 v[2:3], v139 offset:8320
	s_waitcnt lgkmcnt(0)
	v_sub_f32_e32 v7, v9, v2
	v_sub_f32_e32 v5, v11, v2
	v_sub_f32_e32 v4, v10, v2
	v_sub_f32_e32 v6, v8, v2
	v_pk_mul_f32 v[6:7], v[2:3], v[6:7] op_sel:[1,0]
	v_pk_mul_f32 v[2:3], v[2:3], v[4:5] op_sel:[1,0]
	v_pk_fma_f32 v[6:7], v[20:21], v[6:7], v[28:29]
	v_pk_fma_f32 v[2:3], v[22:23], v[2:3], v[30:31]
	s_nop 0
	v_cndmask_b32_e32 v5, v152, v3, vcc
	v_cndmask_b32_e32 v4, v152, v2, vcc
	v_cndmask_b32_e32 v3, v152, v7, vcc
	v_cndmask_b32_e32 v2, v152, v6, vcc
	global_store_dwordx4 v[146:147], v[2:5], off offset:576 sc0 sc1 nt
	ds_read_b64 v[2:3], v139 offset:8448
	s_waitcnt lgkmcnt(0)
	v_sub_f32_e32 v7, v13, v2
	v_sub_f32_e32 v5, v15, v2
	v_sub_f32_e32 v4, v14, v2
	v_sub_f32_e32 v6, v12, v2
	v_pk_mul_f32 v[6:7], v[2:3], v[6:7] op_sel:[1,0]
	v_pk_mul_f32 v[2:3], v[2:3], v[4:5] op_sel:[1,0]
	v_pk_fma_f32 v[6:7], v[20:21], v[6:7], v[28:29]
	v_pk_fma_f32 v[2:3], v[22:23], v[2:3], v[30:31]
	s_nop 0
	v_cndmask_b32_e32 v5, v152, v3, vcc
	v_cndmask_b32_e32 v4, v152, v2, vcc
	v_cndmask_b32_e32 v3, v152, v7, vcc
	v_cndmask_b32_e32 v2, v152, v6, vcc
	global_store_dwordx4 v[88:89], v[2:5], off offset:576 sc0 sc1 nt
	ds_read_b64 v[2:3], v139 offset:8576
	s_waitcnt lgkmcnt(0)
	v_sub_f32_e32 v7, v17, v2
	v_sub_f32_e32 v5, v19, v2
	v_sub_f32_e32 v4, v18, v2
	v_sub_f32_e32 v6, v16, v2
	v_pk_mul_f32 v[6:7], v[2:3], v[6:7] op_sel:[1,0]
	v_pk_mul_f32 v[2:3], v[2:3], v[4:5] op_sel:[1,0]
	v_pk_fma_f32 v[6:7], v[20:21], v[6:7], v[28:29]
	v_pk_fma_f32 v[2:3], v[22:23], v[2:3], v[30:31]
	s_nop 0
	v_cndmask_b32_e32 v5, v152, v3, vcc
	v_cndmask_b32_e32 v4, v152, v2, vcc
	v_cndmask_b32_e32 v3, v152, v7, vcc
	v_cndmask_b32_e32 v2, v152, v6, vcc
	global_store_dwordx4 v[82:83], v[2:5], off offset:576 sc0 sc1 nt
	ds_read_b64 v[2:3], v139 offset:9216
	s_waitcnt lgkmcnt(0)
	v_sub_f32_e32 v7, v25, v2
	v_sub_f32_e32 v5, v27, v2
	v_sub_f32_e32 v4, v26, v2
	v_sub_f32_e32 v6, v24, v2
	v_pk_mul_f32 v[6:7], v[2:3], v[6:7] op_sel:[1,0]
	v_pk_mul_f32 v[2:3], v[2:3], v[4:5] op_sel:[1,0]
	v_pk_fma_f32 v[6:7], v[20:21], v[6:7], v[28:29]
	v_pk_fma_f32 v[2:3], v[22:23], v[2:3], v[30:31]
	s_nop 0
	v_cndmask_b32_e32 v5, v152, v3, vcc
	v_cndmask_b32_e32 v4, v152, v2, vcc
	v_cndmask_b32_e32 v3, v152, v7, vcc
	v_cndmask_b32_e32 v2, v152, v6, vcc
	global_store_dwordx4 v[80:81], v[2:5], off offset:576 sc0 sc1 nt
	ds_read_b64 v[2:3], v139 offset:9344
	s_waitcnt lgkmcnt(0)
	v_sub_f32_e32 v7, v33, v2
	v_sub_f32_e32 v5, v35, v2
	v_sub_f32_e32 v4, v34, v2
	v_sub_f32_e32 v6, v32, v2
	v_pk_mul_f32 v[6:7], v[2:3], v[6:7] op_sel:[1,0]
	v_pk_mul_f32 v[2:3], v[2:3], v[4:5] op_sel:[1,0]
	v_pk_fma_f32 v[6:7], v[20:21], v[6:7], v[28:29]
	v_pk_fma_f32 v[2:3], v[22:23], v[2:3], v[30:31]
	s_nop 0
	v_cndmask_b32_e32 v5, v152, v3, vcc
	v_cndmask_b32_e32 v4, v152, v2, vcc
	v_cndmask_b32_e32 v3, v152, v7, vcc
	v_cndmask_b32_e32 v2, v152, v6, vcc
	global_store_dwordx4 v[90:91], v[2:5], off offset:576 sc0 sc1 nt
	ds_read_b64 v[2:3], v139 offset:9472
	s_waitcnt lgkmcnt(0)
	v_sub_f32_e32 v7, v49, v2
	v_sub_f32_e32 v5, v51, v2
	v_sub_f32_e32 v4, v50, v2
	v_sub_f32_e32 v6, v48, v2
	v_pk_mul_f32 v[6:7], v[2:3], v[6:7] op_sel:[1,0]
	v_pk_mul_f32 v[2:3], v[2:3], v[4:5] op_sel:[1,0]
	v_pk_fma_f32 v[6:7], v[20:21], v[6:7], v[28:29]
	v_pk_fma_f32 v[2:3], v[22:23], v[2:3], v[30:31]
	s_nop 0
	v_cndmask_b32_e32 v5, v152, v3, vcc
	v_cndmask_b32_e32 v4, v152, v2, vcc
	v_cndmask_b32_e32 v3, v152, v7, vcc
	v_cndmask_b32_e32 v2, v152, v6, vcc
	global_store_dwordx4 v[100:101], v[2:5], off offset:576 sc0 sc1 nt
	ds_read_b64 v[2:3], v139 offset:9600
	s_waitcnt lgkmcnt(0)
	v_sub_f32_e32 v7, v65, v2
	v_sub_f32_e32 v5, v67, v2
	v_sub_f32_e32 v4, v66, v2
	v_sub_f32_e32 v6, v64, v2
	v_pk_mul_f32 v[6:7], v[2:3], v[6:7] op_sel:[1,0]
	v_pk_mul_f32 v[2:3], v[2:3], v[4:5] op_sel:[1,0]
	v_pk_fma_f32 v[6:7], v[20:21], v[6:7], v[28:29]
	v_pk_fma_f32 v[2:3], v[22:23], v[2:3], v[30:31]
	s_nop 0
	v_cndmask_b32_e32 v5, v152, v3, vcc
	v_cndmask_b32_e32 v4, v152, v2, vcc
	v_cndmask_b32_e32 v3, v152, v7, vcc
	v_cndmask_b32_e32 v2, v152, v6, vcc
	global_store_dwordx4 v[0:1], v[2:5], off offset:576 sc0 sc1 nt

; __global__ void __launch_bounds__(NTHREADS, 2) mega_fwd(Args a_unused) {
	.amdhsa_kernel _Z8mega_fwd4Args
		.amdhsa_group_segment_fixed_size 0
		.amdhsa_private_segment_fixed_size 0
		.amdhsa_kernarg_size 656
		.amdhsa_user_sgpr_count 2
		.amdhsa_user_sgpr_dispatch_ptr 0
		.amdhsa_user_sgpr_queue_ptr 0
		.amdhsa_user_sgpr_kernarg_segment_ptr 1
		.amdhsa_user_sgpr_dispatch_id 0
		.amdhsa_user_sgpr_kernarg_preload_length 0
		.amdhsa_user_sgpr_kernarg_preload_offset 0
		.amdhsa_user_sgpr_private_segment_size 0
		.amdhsa_uses_dynamic_stack 0
		.amdhsa_enable_private_segment 0
		.amdhsa_system_sgpr_workgroup_id_x 1
		.amdhsa_system_sgpr_workgroup_id_y 0
		.amdhsa_system_sgpr_workgroup_id_z 0
		.amdhsa_system_sgpr_workgroup_info 0
		.amdhsa_system_vgpr_workitem_id 2
		.amdhsa_next_free_vgpr 256
		.amdhsa_next_free_sgpr 102
		.amdhsa_accum_offset 256
		.amdhsa_reserve_vcc 1
		.amdhsa_float_round_mode_32 0
		.amdhsa_float_round_mode_16_64 0
		.amdhsa_float_denorm_mode_32 3
		.amdhsa_float_denorm_mode_16_64 3
		.amdhsa_dx10_clamp 1
		.amdhsa_ieee_mode 1
		.amdhsa_fp16_overflow 0
		.amdhsa_tg_split 0
		.amdhsa_exception_fp_ieee_invalid_op 0
		.amdhsa_exception_fp_denorm_src 0
		.amdhsa_exception_fp_ieee_div_zero 0
		.amdhsa_exception_fp_ieee_overflow 0
		.amdhsa_exception_fp_ieee_underflow 0
		.amdhsa_exception_fp_ieee_inexact 0
		.amdhsa_exception_int_div_zero 0
	.end_amdhsa_kernel

; __global__ void __launch_bounds__(NTHREADS, 2) mega_fwd(Args a_unused) {
amdhsa.kernels:
  - .agpr_count:     0
    .args:
      - .offset:         0
        .size:           400
        .value_kind:     by_value
      - .offset:         400
        .size:           4
        .value_kind:     hidden_block_count_x
      - .offset:         404
        .size:           4
        .value_kind:     hidden_block_count_y
      - .offset:         408
        .size:           4
        .value_kind:     hidden_block_count_z
      - .offset:         412
        .size:           2
        .value_kind:     hidden_group_size_x
      - .offset:         414
        .size:           2
        .value_kind:     hidden_group_size_y
      - .offset:         416
        .size:           2
        .value_kind:     hidden_group_size_z
      - .offset:         418
        .size:           2
        .value_kind:     hidden_remainder_x
      - .offset:         420
        .size:           2
        .value_kind:     hidden_remainder_y
      - .offset:         422
        .size:           2
        .value_kind:     hidden_remainder_z
      - .offset:         440
        .size:           8
        .value_kind:     hidden_global_offset_x
      - .offset:         448
        .size:           8
        .value_kind:     hidden_global_offset_y
      - .offset:         456
        .size:           8
        .value_kind:     hidden_global_offset_z
      - .offset:         464
        .size:           2
        .value_kind:     hidden_grid_dims
      - .offset:         488
        .size:           8
        .value_kind:     hidden_multigrid_sync_arg
      - .offset:         520
        .size:           4
        .value_kind:     hidden_dynamic_lds_size
    .group_segment_fixed_size: 0
    .kernarg_segment_align: 8
    .kernarg_segment_size: 656
    .language:       OpenCL C
    .language_version:
      - 2
      - 0
    .max_flat_workgroup_size: 512
    .name:           _Z8mega_fwd4Args
    .private_segment_fixed_size: 0
    .sgpr_count:     108
    .sgpr_spill_count: 2
    .symbol:         _Z8mega_fwd4Args.kd
    .uniform_work_group_size: 1
    .uses_dynamic_stack: false
    .vgpr_count:     256
    .vgpr_spill_count: 0
    .wavefront_size: 64
